# nt hint also on prep bf16 weight stores and final-norm x loads / output stores
# speedup vs baseline: 1.0240x; 1.0023x over previous
.LBB0_16:
	s_mov_b32 s2, 0x367a25e1
	v_mul_hi_i32 v2, v114, s2
	v_lshrrev_b32_e32 v3, 31, v2
	v_ashrrev_i32_e32 v2, 12, v2
	v_add_u32_e32 v74, v2, v3
	v_mul_i32_i24_e32 v4, 0x4b30, v74
	v_sub_u32_e32 v2, v114, v4
	s_movk_i32 s2, 0x201f
	v_cmp_lt_i32_e32 vcc, s2, v2
	v_ashrrev_i32_e32 v75, 31, v74
	s_and_saveexec_b64 s[2:3], vcc
	s_xor_b64 s[64:65], exec, s[2:3]
	s_cbranch_execz .LBB0_96
	v_add_u32_e32 v81, 0xffffdfe0, v2
	v_cmp_lt_u32_e32 vcc, s77, v81
	s_and_saveexec_b64 s[2:3], vcc
	s_xor_b64 s[2:3], exec, s[2:3]
	v_add_u32_e32 v81, 0xffffdde0, v2
	s_or_saveexec_b64 s[4:5], s[2:3]
	v_mov_b64_e32 v[2:3], s[8:9]
	s_mov_b32 s2, 0xa00000
	v_lshlrev_b64 v[6:7], 21, v[74:75]
	v_mad_i64_i32 v[2:3], s[2:3], v74, s2, v[2:3]
	s_xor_b64 exec, exec, s[4:5]
	s_cbranch_execz .LBB0_21
	v_lshlrev_b32_e32 v5, 6, v4
	v_lshlrev_b32_e32 v4, 1, v4
	v_sub_u32_e32 v4, v102, v4
	v_and_b32_e32 v9, 0x3c0, v4
	v_sub_u32_e32 v5, v101, v5
	v_or_b32_e32 v4, v9, v83
	v_lshl_add_u64 v[10:11], v[6:7], 2, s[38:39]
	v_and_b32_e32 v8, 0x7c0, v5
	v_lshlrev_b32_e32 v68, 13, v4
	v_lshl_add_u64 v[4:5], v[10:11], 0, v[68:69]
	v_lshlrev_b32_e32 v68, 2, v8
	v_lshl_add_u64 v[4:5], v[4:5], 0, v[68:69]
	v_mov_b32_e32 v73, v69
	v_lshl_add_u64 v[4:5], v[4:5], 0, v[72:73]
	v_add_co_u32_e64 v14, s[2:3], s78, v4
	v_lshlrev_b32_e32 v68, 1, v9
	s_nop 0
	v_addc_co_u32_e64 v15, s[2:3], 0, v5, s[2:3]
	v_add_co_u32_e64 v18, s[2:3], s79, v4
	global_load_dwordx4 v[10:13], v[4:5], off nt
	s_nop 0
	global_load_dwordx4 v[14:17], v[14:15], off nt
	v_addc_co_u32_e64 v19, s[2:3], 0, v5, s[2:3]
	v_add_co_u32_e64 v22, s[2:3], s82, v4
	v_add_u32_e32 v9, 0x400, v86
	s_nop 0
	v_addc_co_u32_e64 v23, s[2:3], 0, v5, s[2:3]
	v_add_co_u32_e64 v26, s[2:3], s83, v4
	global_load_dwordx4 v[18:21], v[18:19], off nt
	s_nop 0
	global_load_dwordx4 v[22:25], v[22:23], off nt
	v_addc_co_u32_e64 v27, s[2:3], 0, v5, s[2:3]
	v_add_co_u32_e64 v30, s[2:3], s84, v4
	s_nop 1
	v_addc_co_u32_e64 v31, s[2:3], 0, v5, s[2:3]
	v_add_co_u32_e64 v34, s[2:3], s85, v4
	global_load_dwordx4 v[26:29], v[26:27], off nt
	s_nop 0
	global_load_dwordx4 v[30:33], v[30:31], off nt
	v_addc_co_u32_e64 v35, s[2:3], 0, v5, s[2:3]
	v_add_co_u32_e64 v38, s[2:3], s86, v4
	s_nop 1
	v_addc_co_u32_e64 v39, s[2:3], 0, v5, s[2:3]
	global_load_dwordx4 v[34:37], v[34:35], off nt
	s_nop 0
	global_load_dwordx4 v[38:41], v[38:39], off nt
	v_add_co_u32_e64 v42, s[2:3], s87, v4
	s_nop 1
	v_addc_co_u32_e64 v43, s[2:3], 0, v5, s[2:3]
	v_add_co_u32_e64 v46, s[2:3], s88, v4
	s_nop 1
	v_addc_co_u32_e64 v47, s[2:3], 0, v5, s[2:3]
	global_load_dwordx4 v[42:45], v[42:43], off nt
	s_nop 0
	global_load_dwordx4 v[46:49], v[46:47], off nt
	v_add_co_u32_e64 v50, s[2:3], s89, v4
	s_nop 1
	v_addc_co_u32_e64 v51, s[2:3], 0, v5, s[2:3]
	v_add_co_u32_e64 v54, s[2:3], s90, v4
	s_nop 1
	v_addc_co_u32_e64 v55, s[2:3], 0, v5, s[2:3]
	global_load_dwordx4 v[50:53], v[50:51], off nt
	s_nop 0
	global_load_dwordx4 v[54:57], v[54:55], off nt
	v_add_co_u32_e64 v58, s[2:3], s91, v4
	s_nop 1
	v_addc_co_u32_e64 v59, s[2:3], 0, v5, s[2:3]
	global_load_dwordx4 v[58:61], v[58:59], off nt
	v_add_co_u32_e64 v62, s[2:3], s92, v4
	s_nop 1
	v_addc_co_u32_e64 v63, s[2:3], 0, v5, s[2:3]
	global_load_dwordx4 v[62:65], v[62:63], off nt
	v_add_co_u32_e64 v76, s[2:3], s93, v4
	s_nop 1
	v_addc_co_u32_e64 v77, s[2:3], 0, v5, s[2:3]
	global_load_dwordx4 v[76:79], v[76:77], off nt
	v_add_co_u32_e64 v4, s[2:3], s94, v4
	s_nop 1
	v_addc_co_u32_e64 v5, s[2:3], 0, v5, s[2:3]
	global_load_dwordx4 v[116:119], v[4:5], off nt
	v_add_u32_e32 v4, 0x1458, v84
	s_waitcnt vmcnt(15)
	ds_write2_b32 v84, v10, v11 offset1:1
	ds_write2_b32 v84, v12, v13 offset0:2 offset1:3
	s_waitcnt vmcnt(14)
	ds_write2_b32 v103, v14, v15 offset1:1
	ds_write2_b32 v104, v16, v17 offset1:1
	s_waitcnt vmcnt(13)
	ds_write2_b32 v105, v18, v19 offset1:1
	ds_write2_b32 v106, v20, v21 offset1:1
	s_waitcnt vmcnt(12)
	ds_write2_b32 v107, v22, v23 offset1:1
	ds_write2_b32 v108, v24, v25 offset1:1
	s_waitcnt vmcnt(11)
	ds_write2_b32 v109, v26, v27 offset1:1
	ds_write2_b32 v110, v28, v29 offset1:1
	s_waitcnt vmcnt(10)
	ds_write2_b32 v111, v30, v31 offset1:1
	ds_write2_b32 v4, v32, v33 offset1:1
	v_add_u32_e32 v4, 0x1860, v84
	s_waitcnt vmcnt(9)
	ds_write2_b32 v4, v34, v35 offset1:1
	v_add_u32_e32 v4, 0x1868, v84
	ds_write2_b32 v4, v36, v37 offset1:1
	v_add_u32_e32 v4, 0x1c70, v84
	s_waitcnt vmcnt(8)
	ds_write2_b32 v4, v38, v39 offset1:1
	v_add_u32_e32 v4, 0x1c78, v84
	ds_write2_b32 v4, v40, v41 offset1:1
	v_add_u32_e32 v4, 0x2080, v84
	s_waitcnt vmcnt(7)
	ds_write2_b32 v4, v42, v43 offset1:1
	v_add_u32_e32 v4, 0x2088, v84
	ds_write2_b32 v4, v44, v45 offset1:1
	v_add_u32_e32 v4, 0x2490, v84
	s_waitcnt vmcnt(6)
	ds_write2_b32 v4, v46, v47 offset1:1
	v_add_u32_e32 v4, 0x2498, v84
	ds_write2_b32 v4, v48, v49 offset1:1
	v_add_u32_e32 v4, 0x28a0, v84
	s_waitcnt vmcnt(5)
	ds_write2_b32 v4, v50, v51 offset1:1
	v_add_u32_e32 v4, 0x28a8, v84
	ds_write2_b32 v4, v52, v53 offset1:1
	v_add_u32_e32 v4, 0x2cb0, v84
	s_waitcnt vmcnt(4)
	ds_write2_b32 v4, v54, v55 offset1:1
	v_add_u32_e32 v4, 0x2cb8, v84
	ds_write2_b32 v4, v56, v57 offset1:1
	v_add_u32_e32 v4, 0x30c0, v84
	s_waitcnt vmcnt(3)
	ds_write2_b32 v4, v58, v59 offset1:1
	v_add_u32_e32 v4, 0x30c8, v84
	ds_write2_b32 v4, v60, v61 offset1:1
	v_add_u32_e32 v4, 0x34d0, v84
	s_waitcnt vmcnt(2)
	ds_write2_b32 v4, v62, v63 offset1:1
	v_add_u32_e32 v4, 0x34d8, v84
	ds_write2_b32 v4, v64, v65 offset1:1
	v_add_u32_e32 v4, 0x38e0, v84
	s_waitcnt vmcnt(1)
	ds_write2_b32 v4, v76, v77 offset1:1
	v_add_u32_e32 v4, 0x38e8, v84
	ds_write2_b32 v4, v78, v79 offset1:1
	v_add_u32_e32 v4, 0x3cf0, v84
	s_waitcnt vmcnt(0)
	ds_write2_b32 v4, v116, v117 offset1:1
	v_add_u32_e32 v4, 0x3cf8, v84
	ds_write2_b32 v4, v118, v119 offset1:1
	s_waitcnt lgkmcnt(0)
	ds_read2_b32 v[16:17], v9 offset0:134 offset1:142
	ds_read2_b32 v[14:15], v9 offset0:199 offset1:207
	ds_read2_b32 v[20:21], v9 offset0:4 offset1:12
	ds_read2_b32 v[18:19], v9 offset0:69 offset1:77
	ds_read2_b32 v[24:25], v86 offset0:130 offset1:138
	s_waitcnt lgkmcnt(4)
	v_bfe_u32 v11, v16, 16, 1
	s_waitcnt lgkmcnt(3)
	v_bfe_u32 v10, v14, 16, 1
	v_add3_u32 v11, v16, v11, s95
	v_add3_u32 v10, v14, v10, s95
	v_lshrrev_b32_e32 v11, 16, v11
	ds_read2_b32 v[22:23], v86 offset0:195 offset1:203
	v_and_or_b32 v13, v10, s96, v11
	s_waitcnt lgkmcnt(3)
	v_bfe_u32 v11, v20, 16, 1
	ds_read2_b32 v[28:29], v86 offset1:8
	s_waitcnt lgkmcnt(3)
	v_bfe_u32 v10, v18, 16, 1
	v_add3_u32 v11, v20, v11, s95
	ds_read2_b32 v[26:27], v86 offset0:65 offset1:73
	v_add3_u32 v10, v18, v10, s95
	v_lshrrev_b32_e32 v11, 16, v11
	v_and_or_b32 v12, v10, s96, v11
	s_waitcnt lgkmcnt(3)
	v_bfe_u32 v11, v24, 16, 1
	s_waitcnt lgkmcnt(2)
	v_bfe_u32 v10, v22, 16, 1
	v_add3_u32 v11, v24, v11, s95
	v_add3_u32 v10, v22, v10, s95
	v_lshrrev_b32_e32 v11, 16, v11
	s_waitcnt lgkmcnt(1)
	v_bfe_u32 v14, v28, 16, 1
	v_and_or_b32 v11, v10, s96, v11
	s_waitcnt lgkmcnt(0)
	v_bfe_u32 v10, v26, 16, 1
	v_add3_u32 v14, v28, v14, s95
	v_add3_u32 v10, v26, v10, s95
	v_lshrrev_b32_e32 v14, 16, v14
	v_and_or_b32 v10, v10, s96, v14
	v_or_b32_e32 v14, v8, v85
	v_lshl_add_u64 v[4:5], v[2:3], 0, v[68:69]
	v_lshlrev_b32_e32 v68, 1, v70
	v_mul_u32_u24_e32 v14, 0xa00, v14
	v_lshl_add_u64 v[4:5], v[4:5], 0, v[68:69]
	v_lshlrev_b32_e32 v68, 1, v14
	v_lshl_add_u64 v[30:31], v[4:5], 0, v[68:69]
	global_store_dwordx4 v[30:31], v[10:13], off nt
	v_bfe_u32 v14, v29, 16, 1
	v_add3_u32 v14, v29, v14, s95
	v_bfe_u32 v11, v17, 16, 1
	v_bfe_u32 v10, v15, 16, 1
	v_add3_u32 v11, v17, v11, s95
	v_add3_u32 v10, v15, v10, s95
	v_lshrrev_b32_e32 v11, 16, v11
	v_and_or_b32 v13, v10, s96, v11
	v_bfe_u32 v11, v21, 16, 1
	v_bfe_u32 v10, v19, 16, 1
	v_add3_u32 v11, v21, v11, s95
	v_add3_u32 v10, v19, v10, s95
	v_lshrrev_b32_e32 v11, 16, v11
	v_and_or_b32 v12, v10, s96, v11
	v_bfe_u32 v11, v25, 16, 1
	v_bfe_u32 v10, v23, 16, 1
	v_add3_u32 v11, v25, v11, s95
	v_add3_u32 v10, v23, v10, s95
	v_lshrrev_b32_e32 v11, 16, v11
	v_and_or_b32 v11, v10, s96, v11
	v_bfe_u32 v10, v27, 16, 1
	v_add3_u32 v10, v27, v10, s95
	v_lshrrev_b32_e32 v14, 16, v14
	v_and_or_b32 v10, v10, s96, v14
	v_or_b32_e32 v14, v8, v87
	v_mul_u32_u24_e32 v16, 0xa00, v14
	v_lshlrev_b32_e32 v68, 1, v16
	ds_read2_b32 v[16:17], v9 offset0:150 offset1:158
	ds_read2_b32 v[14:15], v9 offset0:215 offset1:223
	v_lshl_add_u64 v[18:19], v[4:5], 0, v[68:69]
	ds_read2_b32 v[20:21], v9 offset0:20 offset1:28
	global_store_dwordx4 v[18:19], v[10:13], off nt
	ds_read2_b32 v[18:19], v9 offset0:85 offset1:93
	ds_read2_b32 v[24:25], v86 offset0:146 offset1:154
	s_waitcnt lgkmcnt(4)
	v_bfe_u32 v11, v16, 16, 1
	s_waitcnt lgkmcnt(3)
	v_bfe_u32 v10, v14, 16, 1
	v_add3_u32 v11, v16, v11, s95
	v_add3_u32 v10, v14, v10, s95
	v_lshrrev_b32_e32 v11, 16, v11
	ds_read2_b32 v[22:23], v86 offset0:211 offset1:219
	v_and_or_b32 v13, v10, s96, v11
	s_waitcnt lgkmcnt(3)
	v_bfe_u32 v11, v20, 16, 1
	ds_read2_b32 v[28:29], v86 offset0:16 offset1:24
	s_waitcnt lgkmcnt(3)
	v_bfe_u32 v10, v18, 16, 1
	v_add3_u32 v11, v20, v11, s95
	ds_read2_b32 v[26:27], v86 offset0:81 offset1:89
	v_add3_u32 v10, v18, v10, s95
	v_lshrrev_b32_e32 v11, 16, v11
	v_and_or_b32 v12, v10, s96, v11
	s_waitcnt lgkmcnt(3)
	v_bfe_u32 v11, v24, 16, 1
	s_waitcnt lgkmcnt(2)
	v_bfe_u32 v10, v22, 16, 1
	v_add3_u32 v11, v24, v11, s95
	v_add3_u32 v10, v22, v10, s95
	v_lshrrev_b32_e32 v11, 16, v11
	s_waitcnt lgkmcnt(1)
	v_bfe_u32 v14, v28, 16, 1
	v_and_or_b32 v11, v10, s96, v11
	s_waitcnt lgkmcnt(0)
	v_bfe_u32 v10, v26, 16, 1
	v_add3_u32 v14, v28, v14, s95
	v_add3_u32 v10, v26, v10, s95
	v_lshrrev_b32_e32 v14, 16, v14
	v_and_or_b32 v10, v10, s96, v14
	v_or_b32_e32 v14, v8, v88
	v_mul_u32_u24_e32 v14, 0xa00, v14
	v_lshlrev_b32_e32 v68, 1, v14
	v_lshl_add_u64 v[30:31], v[4:5], 0, v[68:69]
	global_store_dwordx4 v[30:31], v[10:13], off nt
	v_bfe_u32 v14, v29, 16, 1
	v_add3_u32 v14, v29, v14, s95
	v_bfe_u32 v11, v17, 16, 1
	v_bfe_u32 v10, v15, 16, 1
	v_add3_u32 v11, v17, v11, s95
	v_add3_u32 v10, v15, v10, s95
	v_lshrrev_b32_e32 v11, 16, v11
	v_and_or_b32 v13, v10, s96, v11
	v_bfe_u32 v11, v21, 16, 1
	v_bfe_u32 v10, v19, 16, 1
	v_add3_u32 v11, v21, v11, s95
	v_add3_u32 v10, v19, v10, s95
	v_lshrrev_b32_e32 v11, 16, v11
	v_and_or_b32 v12, v10, s96, v11
	v_bfe_u32 v11, v25, 16, 1
	v_bfe_u32 v10, v23, 16, 1
	v_add3_u32 v11, v25, v11, s95
	v_add3_u32 v10, v23, v10, s95
	v_lshrrev_b32_e32 v11, 16, v11
	v_and_or_b32 v11, v10, s96, v11
	v_bfe_u32 v10, v27, 16, 1
	v_add3_u32 v10, v27, v10, s95
	v_lshrrev_b32_e32 v14, 16, v14
	v_and_or_b32 v10, v10, s96, v14
	v_or_b32_e32 v14, v8, v89
	v_mul_u32_u24_e32 v16, 0xa00, v14
	v_lshlrev_b32_e32 v68, 1, v16
	ds_read2_b32 v[16:17], v9 offset0:166 offset1:174
	ds_read2_b32 v[14:15], v9 offset0:231 offset1:239
	v_lshl_add_u64 v[18:19], v[4:5], 0, v[68:69]
	ds_read2_b32 v[20:21], v9 offset0:36 offset1:44
	global_store_dwordx4 v[18:19], v[10:13], off nt
	ds_read2_b32 v[18:19], v9 offset0:101 offset1:109
	ds_read2_b32 v[24:25], v86 offset0:162 offset1:170
	s_waitcnt lgkmcnt(4)
	v_bfe_u32 v11, v16, 16, 1
	s_waitcnt lgkmcnt(3)
	v_bfe_u32 v10, v14, 16, 1
	v_add3_u32 v11, v16, v11, s95
	v_add3_u32 v10, v14, v10, s95
	v_lshrrev_b32_e32 v11, 16, v11
	ds_read2_b32 v[22:23], v86 offset0:227 offset1:235
	v_and_or_b32 v13, v10, s96, v11
	s_waitcnt lgkmcnt(3)
	v_bfe_u32 v11, v20, 16, 1
	ds_read2_b32 v[28:29], v86 offset0:32 offset1:40
	s_waitcnt lgkmcnt(3)
	v_bfe_u32 v10, v18, 16, 1
	v_add3_u32 v11, v20, v11, s95
	ds_read2_b32 v[26:27], v86 offset0:97 offset1:105
	v_add3_u32 v10, v18, v10, s95
	v_lshrrev_b32_e32 v11, 16, v11
	v_and_or_b32 v12, v10, s96, v11
	s_waitcnt lgkmcnt(3)
	v_bfe_u32 v11, v24, 16, 1
	s_waitcnt lgkmcnt(2)
	v_bfe_u32 v10, v22, 16, 1
	v_add3_u32 v11, v24, v11, s95
	v_add3_u32 v10, v22, v10, s95
	v_lshrrev_b32_e32 v11, 16, v11
	s_waitcnt lgkmcnt(1)
	v_bfe_u32 v14, v28, 16, 1
	v_and_or_b32 v11, v10, s96, v11
	s_waitcnt lgkmcnt(0)
	v_bfe_u32 v10, v26, 16, 1
	v_add3_u32 v14, v28, v14, s95
	v_add3_u32 v10, v26, v10, s95
	v_lshrrev_b32_e32 v14, 16, v14
	v_and_or_b32 v10, v10, s96, v14
	v_or_b32_e32 v14, v8, v90
	v_mul_u32_u24_e32 v14, 0xa00, v14
	v_lshlrev_b32_e32 v68, 1, v14
	v_lshl_add_u64 v[30:31], v[4:5], 0, v[68:69]
	global_store_dwordx4 v[30:31], v[10:13], off nt
	v_bfe_u32 v14, v29, 16, 1
	v_add3_u32 v14, v29, v14, s95
	v_bfe_u32 v11, v17, 16, 1
	v_bfe_u32 v10, v15, 16, 1
	v_add3_u32 v11, v17, v11, s95
	v_add3_u32 v10, v15, v10, s95
	v_lshrrev_b32_e32 v11, 16, v11
	v_and_or_b32 v13, v10, s96, v11
	v_bfe_u32 v11, v21, 16, 1
	v_bfe_u32 v10, v19, 16, 1
	v_add3_u32 v11, v21, v11, s95
	v_add3_u32 v10, v19, v10, s95
	v_lshrrev_b32_e32 v11, 16, v11
	v_and_or_b32 v12, v10, s96, v11
	v_bfe_u32 v11, v25, 16, 1
	v_bfe_u32 v10, v23, 16, 1
	v_add3_u32 v11, v25, v11, s95
	v_add3_u32 v10, v23, v10, s95
	v_lshrrev_b32_e32 v11, 16, v11
	v_and_or_b32 v11, v10, s96, v11
	v_bfe_u32 v10, v27, 16, 1
	v_add3_u32 v10, v27, v10, s95
	v_lshrrev_b32_e32 v14, 16, v14
	v_and_or_b32 v10, v10, s96, v14
	v_or_b32_e32 v14, v8, v91
	v_mul_u32_u24_e32 v16, 0xa00, v14
	v_lshlrev_b32_e32 v68, 1, v16
	ds_read2_b32 v[16:17], v9 offset0:182 offset1:190
	ds_read2_b32 v[14:15], v9 offset0:247 offset1:255
	v_lshl_add_u64 v[18:19], v[4:5], 0, v[68:69]
	ds_read2_b32 v[20:21], v9 offset0:52 offset1:60
	global_store_dwordx4 v[18:19], v[10:13], off nt
	ds_read2_b32 v[18:19], v9 offset0:117 offset1:125
	ds_read2_b32 v[24:25], v86 offset0:178 offset1:186
	s_waitcnt lgkmcnt(4)
	v_bfe_u32 v11, v16, 16, 1
	s_waitcnt lgkmcnt(3)
	v_bfe_u32 v10, v14, 16, 1
	v_add3_u32 v11, v16, v11, s95
	v_add3_u32 v10, v14, v10, s95
	v_lshrrev_b32_e32 v9, 16, v11
	ds_read2_b32 v[22:23], v86 offset0:243 offset1:251
	v_and_or_b32 v13, v10, s96, v9
	s_waitcnt lgkmcnt(3)
	v_bfe_u32 v10, v20, 16, 1
	s_waitcnt lgkmcnt(2)
	v_bfe_u32 v9, v18, 16, 1
	v_add3_u32 v10, v20, v10, s95
	ds_read2_b32 v[28:29], v86 offset0:48 offset1:56
	v_add3_u32 v9, v18, v9, s95
	v_lshrrev_b32_e32 v10, 16, v10
	ds_read2_b32 v[26:27], v86 offset0:113 offset1:121
	v_and_or_b32 v12, v9, s96, v10
	s_waitcnt lgkmcnt(3)
	v_bfe_u32 v10, v24, 16, 1
	s_waitcnt lgkmcnt(2)
	v_bfe_u32 v9, v22, 16, 1
	v_add3_u32 v10, v24, v10, s95
	v_add3_u32 v9, v22, v9, s95
	v_lshrrev_b32_e32 v10, 16, v10
	v_and_or_b32 v11, v9, s96, v10
	s_waitcnt lgkmcnt(1)
	v_bfe_u32 v10, v28, 16, 1
	s_waitcnt lgkmcnt(0)
	v_bfe_u32 v9, v26, 16, 1
	v_add3_u32 v10, v28, v10, s95
	v_add3_u32 v9, v26, v9, s95
	v_lshrrev_b32_e32 v10, 16, v10
	v_and_or_b32 v10, v9, s96, v10
	v_or_b32_e32 v9, v8, v92
	v_mul_u32_u24_e32 v9, 0xa00, v9
	v_lshlrev_b32_e32 v68, 1, v9
	v_lshl_add_u64 v[30:31], v[4:5], 0, v[68:69]
	global_store_dwordx4 v[30:31], v[10:13], off nt
	v_bfe_u32 v9, v15, 16, 1
	v_add3_u32 v9, v15, v9, s95
	v_bfe_u32 v10, v17, 16, 1
	v_add3_u32 v10, v17, v10, s95
	v_lshrrev_b32_e32 v10, 16, v10
	v_and_or_b32 v13, v9, s96, v10
	v_bfe_u32 v10, v21, 16, 1
	v_bfe_u32 v9, v19, 16, 1
	v_add3_u32 v10, v21, v10, s95
	v_add3_u32 v9, v19, v9, s95
	v_lshrrev_b32_e32 v10, 16, v10
	v_and_or_b32 v12, v9, s96, v10
	v_bfe_u32 v10, v25, 16, 1
	v_bfe_u32 v9, v23, 16, 1
	v_add3_u32 v10, v25, v10, s95
	v_add3_u32 v9, v23, v9, s95
	v_lshrrev_b32_e32 v10, 16, v10
	v_and_or_b32 v11, v9, s96, v10
	v_bfe_u32 v10, v29, 16, 1
	v_or_b32_e32 v8, v8, v93
	v_bfe_u32 v9, v27, 16, 1
	v_add3_u32 v10, v29, v10, s95
	v_mul_u32_u24_e32 v8, 0xa00, v8
	v_add3_u32 v9, v27, v9, s95
	v_lshrrev_b32_e32 v10, 16, v10
	v_lshlrev_b32_e32 v68, 1, v8
	v_and_or_b32 v10, v9, s96, v10
	v_lshl_add_u64 v[4:5], v[4:5], 0, v[68:69]
	global_store_dwordx4 v[4:5], v[10:13], off nt
	s_waitcnt lgkmcnt(0)

.LBB0_26:
	v_lshlrev_b32_e32 v11, 1, v81
	v_and_b32_e32 v11, 0x1c0, v11
	v_lshlrev_b32_e32 v10, 6, v81
	v_or_b32_e32 v12, v11, v83
	v_lshl_add_u64 v[8:9], s[40:41], 0, v[4:5]
	v_and_b32_e32 v10, 0x7c0, v10
	v_lshlrev_b32_e32 v68, 13, v12
	v_lshl_add_u64 v[8:9], v[8:9], 0, v[68:69]
	v_lshlrev_b32_e32 v68, 2, v10
	v_lshl_add_u64 v[8:9], v[8:9], 0, v[68:69]
	v_mov_b32_e32 v73, v69
	v_lshl_add_u64 v[8:9], v[8:9], 0, v[72:73]
	v_add_co_u32_e32 v16, vcc, s78, v8
	v_lshlrev_b32_e32 v68, 1, v11
	s_nop 0
	v_addc_co_u32_e32 v17, vcc, 0, v9, vcc
	v_add_co_u32_e32 v20, vcc, s79, v8
	global_load_dwordx4 v[12:15], v[8:9], off nt
	s_nop 0
	global_load_dwordx4 v[16:19], v[16:17], off nt
	v_addc_co_u32_e32 v21, vcc, 0, v9, vcc
	v_add_co_u32_e32 v24, vcc, s82, v8
	v_add_u32_e32 v11, 0x400, v86
	s_nop 0
	v_addc_co_u32_e32 v25, vcc, 0, v9, vcc
	v_add_co_u32_e32 v28, vcc, s83, v8
	global_load_dwordx4 v[20:23], v[20:21], off nt
	s_nop 0
	global_load_dwordx4 v[24:27], v[24:25], off nt
	v_addc_co_u32_e32 v29, vcc, 0, v9, vcc
	v_add_co_u32_e32 v32, vcc, s84, v8
	s_nop 1
	v_addc_co_u32_e32 v33, vcc, 0, v9, vcc
	v_add_co_u32_e32 v36, vcc, s85, v8
	global_load_dwordx4 v[28:31], v[28:29], off nt
	s_nop 0
	global_load_dwordx4 v[32:35], v[32:33], off nt
	v_addc_co_u32_e32 v37, vcc, 0, v9, vcc
	v_add_co_u32_e32 v40, vcc, s86, v8
	s_nop 1
	v_addc_co_u32_e32 v41, vcc, 0, v9, vcc
	global_load_dwordx4 v[36:39], v[36:37], off nt
	s_nop 0
	global_load_dwordx4 v[40:43], v[40:41], off nt
	v_add_co_u32_e32 v44, vcc, s87, v8
	s_nop 1
	v_addc_co_u32_e32 v45, vcc, 0, v9, vcc
	v_add_co_u32_e32 v48, vcc, s88, v8
	s_nop 1
	v_addc_co_u32_e32 v49, vcc, 0, v9, vcc
	global_load_dwordx4 v[44:47], v[44:45], off nt
	s_nop 0
	global_load_dwordx4 v[48:51], v[48:49], off nt
	v_add_co_u32_e32 v52, vcc, s89, v8
	s_nop 1
	v_addc_co_u32_e32 v53, vcc, 0, v9, vcc
	v_add_co_u32_e32 v56, vcc, s90, v8
	s_nop 1
	v_addc_co_u32_e32 v57, vcc, 0, v9, vcc
	global_load_dwordx4 v[52:55], v[52:53], off nt
	s_nop 0
	global_load_dwordx4 v[56:59], v[56:57], off nt
	v_add_co_u32_e32 v60, vcc, s91, v8
	s_nop 1
	v_addc_co_u32_e32 v61, vcc, 0, v9, vcc
	v_add_co_u32_e32 v64, vcc, s92, v8
	s_nop 1
	v_addc_co_u32_e32 v65, vcc, 0, v9, vcc
	global_load_dwordx4 v[60:63], v[60:61], off nt
	s_nop 0
	global_load_dwordx4 v[76:79], v[64:65], off nt
	v_add_co_u32_e32 v64, vcc, s93, v8
	s_nop 1
	v_addc_co_u32_e32 v65, vcc, 0, v9, vcc
	global_load_dwordx4 v[116:119], v[64:65], off nt
	v_add_co_u32_e32 v8, vcc, s94, v8
	s_nop 1
	v_addc_co_u32_e32 v9, vcc, 0, v9, vcc
	global_load_dwordx4 v[120:123], v[8:9], off nt
	v_add_u32_e32 v8, 0x1458, v84
	s_waitcnt vmcnt(15)
	ds_write2_b32 v84, v12, v13 offset1:1
	ds_write2_b32 v84, v14, v15 offset0:2 offset1:3
	s_waitcnt vmcnt(14)
	ds_write2_b32 v103, v16, v17 offset1:1
	ds_write2_b32 v104, v18, v19 offset1:1
	s_waitcnt vmcnt(13)
	ds_write2_b32 v105, v20, v21 offset1:1
	ds_write2_b32 v106, v22, v23 offset1:1
	s_waitcnt vmcnt(12)
	ds_write2_b32 v107, v24, v25 offset1:1
	ds_write2_b32 v108, v26, v27 offset1:1
	s_waitcnt vmcnt(11)
	ds_write2_b32 v109, v28, v29 offset1:1
	ds_write2_b32 v110, v30, v31 offset1:1
	s_waitcnt vmcnt(10)
	ds_write2_b32 v111, v32, v33 offset1:1
	ds_write2_b32 v8, v34, v35 offset1:1
	v_add_u32_e32 v8, 0x1860, v84
	s_waitcnt vmcnt(9)
	ds_write2_b32 v8, v36, v37 offset1:1
	v_add_u32_e32 v8, 0x1868, v84
	ds_write2_b32 v8, v38, v39 offset1:1
	v_add_u32_e32 v8, 0x1c70, v84
	s_waitcnt vmcnt(8)
	ds_write2_b32 v8, v40, v41 offset1:1
	v_add_u32_e32 v8, 0x1c78, v84
	ds_write2_b32 v8, v42, v43 offset1:1
	v_add_u32_e32 v8, 0x2080, v84
	s_waitcnt vmcnt(7)
	ds_write2_b32 v8, v44, v45 offset1:1
	v_add_u32_e32 v8, 0x2088, v84
	ds_write2_b32 v8, v46, v47 offset1:1
	v_add_u32_e32 v8, 0x2490, v84
	s_waitcnt vmcnt(6)
	ds_write2_b32 v8, v48, v49 offset1:1
	v_add_u32_e32 v8, 0x2498, v84
	ds_write2_b32 v8, v50, v51 offset1:1
	v_add_u32_e32 v8, 0x28a0, v84
	s_waitcnt vmcnt(5)
	ds_write2_b32 v8, v52, v53 offset1:1
	v_add_u32_e32 v8, 0x28a8, v84
	ds_write2_b32 v8, v54, v55 offset1:1
	v_add_u32_e32 v8, 0x2cb0, v84
	s_waitcnt vmcnt(4)
	ds_write2_b32 v8, v56, v57 offset1:1
	v_add_u32_e32 v8, 0x2cb8, v84
	ds_write2_b32 v8, v58, v59 offset1:1
	v_add_u32_e32 v8, 0x30c0, v84
	s_waitcnt vmcnt(3)
	ds_write2_b32 v8, v60, v61 offset1:1
	v_add_u32_e32 v8, 0x30c8, v84
	ds_write2_b32 v8, v62, v63 offset1:1
	v_add_u32_e32 v8, 0x34d0, v84
	s_waitcnt vmcnt(2)
	ds_write2_b32 v8, v76, v77 offset1:1
	v_add_u32_e32 v8, 0x34d8, v84
	ds_write2_b32 v8, v78, v79 offset1:1
	v_add_u32_e32 v8, 0x38e0, v84
	s_waitcnt vmcnt(1)
	ds_write2_b32 v8, v116, v117 offset1:1
	v_add_u32_e32 v8, 0x38e8, v84
	ds_write2_b32 v8, v118, v119 offset1:1
	v_add_u32_e32 v8, 0x3cf0, v84
	s_waitcnt vmcnt(0)
	ds_write2_b32 v8, v120, v121 offset1:1
	v_add_u32_e32 v8, 0x3cf8, v84
	ds_write2_b32 v8, v122, v123 offset1:1
	s_waitcnt lgkmcnt(0)
	ds_read2_b32 v[18:19], v11 offset0:134 offset1:142
	ds_read2_b32 v[16:17], v11 offset0:199 offset1:207
	ds_read2_b32 v[22:23], v11 offset0:4 offset1:12
	ds_read2_b32 v[20:21], v11 offset0:69 offset1:77
	ds_read2_b32 v[26:27], v86 offset0:130 offset1:138
	s_waitcnt lgkmcnt(4)
	v_bfe_u32 v13, v18, 16, 1
	s_waitcnt lgkmcnt(3)
	v_bfe_u32 v12, v16, 16, 1
	v_add3_u32 v13, v18, v13, s95
	v_add3_u32 v12, v16, v12, s95
	v_lshrrev_b32_e32 v13, 16, v13
	ds_read2_b32 v[24:25], v86 offset0:195 offset1:203
	v_and_or_b32 v15, v12, s96, v13
	s_waitcnt lgkmcnt(3)
	v_bfe_u32 v13, v22, 16, 1
	ds_read2_b32 v[30:31], v86 offset1:8
	s_waitcnt lgkmcnt(3)
	v_bfe_u32 v12, v20, 16, 1
	v_add3_u32 v13, v22, v13, s95
	ds_read2_b32 v[28:29], v86 offset0:65 offset1:73
	v_add3_u32 v12, v20, v12, s95
	v_lshrrev_b32_e32 v13, 16, v13
	v_and_or_b32 v14, v12, s96, v13
	s_waitcnt lgkmcnt(3)
	v_bfe_u32 v13, v26, 16, 1
	s_waitcnt lgkmcnt(2)
	v_bfe_u32 v12, v24, 16, 1
	v_add3_u32 v13, v26, v13, s95
	v_add3_u32 v12, v24, v12, s95
	v_lshrrev_b32_e32 v13, 16, v13
	s_waitcnt lgkmcnt(1)
	v_bfe_u32 v16, v30, 16, 1
	v_and_or_b32 v13, v12, s96, v13
	s_waitcnt lgkmcnt(0)
	v_bfe_u32 v12, v28, 16, 1
	v_add3_u32 v16, v30, v16, s95
	v_add3_u32 v12, v28, v12, s95
	v_lshrrev_b32_e32 v16, 16, v16
	v_and_or_b32 v12, v12, s96, v16
	v_or_b32_e32 v16, v10, v85
	v_lshl_add_u64 v[8:9], v[2:3], 0, v[68:69]
	v_lshlrev_b32_e32 v68, 1, v70
	v_mul_u32_u24_e32 v16, 0xa00, v16
	v_lshl_add_u64 v[8:9], v[8:9], 0, v[68:69]
	v_lshlrev_b32_e32 v68, 1, v16
	v_lshl_add_u64 v[32:33], v[8:9], 0, v[68:69]
	global_store_dwordx4 v[32:33], v[12:15], off offset:2048 nt
	v_bfe_u32 v16, v31, 16, 1
	v_add3_u32 v16, v31, v16, s95
	v_bfe_u32 v13, v19, 16, 1
	v_bfe_u32 v12, v17, 16, 1
	v_add3_u32 v13, v19, v13, s95
	v_add3_u32 v12, v17, v12, s95
	v_lshrrev_b32_e32 v13, 16, v13
	v_and_or_b32 v15, v12, s96, v13
	v_bfe_u32 v13, v23, 16, 1
	v_bfe_u32 v12, v21, 16, 1
	v_add3_u32 v13, v23, v13, s95
	v_add3_u32 v12, v21, v12, s95
	v_lshrrev_b32_e32 v13, 16, v13
	v_and_or_b32 v14, v12, s96, v13
	v_bfe_u32 v13, v27, 16, 1
	v_bfe_u32 v12, v25, 16, 1
	v_add3_u32 v13, v27, v13, s95
	v_add3_u32 v12, v25, v12, s95
	v_lshrrev_b32_e32 v13, 16, v13
	v_and_or_b32 v13, v12, s96, v13
	v_bfe_u32 v12, v29, 16, 1
	v_add3_u32 v12, v29, v12, s95
	v_lshrrev_b32_e32 v16, 16, v16
	v_and_or_b32 v12, v12, s96, v16
	v_or_b32_e32 v16, v10, v87
	v_mul_u32_u24_e32 v18, 0xa00, v16
	v_lshlrev_b32_e32 v68, 1, v18
	ds_read2_b32 v[18:19], v11 offset0:150 offset1:158
	ds_read2_b32 v[16:17], v11 offset0:215 offset1:223
	v_lshl_add_u64 v[20:21], v[8:9], 0, v[68:69]
	ds_read2_b32 v[22:23], v11 offset0:20 offset1:28
	global_store_dwordx4 v[20:21], v[12:15], off offset:2048 nt
	ds_read2_b32 v[20:21], v11 offset0:85 offset1:93
	ds_read2_b32 v[26:27], v86 offset0:146 offset1:154
	s_waitcnt lgkmcnt(4)
	v_bfe_u32 v13, v18, 16, 1
	s_waitcnt lgkmcnt(3)
	v_bfe_u32 v12, v16, 16, 1
	v_add3_u32 v13, v18, v13, s95
	v_add3_u32 v12, v16, v12, s95
	v_lshrrev_b32_e32 v13, 16, v13
	ds_read2_b32 v[24:25], v86 offset0:211 offset1:219
	v_and_or_b32 v15, v12, s96, v13
	s_waitcnt lgkmcnt(3)
	v_bfe_u32 v13, v22, 16, 1
	ds_read2_b32 v[30:31], v86 offset0:16 offset1:24
	s_waitcnt lgkmcnt(3)
	v_bfe_u32 v12, v20, 16, 1
	v_add3_u32 v13, v22, v13, s95
	ds_read2_b32 v[28:29], v86 offset0:81 offset1:89
	v_add3_u32 v12, v20, v12, s95
	v_lshrrev_b32_e32 v13, 16, v13
	v_and_or_b32 v14, v12, s96, v13
	s_waitcnt lgkmcnt(3)
	v_bfe_u32 v13, v26, 16, 1
	s_waitcnt lgkmcnt(2)
	v_bfe_u32 v12, v24, 16, 1
	v_add3_u32 v13, v26, v13, s95
	v_add3_u32 v12, v24, v12, s95
	v_lshrrev_b32_e32 v13, 16, v13
	s_waitcnt lgkmcnt(1)
	v_bfe_u32 v16, v30, 16, 1
	v_and_or_b32 v13, v12, s96, v13
	s_waitcnt lgkmcnt(0)
	v_bfe_u32 v12, v28, 16, 1
	v_add3_u32 v16, v30, v16, s95
	v_add3_u32 v12, v28, v12, s95
	v_lshrrev_b32_e32 v16, 16, v16
	v_and_or_b32 v12, v12, s96, v16
	v_or_b32_e32 v16, v10, v88
	v_mul_u32_u24_e32 v16, 0xa00, v16
	v_lshlrev_b32_e32 v68, 1, v16
	v_lshl_add_u64 v[32:33], v[8:9], 0, v[68:69]
	global_store_dwordx4 v[32:33], v[12:15], off offset:2048 nt
	v_bfe_u32 v16, v31, 16, 1
	v_add3_u32 v16, v31, v16, s95
	v_bfe_u32 v13, v19, 16, 1
	v_bfe_u32 v12, v17, 16, 1
	v_add3_u32 v13, v19, v13, s95
	v_add3_u32 v12, v17, v12, s95
	v_lshrrev_b32_e32 v13, 16, v13
	v_and_or_b32 v15, v12, s96, v13
	v_bfe_u32 v13, v23, 16, 1
	v_bfe_u32 v12, v21, 16, 1
	v_add3_u32 v13, v23, v13, s95
	v_add3_u32 v12, v21, v12, s95
	v_lshrrev_b32_e32 v13, 16, v13
	v_and_or_b32 v14, v12, s96, v13
	v_bfe_u32 v13, v27, 16, 1
	v_bfe_u32 v12, v25, 16, 1
	v_add3_u32 v13, v27, v13, s95
	v_add3_u32 v12, v25, v12, s95
	v_lshrrev_b32_e32 v13, 16, v13
	v_and_or_b32 v13, v12, s96, v13
	v_bfe_u32 v12, v29, 16, 1
	v_add3_u32 v12, v29, v12, s95
	v_lshrrev_b32_e32 v16, 16, v16
	v_and_or_b32 v12, v12, s96, v16
	v_or_b32_e32 v16, v10, v89
	v_mul_u32_u24_e32 v18, 0xa00, v16
	v_lshlrev_b32_e32 v68, 1, v18
	ds_read2_b32 v[18:19], v11 offset0:166 offset1:174
	ds_read2_b32 v[16:17], v11 offset0:231 offset1:239
	v_lshl_add_u64 v[20:21], v[8:9], 0, v[68:69]
	ds_read2_b32 v[22:23], v11 offset0:36 offset1:44
	global_store_dwordx4 v[20:21], v[12:15], off offset:2048 nt
	ds_read2_b32 v[20:21], v11 offset0:101 offset1:109
	ds_read2_b32 v[26:27], v86 offset0:162 offset1:170
	s_waitcnt lgkmcnt(4)
	v_bfe_u32 v13, v18, 16, 1
	s_waitcnt lgkmcnt(3)
	v_bfe_u32 v12, v16, 16, 1
	v_add3_u32 v13, v18, v13, s95
	v_add3_u32 v12, v16, v12, s95
	v_lshrrev_b32_e32 v13, 16, v13
	ds_read2_b32 v[24:25], v86 offset0:227 offset1:235
	v_and_or_b32 v15, v12, s96, v13
	s_waitcnt lgkmcnt(3)
	v_bfe_u32 v13, v22, 16, 1
	ds_read2_b32 v[30:31], v86 offset0:32 offset1:40
	s_waitcnt lgkmcnt(3)
	v_bfe_u32 v12, v20, 16, 1
	v_add3_u32 v13, v22, v13, s95
	ds_read2_b32 v[28:29], v86 offset0:97 offset1:105
	v_add3_u32 v12, v20, v12, s95
	v_lshrrev_b32_e32 v13, 16, v13
	v_and_or_b32 v14, v12, s96, v13
	s_waitcnt lgkmcnt(3)
	v_bfe_u32 v13, v26, 16, 1
	s_waitcnt lgkmcnt(2)
	v_bfe_u32 v12, v24, 16, 1
	v_add3_u32 v13, v26, v13, s95
	v_add3_u32 v12, v24, v12, s95
	v_lshrrev_b32_e32 v13, 16, v13
	s_waitcnt lgkmcnt(1)
	v_bfe_u32 v16, v30, 16, 1
	v_and_or_b32 v13, v12, s96, v13
	s_waitcnt lgkmcnt(0)
	v_bfe_u32 v12, v28, 16, 1
	v_add3_u32 v16, v30, v16, s95
	v_add3_u32 v12, v28, v12, s95
	v_lshrrev_b32_e32 v16, 16, v16
	v_and_or_b32 v12, v12, s96, v16
	v_or_b32_e32 v16, v10, v90
	v_mul_u32_u24_e32 v16, 0xa00, v16
	v_lshlrev_b32_e32 v68, 1, v16
	v_lshl_add_u64 v[32:33], v[8:9], 0, v[68:69]
	global_store_dwordx4 v[32:33], v[12:15], off offset:2048 nt
	v_bfe_u32 v16, v31, 16, 1
	v_add3_u32 v16, v31, v16, s95
	v_bfe_u32 v13, v19, 16, 1
	v_bfe_u32 v12, v17, 16, 1
	v_add3_u32 v13, v19, v13, s95
	v_add3_u32 v12, v17, v12, s95
	v_lshrrev_b32_e32 v13, 16, v13
	v_and_or_b32 v15, v12, s96, v13
	v_bfe_u32 v13, v23, 16, 1
	v_bfe_u32 v12, v21, 16, 1
	v_add3_u32 v13, v23, v13, s95
	v_add3_u32 v12, v21, v12, s95
	v_lshrrev_b32_e32 v13, 16, v13
	v_and_or_b32 v14, v12, s96, v13
	v_bfe_u32 v13, v27, 16, 1
	v_bfe_u32 v12, v25, 16, 1
	v_add3_u32 v13, v27, v13, s95
	v_add3_u32 v12, v25, v12, s95
	v_lshrrev_b32_e32 v13, 16, v13
	v_and_or_b32 v13, v12, s96, v13
	v_bfe_u32 v12, v29, 16, 1
	v_add3_u32 v12, v29, v12, s95
	v_lshrrev_b32_e32 v16, 16, v16
	v_and_or_b32 v12, v12, s96, v16
	v_or_b32_e32 v16, v10, v91
	v_mul_u32_u24_e32 v18, 0xa00, v16
	v_lshlrev_b32_e32 v68, 1, v18
	ds_read2_b32 v[18:19], v11 offset0:182 offset1:190
	ds_read2_b32 v[16:17], v11 offset0:247 offset1:255
	v_lshl_add_u64 v[20:21], v[8:9], 0, v[68:69]
	ds_read2_b32 v[22:23], v11 offset0:52 offset1:60
	global_store_dwordx4 v[20:21], v[12:15], off offset:2048 nt
	ds_read2_b32 v[20:21], v11 offset0:117 offset1:125
	ds_read2_b32 v[26:27], v86 offset0:178 offset1:186
	s_waitcnt lgkmcnt(4)
	v_bfe_u32 v13, v18, 16, 1
	s_waitcnt lgkmcnt(3)
	v_bfe_u32 v12, v16, 16, 1
	v_add3_u32 v13, v18, v13, s95
	v_add3_u32 v12, v16, v12, s95
	v_lshrrev_b32_e32 v11, 16, v13
	ds_read2_b32 v[24:25], v86 offset0:243 offset1:251
	v_and_or_b32 v15, v12, s96, v11
	s_waitcnt lgkmcnt(3)
	v_bfe_u32 v12, v22, 16, 1
	s_waitcnt lgkmcnt(2)
	v_bfe_u32 v11, v20, 16, 1
	v_add3_u32 v12, v22, v12, s95
	ds_read2_b32 v[30:31], v86 offset0:48 offset1:56
	v_add3_u32 v11, v20, v11, s95
	v_lshrrev_b32_e32 v12, 16, v12
	ds_read2_b32 v[28:29], v86 offset0:113 offset1:121
	v_and_or_b32 v14, v11, s96, v12
	s_waitcnt lgkmcnt(3)
	v_bfe_u32 v12, v26, 16, 1
	s_waitcnt lgkmcnt(2)
	v_bfe_u32 v11, v24, 16, 1
	v_add3_u32 v12, v26, v12, s95
	v_add3_u32 v11, v24, v11, s95
	v_lshrrev_b32_e32 v12, 16, v12
	v_and_or_b32 v13, v11, s96, v12
	s_waitcnt lgkmcnt(1)
	v_bfe_u32 v12, v30, 16, 1
	s_waitcnt lgkmcnt(0)
	v_bfe_u32 v11, v28, 16, 1
	v_add3_u32 v12, v30, v12, s95
	v_add3_u32 v11, v28, v11, s95
	v_lshrrev_b32_e32 v12, 16, v12
	v_and_or_b32 v12, v11, s96, v12
	v_or_b32_e32 v11, v10, v92
	v_mul_u32_u24_e32 v11, 0xa00, v11
	v_lshlrev_b32_e32 v68, 1, v11
	v_lshl_add_u64 v[32:33], v[8:9], 0, v[68:69]
	global_store_dwordx4 v[32:33], v[12:15], off offset:2048 nt
	v_bfe_u32 v11, v17, 16, 1
	v_add3_u32 v11, v17, v11, s95
	v_bfe_u32 v12, v19, 16, 1
	v_add3_u32 v12, v19, v12, s95
	v_lshrrev_b32_e32 v12, 16, v12
	v_and_or_b32 v15, v11, s96, v12
	v_bfe_u32 v12, v23, 16, 1
	v_bfe_u32 v11, v21, 16, 1
	v_add3_u32 v12, v23, v12, s95
	v_add3_u32 v11, v21, v11, s95
	v_lshrrev_b32_e32 v12, 16, v12
	v_and_or_b32 v14, v11, s96, v12
	v_bfe_u32 v12, v27, 16, 1
	v_bfe_u32 v11, v25, 16, 1
	v_add3_u32 v12, v27, v12, s95
	v_add3_u32 v11, v25, v11, s95
	v_lshrrev_b32_e32 v12, 16, v12
	v_and_or_b32 v13, v11, s96, v12
	v_bfe_u32 v12, v31, 16, 1
	v_or_b32_e32 v10, v10, v93
	v_bfe_u32 v11, v29, 16, 1
	v_add3_u32 v12, v31, v12, s95
	v_mul_u32_u24_e32 v10, 0xa00, v10
	v_add3_u32 v11, v29, v11, s95
	v_lshrrev_b32_e32 v12, 16, v12
	v_lshlrev_b32_e32 v68, 1, v10
	v_and_or_b32 v12, v11, s96, v12
	v_lshl_add_u64 v[8:9], v[8:9], 0, v[68:69]
	global_store_dwordx4 v[8:9], v[12:15], off offset:2048 nt
	s_waitcnt lgkmcnt(0)
	s_or_b64 exec, exec, s[4:5]
	s_and_b64 exec, exec, s[2:3]
	s_cbranch_execz .LBB0_95

.LBB0_31:
	v_lshl_add_u64 v[8:9], v[6:7], 2, s[42:43]
	v_lshlrev_b32_e32 v7, 1, v81
	v_and_b32_e32 v7, 0x3c0, v7
	v_lshlrev_b32_e32 v6, 6, v81
	v_or_b32_e32 v10, v7, v83
	v_and_b32_e32 v6, 0x7c0, v6
	v_lshlrev_b32_e32 v68, 13, v10
	v_lshl_add_u64 v[8:9], v[8:9], 0, v[68:69]
	v_lshlrev_b32_e32 v68, 2, v6
	v_lshl_add_u64 v[8:9], v[8:9], 0, v[68:69]
	v_mov_b32_e32 v73, v69
	v_lshl_add_u64 v[64:65], v[8:9], 0, v[72:73]
	v_add_co_u32_e32 v12, vcc, s78, v64
	v_lshlrev_b32_e32 v68, 1, v7
	s_nop 0
	v_addc_co_u32_e32 v13, vcc, 0, v65, vcc
	v_add_co_u32_e32 v16, vcc, s79, v64
	global_load_dwordx4 v[8:11], v[64:65], off nt
	s_nop 0
	global_load_dwordx4 v[12:15], v[12:13], off nt
	v_addc_co_u32_e32 v17, vcc, 0, v65, vcc
	v_add_co_u32_e32 v20, vcc, s82, v64
	v_add_u32_e32 v7, 0x400, v86
	s_nop 0
	v_addc_co_u32_e32 v21, vcc, 0, v65, vcc
	v_add_co_u32_e32 v24, vcc, s83, v64
	global_load_dwordx4 v[16:19], v[16:17], off nt
	s_nop 0
	global_load_dwordx4 v[20:23], v[20:21], off nt
	v_addc_co_u32_e32 v25, vcc, 0, v65, vcc
	v_add_co_u32_e32 v28, vcc, s84, v64
	v_lshl_add_u64 v[2:3], v[2:3], 0, v[68:69]
	s_nop 0
	v_addc_co_u32_e32 v29, vcc, 0, v65, vcc
	v_add_co_u32_e32 v32, vcc, s85, v64
	global_load_dwordx4 v[24:27], v[24:25], off nt
	s_nop 0
	global_load_dwordx4 v[28:31], v[28:29], off nt
	v_addc_co_u32_e32 v33, vcc, 0, v65, vcc
	v_add_co_u32_e32 v36, vcc, s86, v64
	v_lshlrev_b32_e32 v68, 1, v70
	s_nop 0
	v_addc_co_u32_e32 v37, vcc, 0, v65, vcc
	global_load_dwordx4 v[32:35], v[32:33], off nt
	s_nop 0
	global_load_dwordx4 v[36:39], v[36:37], off nt
	v_add_co_u32_e32 v40, vcc, s87, v64
	v_lshl_add_u64 v[2:3], v[2:3], 0, v[68:69]
	s_nop 0
	v_addc_co_u32_e32 v41, vcc, 0, v65, vcc
	v_add_co_u32_e32 v44, vcc, s88, v64
	s_nop 1
	v_addc_co_u32_e32 v45, vcc, 0, v65, vcc
	global_load_dwordx4 v[40:43], v[40:41], off nt
	s_nop 0
	global_load_dwordx4 v[44:47], v[44:45], off nt
	v_add_co_u32_e32 v48, vcc, s89, v64
	s_nop 1
	v_addc_co_u32_e32 v49, vcc, 0, v65, vcc
	v_add_co_u32_e32 v52, vcc, s90, v64
	s_nop 1
	v_addc_co_u32_e32 v53, vcc, 0, v65, vcc
	global_load_dwordx4 v[48:51], v[48:49], off nt
	s_nop 0
	global_load_dwordx4 v[52:55], v[52:53], off nt
	v_add_co_u32_e32 v56, vcc, s91, v64
	s_nop 1
	v_addc_co_u32_e32 v57, vcc, 0, v65, vcc
	v_add_co_u32_e32 v60, vcc, s92, v64
	s_nop 1
	v_addc_co_u32_e32 v61, vcc, 0, v65, vcc
	global_load_dwordx4 v[56:59], v[56:57], off nt
	s_nop 0
	global_load_dwordx4 v[60:63], v[60:61], off nt
	v_add_co_u32_e32 v76, vcc, s93, v64
	s_nop 1
	v_addc_co_u32_e32 v77, vcc, 0, v65, vcc
	global_load_dwordx4 v[76:79], v[76:77], off nt
	v_add_co_u32_e32 v64, vcc, s94, v64
	s_nop 1
	v_addc_co_u32_e32 v65, vcc, 0, v65, vcc
	global_load_dwordx4 v[116:119], v[64:65], off nt
	s_waitcnt vmcnt(15)
	ds_write2_b32 v84, v8, v9 offset1:1
	ds_write2_b32 v84, v10, v11 offset0:2 offset1:3
	s_waitcnt vmcnt(14)
	ds_write2_b32 v103, v12, v13 offset1:1
	ds_write2_b32 v104, v14, v15 offset1:1
	s_waitcnt vmcnt(13)
	ds_write2_b32 v105, v16, v17 offset1:1
	ds_write2_b32 v106, v18, v19 offset1:1
	s_waitcnt vmcnt(12)
	ds_write2_b32 v107, v20, v21 offset1:1
	ds_write2_b32 v108, v22, v23 offset1:1
	s_waitcnt vmcnt(11)
	ds_write2_b32 v109, v24, v25 offset1:1
	ds_write2_b32 v110, v26, v27 offset1:1
	s_waitcnt vmcnt(10)
	ds_write2_b32 v111, v28, v29 offset1:1
	v_add_u32_e32 v8, 0x1458, v84
	ds_write2_b32 v8, v30, v31 offset1:1
	v_add_u32_e32 v8, 0x1860, v84
	s_waitcnt vmcnt(9)
	ds_write2_b32 v8, v32, v33 offset1:1
	v_add_u32_e32 v8, 0x1868, v84
	ds_write2_b32 v8, v34, v35 offset1:1
	v_add_u32_e32 v8, 0x1c70, v84
	s_waitcnt vmcnt(8)
	ds_write2_b32 v8, v36, v37 offset1:1
	v_add_u32_e32 v8, 0x1c78, v84
	ds_write2_b32 v8, v38, v39 offset1:1
	v_add_u32_e32 v8, 0x2080, v84
	s_waitcnt vmcnt(7)
	ds_write2_b32 v8, v40, v41 offset1:1
	v_add_u32_e32 v8, 0x2088, v84
	ds_write2_b32 v8, v42, v43 offset1:1
	v_add_u32_e32 v8, 0x2490, v84
	s_waitcnt vmcnt(6)
	ds_write2_b32 v8, v44, v45 offset1:1
	v_add_u32_e32 v8, 0x2498, v84
	ds_write2_b32 v8, v46, v47 offset1:1
	v_add_u32_e32 v8, 0x28a0, v84
	s_waitcnt vmcnt(5)
	ds_write2_b32 v8, v48, v49 offset1:1
	v_add_u32_e32 v8, 0x28a8, v84
	ds_write2_b32 v8, v50, v51 offset1:1
	v_add_u32_e32 v8, 0x2cb0, v84
	s_waitcnt vmcnt(4)
	ds_write2_b32 v8, v52, v53 offset1:1
	v_add_u32_e32 v8, 0x2cb8, v84
	ds_write2_b32 v8, v54, v55 offset1:1
	v_add_u32_e32 v8, 0x30c0, v84
	s_waitcnt vmcnt(3)
	ds_write2_b32 v8, v56, v57 offset1:1
	v_add_u32_e32 v8, 0x30c8, v84
	ds_write2_b32 v8, v58, v59 offset1:1
	v_add_u32_e32 v8, 0x34d0, v84
	s_waitcnt vmcnt(2)
	ds_write2_b32 v8, v60, v61 offset1:1
	v_add_u32_e32 v8, 0x34d8, v84
	ds_write2_b32 v8, v62, v63 offset1:1
	v_add_u32_e32 v8, 0x38e0, v84
	s_waitcnt vmcnt(1)
	ds_write2_b32 v8, v76, v77 offset1:1
	v_add_u32_e32 v8, 0x38e8, v84
	ds_write2_b32 v8, v78, v79 offset1:1
	v_add_u32_e32 v8, 0x3cf0, v84
	s_waitcnt vmcnt(0)
	ds_write2_b32 v8, v116, v117 offset1:1
	v_add_u32_e32 v8, 0x3cf8, v84
	ds_write2_b32 v8, v118, v119 offset1:1
	s_waitcnt lgkmcnt(0)
	ds_read2_b32 v[14:15], v7 offset0:134 offset1:142
	ds_read2_b32 v[12:13], v7 offset0:199 offset1:207
	ds_read2_b32 v[18:19], v7 offset0:4 offset1:12
	ds_read2_b32 v[16:17], v7 offset0:69 offset1:77
	ds_read2_b32 v[22:23], v86 offset0:130 offset1:138
	s_waitcnt lgkmcnt(4)
	v_bfe_u32 v9, v14, 16, 1
	s_waitcnt lgkmcnt(3)
	v_bfe_u32 v8, v12, 16, 1
	v_add3_u32 v9, v14, v9, s95
	v_add3_u32 v8, v12, v8, s95
	v_lshrrev_b32_e32 v9, 16, v9
	ds_read2_b32 v[20:21], v86 offset0:195 offset1:203
	v_and_or_b32 v11, v8, s96, v9
	s_waitcnt lgkmcnt(3)
	v_bfe_u32 v9, v18, 16, 1
	ds_read2_b32 v[26:27], v86 offset1:8
	s_waitcnt lgkmcnt(3)
	v_bfe_u32 v8, v16, 16, 1
	v_add3_u32 v9, v18, v9, s95
	ds_read2_b32 v[24:25], v86 offset0:65 offset1:73
	v_add3_u32 v8, v16, v8, s95
	v_lshrrev_b32_e32 v9, 16, v9
	v_and_or_b32 v10, v8, s96, v9
	s_waitcnt lgkmcnt(3)
	v_bfe_u32 v9, v22, 16, 1
	s_waitcnt lgkmcnt(2)
	v_bfe_u32 v8, v20, 16, 1
	v_add3_u32 v9, v22, v9, s95
	v_add3_u32 v8, v20, v8, s95
	v_lshrrev_b32_e32 v9, 16, v9
	s_waitcnt lgkmcnt(1)
	v_bfe_u32 v12, v26, 16, 1
	v_and_or_b32 v9, v8, s96, v9
	s_waitcnt lgkmcnt(0)
	v_bfe_u32 v8, v24, 16, 1
	v_add3_u32 v12, v26, v12, s95
	v_add3_u32 v8, v24, v8, s95
	v_lshrrev_b32_e32 v12, 16, v12
	v_and_or_b32 v8, v8, s96, v12
	v_or_b32_e32 v12, v6, v85
	v_mul_u32_u24_e32 v12, 0xa00, v12
	v_lshlrev_b32_e32 v68, 1, v12
	v_lshl_add_u64 v[28:29], v[2:3], 0, v[68:69]
	global_store_dwordx4 v[28:29], v[8:11], off offset:3072 nt
	v_bfe_u32 v12, v27, 16, 1
	v_add3_u32 v12, v27, v12, s95
	v_bfe_u32 v9, v15, 16, 1
	v_bfe_u32 v8, v13, 16, 1
	v_add3_u32 v9, v15, v9, s95
	v_add3_u32 v8, v13, v8, s95
	v_lshrrev_b32_e32 v9, 16, v9
	v_and_or_b32 v11, v8, s96, v9
	v_bfe_u32 v9, v19, 16, 1
	v_bfe_u32 v8, v17, 16, 1
	v_add3_u32 v9, v19, v9, s95
	v_add3_u32 v8, v17, v8, s95
	v_lshrrev_b32_e32 v9, 16, v9
	v_and_or_b32 v10, v8, s96, v9
	v_bfe_u32 v9, v23, 16, 1
	v_bfe_u32 v8, v21, 16, 1
	v_add3_u32 v9, v23, v9, s95
	v_add3_u32 v8, v21, v8, s95
	v_lshrrev_b32_e32 v9, 16, v9
	v_and_or_b32 v9, v8, s96, v9
	v_bfe_u32 v8, v25, 16, 1
	v_add3_u32 v8, v25, v8, s95
	v_lshrrev_b32_e32 v12, 16, v12
	v_and_or_b32 v8, v8, s96, v12
	v_or_b32_e32 v12, v6, v87
	v_mul_u32_u24_e32 v14, 0xa00, v12
	v_lshlrev_b32_e32 v68, 1, v14
	ds_read2_b32 v[14:15], v7 offset0:150 offset1:158
	ds_read2_b32 v[12:13], v7 offset0:215 offset1:223
	v_lshl_add_u64 v[16:17], v[2:3], 0, v[68:69]
	ds_read2_b32 v[18:19], v7 offset0:20 offset1:28
	global_store_dwordx4 v[16:17], v[8:11], off offset:3072 nt
	ds_read2_b32 v[16:17], v7 offset0:85 offset1:93
	ds_read2_b32 v[22:23], v86 offset0:146 offset1:154
	s_waitcnt lgkmcnt(4)
	v_bfe_u32 v9, v14, 16, 1
	s_waitcnt lgkmcnt(3)
	v_bfe_u32 v8, v12, 16, 1
	v_add3_u32 v9, v14, v9, s95
	v_add3_u32 v8, v12, v8, s95
	v_lshrrev_b32_e32 v9, 16, v9
	ds_read2_b32 v[20:21], v86 offset0:211 offset1:219
	v_and_or_b32 v11, v8, s96, v9
	s_waitcnt lgkmcnt(3)
	v_bfe_u32 v9, v18, 16, 1
	ds_read2_b32 v[26:27], v86 offset0:16 offset1:24
	s_waitcnt lgkmcnt(3)
	v_bfe_u32 v8, v16, 16, 1
	v_add3_u32 v9, v18, v9, s95
	ds_read2_b32 v[24:25], v86 offset0:81 offset1:89
	v_add3_u32 v8, v16, v8, s95
	v_lshrrev_b32_e32 v9, 16, v9
	v_and_or_b32 v10, v8, s96, v9
	s_waitcnt lgkmcnt(3)
	v_bfe_u32 v9, v22, 16, 1
	s_waitcnt lgkmcnt(2)
	v_bfe_u32 v8, v20, 16, 1
	v_add3_u32 v9, v22, v9, s95
	v_add3_u32 v8, v20, v8, s95
	v_lshrrev_b32_e32 v9, 16, v9
	s_waitcnt lgkmcnt(1)
	v_bfe_u32 v12, v26, 16, 1
	v_and_or_b32 v9, v8, s96, v9
	s_waitcnt lgkmcnt(0)
	v_bfe_u32 v8, v24, 16, 1
	v_add3_u32 v12, v26, v12, s95
	v_add3_u32 v8, v24, v8, s95
	v_lshrrev_b32_e32 v12, 16, v12
	v_and_or_b32 v8, v8, s96, v12
	v_or_b32_e32 v12, v6, v88
	v_mul_u32_u24_e32 v12, 0xa00, v12
	v_lshlrev_b32_e32 v68, 1, v12
	v_lshl_add_u64 v[28:29], v[2:3], 0, v[68:69]
	global_store_dwordx4 v[28:29], v[8:11], off offset:3072 nt
	v_bfe_u32 v12, v27, 16, 1
	v_add3_u32 v12, v27, v12, s95
	v_bfe_u32 v9, v15, 16, 1
	v_bfe_u32 v8, v13, 16, 1
	v_add3_u32 v9, v15, v9, s95
	v_add3_u32 v8, v13, v8, s95
	v_lshrrev_b32_e32 v9, 16, v9
	v_and_or_b32 v11, v8, s96, v9
	v_bfe_u32 v9, v19, 16, 1
	v_bfe_u32 v8, v17, 16, 1
	v_add3_u32 v9, v19, v9, s95
	v_add3_u32 v8, v17, v8, s95
	v_lshrrev_b32_e32 v9, 16, v9
	v_and_or_b32 v10, v8, s96, v9
	v_bfe_u32 v9, v23, 16, 1
	v_bfe_u32 v8, v21, 16, 1
	v_add3_u32 v9, v23, v9, s95
	v_add3_u32 v8, v21, v8, s95
	v_lshrrev_b32_e32 v9, 16, v9
	v_and_or_b32 v9, v8, s96, v9
	v_bfe_u32 v8, v25, 16, 1
	v_add3_u32 v8, v25, v8, s95
	v_lshrrev_b32_e32 v12, 16, v12
	v_and_or_b32 v8, v8, s96, v12
	v_or_b32_e32 v12, v6, v89
	v_mul_u32_u24_e32 v14, 0xa00, v12
	v_lshlrev_b32_e32 v68, 1, v14
	ds_read2_b32 v[14:15], v7 offset0:166 offset1:174
	ds_read2_b32 v[12:13], v7 offset0:231 offset1:239
	v_lshl_add_u64 v[16:17], v[2:3], 0, v[68:69]
	ds_read2_b32 v[18:19], v7 offset0:36 offset1:44
	global_store_dwordx4 v[16:17], v[8:11], off offset:3072 nt
	ds_read2_b32 v[16:17], v7 offset0:101 offset1:109
	ds_read2_b32 v[22:23], v86 offset0:162 offset1:170
	s_waitcnt lgkmcnt(4)
	v_bfe_u32 v9, v14, 16, 1
	s_waitcnt lgkmcnt(3)
	v_bfe_u32 v8, v12, 16, 1
	v_add3_u32 v9, v14, v9, s95
	v_add3_u32 v8, v12, v8, s95
	v_lshrrev_b32_e32 v9, 16, v9
	ds_read2_b32 v[20:21], v86 offset0:227 offset1:235
	v_and_or_b32 v11, v8, s96, v9
	s_waitcnt lgkmcnt(3)
	v_bfe_u32 v9, v18, 16, 1
	ds_read2_b32 v[26:27], v86 offset0:32 offset1:40
	s_waitcnt lgkmcnt(3)
	v_bfe_u32 v8, v16, 16, 1
	v_add3_u32 v9, v18, v9, s95
	ds_read2_b32 v[24:25], v86 offset0:97 offset1:105
	v_add3_u32 v8, v16, v8, s95
	v_lshrrev_b32_e32 v9, 16, v9
	v_and_or_b32 v10, v8, s96, v9
	s_waitcnt lgkmcnt(3)
	v_bfe_u32 v9, v22, 16, 1
	s_waitcnt lgkmcnt(2)
	v_bfe_u32 v8, v20, 16, 1
	v_add3_u32 v9, v22, v9, s95
	v_add3_u32 v8, v20, v8, s95
	v_lshrrev_b32_e32 v9, 16, v9
	s_waitcnt lgkmcnt(1)
	v_bfe_u32 v12, v26, 16, 1
	v_and_or_b32 v9, v8, s96, v9
	s_waitcnt lgkmcnt(0)
	v_bfe_u32 v8, v24, 16, 1
	v_add3_u32 v12, v26, v12, s95
	v_add3_u32 v8, v24, v8, s95
	v_lshrrev_b32_e32 v12, 16, v12
	v_and_or_b32 v8, v8, s96, v12
	v_or_b32_e32 v12, v6, v90
	v_mul_u32_u24_e32 v12, 0xa00, v12
	v_lshlrev_b32_e32 v68, 1, v12
	v_lshl_add_u64 v[28:29], v[2:3], 0, v[68:69]
	global_store_dwordx4 v[28:29], v[8:11], off offset:3072 nt
	v_bfe_u32 v12, v27, 16, 1
	v_add3_u32 v12, v27, v12, s95
	v_bfe_u32 v9, v15, 16, 1
	v_bfe_u32 v8, v13, 16, 1
	v_add3_u32 v9, v15, v9, s95
	v_add3_u32 v8, v13, v8, s95
	v_lshrrev_b32_e32 v9, 16, v9
	v_and_or_b32 v11, v8, s96, v9
	v_bfe_u32 v9, v19, 16, 1
	v_bfe_u32 v8, v17, 16, 1
	v_add3_u32 v9, v19, v9, s95
	v_add3_u32 v8, v17, v8, s95
	v_lshrrev_b32_e32 v9, 16, v9
	v_and_or_b32 v10, v8, s96, v9
	v_bfe_u32 v9, v23, 16, 1
	v_bfe_u32 v8, v21, 16, 1
	v_add3_u32 v9, v23, v9, s95
	v_add3_u32 v8, v21, v8, s95
	v_lshrrev_b32_e32 v9, 16, v9
	v_and_or_b32 v9, v8, s96, v9
	v_bfe_u32 v8, v25, 16, 1
	v_add3_u32 v8, v25, v8, s95
	v_lshrrev_b32_e32 v12, 16, v12
	v_and_or_b32 v8, v8, s96, v12
	v_or_b32_e32 v12, v6, v91
	v_mul_u32_u24_e32 v14, 0xa00, v12
	v_lshlrev_b32_e32 v68, 1, v14
	ds_read2_b32 v[14:15], v7 offset0:182 offset1:190
	ds_read2_b32 v[12:13], v7 offset0:247 offset1:255
	v_lshl_add_u64 v[16:17], v[2:3], 0, v[68:69]
	ds_read2_b32 v[18:19], v7 offset0:52 offset1:60
	global_store_dwordx4 v[16:17], v[8:11], off offset:3072 nt
	ds_read2_b32 v[16:17], v7 offset0:117 offset1:125
	ds_read2_b32 v[22:23], v86 offset0:178 offset1:186
	s_waitcnt lgkmcnt(4)
	v_bfe_u32 v9, v14, 16, 1
	s_waitcnt lgkmcnt(3)
	v_bfe_u32 v8, v12, 16, 1
	v_add3_u32 v9, v14, v9, s95
	v_add3_u32 v8, v12, v8, s95
	v_lshrrev_b32_e32 v7, 16, v9
	ds_read2_b32 v[20:21], v86 offset0:243 offset1:251
	v_and_or_b32 v11, v8, s96, v7
	s_waitcnt lgkmcnt(3)
	v_bfe_u32 v8, v18, 16, 1
	s_waitcnt lgkmcnt(2)
	v_bfe_u32 v7, v16, 16, 1
	v_add3_u32 v8, v18, v8, s95
	ds_read2_b32 v[26:27], v86 offset0:48 offset1:56
	v_add3_u32 v7, v16, v7, s95
	v_lshrrev_b32_e32 v8, 16, v8
	ds_read2_b32 v[24:25], v86 offset0:113 offset1:121
	v_and_or_b32 v10, v7, s96, v8
	s_waitcnt lgkmcnt(3)
	v_bfe_u32 v8, v22, 16, 1
	s_waitcnt lgkmcnt(2)
	v_bfe_u32 v7, v20, 16, 1
	v_add3_u32 v8, v22, v8, s95
	v_add3_u32 v7, v20, v7, s95
	v_lshrrev_b32_e32 v8, 16, v8
	v_and_or_b32 v9, v7, s96, v8
	s_waitcnt lgkmcnt(1)
	v_bfe_u32 v8, v26, 16, 1
	s_waitcnt lgkmcnt(0)
	v_bfe_u32 v7, v24, 16, 1
	v_add3_u32 v8, v26, v8, s95
	v_add3_u32 v7, v24, v7, s95
	v_lshrrev_b32_e32 v8, 16, v8
	v_and_or_b32 v8, v7, s96, v8
	v_or_b32_e32 v7, v6, v92
	v_mul_u32_u24_e32 v7, 0xa00, v7
	v_lshlrev_b32_e32 v68, 1, v7
	v_lshl_add_u64 v[28:29], v[2:3], 0, v[68:69]
	global_store_dwordx4 v[28:29], v[8:11], off offset:3072 nt
	v_bfe_u32 v7, v13, 16, 1
	v_add3_u32 v7, v13, v7, s95
	v_bfe_u32 v8, v15, 16, 1
	v_add3_u32 v8, v15, v8, s95
	v_lshrrev_b32_e32 v8, 16, v8
	v_and_or_b32 v11, v7, s96, v8
	v_bfe_u32 v8, v19, 16, 1
	v_bfe_u32 v7, v17, 16, 1
	v_add3_u32 v8, v19, v8, s95
	v_add3_u32 v7, v17, v7, s95
	v_lshrrev_b32_e32 v8, 16, v8
	v_and_or_b32 v10, v7, s96, v8
	v_bfe_u32 v8, v23, 16, 1
	v_bfe_u32 v7, v21, 16, 1
	v_add3_u32 v8, v23, v8, s95
	v_add3_u32 v7, v21, v7, s95
	v_lshrrev_b32_e32 v8, 16, v8
	v_and_or_b32 v9, v7, s96, v8
	v_bfe_u32 v8, v27, 16, 1
	v_or_b32_e32 v6, v6, v93
	v_bfe_u32 v7, v25, 16, 1
	v_add3_u32 v8, v27, v8, s95
	v_mul_u32_u24_e32 v6, 0xa00, v6
	v_add3_u32 v7, v25, v7, s95
	v_lshrrev_b32_e32 v8, 16, v8
	v_lshlrev_b32_e32 v68, 1, v6
	v_and_or_b32 v8, v7, s96, v8
	v_lshl_add_u64 v[2:3], v[2:3], 0, v[68:69]
	global_store_dwordx4 v[2:3], v[8:11], off offset:3072 nt
	s_waitcnt lgkmcnt(0)
	s_or_b64 exec, exec, s[4:5]
	s_and_b64 exec, exec, s[2:3]
	s_cbranch_execz .LBB0_95

.LBB0_36:
	v_lshlrev_b32_e32 v7, 1, v81
	v_and_b32_e32 v7, 0x7c0, v7
	v_lshlrev_b32_e32 v6, 6, v81
	v_or_b32_e32 v8, v7, v83
	v_lshl_add_u64 v[2:3], v[4:5], 2, s[44:45]
	v_and_b32_e32 v6, 0x7c0, v6
	v_lshlrev_b32_e32 v68, 13, v8
	v_lshl_add_u64 v[2:3], v[2:3], 0, v[68:69]
	v_lshlrev_b32_e32 v68, 2, v6
	v_lshl_add_u64 v[2:3], v[2:3], 0, v[68:69]
	v_mov_b32_e32 v73, v69
	v_lshl_add_u64 v[2:3], v[2:3], 0, v[72:73]
	v_add_co_u32_e32 v12, vcc, s78, v2
	v_lshlrev_b32_e32 v68, 1, v7
	s_nop 0
	v_addc_co_u32_e32 v13, vcc, 0, v3, vcc
	v_add_co_u32_e32 v16, vcc, s79, v2
	global_load_dwordx4 v[8:11], v[2:3], off nt
	s_nop 0
	global_load_dwordx4 v[12:15], v[12:13], off nt
	v_addc_co_u32_e32 v17, vcc, 0, v3, vcc
	v_add_co_u32_e32 v20, vcc, s82, v2
	v_add_u32_e32 v7, 0x400, v86
	s_nop 0
	v_addc_co_u32_e32 v21, vcc, 0, v3, vcc
	v_add_co_u32_e32 v24, vcc, s83, v2
	global_load_dwordx4 v[16:19], v[16:17], off nt
	s_nop 0
	global_load_dwordx4 v[20:23], v[20:21], off nt
	v_addc_co_u32_e32 v25, vcc, 0, v3, vcc
	v_add_co_u32_e32 v28, vcc, s84, v2
	s_nop 1
	v_addc_co_u32_e32 v29, vcc, 0, v3, vcc
	v_add_co_u32_e32 v32, vcc, s85, v2
	global_load_dwordx4 v[24:27], v[24:25], off nt
	s_nop 0
	global_load_dwordx4 v[28:31], v[28:29], off nt
	v_addc_co_u32_e32 v33, vcc, 0, v3, vcc
	v_add_co_u32_e32 v36, vcc, s86, v2
	s_nop 1
	v_addc_co_u32_e32 v37, vcc, 0, v3, vcc
	global_load_dwordx4 v[32:35], v[32:33], off nt
	s_nop 0
	global_load_dwordx4 v[36:39], v[36:37], off nt
	v_add_co_u32_e32 v40, vcc, s87, v2
	s_nop 1
	v_addc_co_u32_e32 v41, vcc, 0, v3, vcc
	v_add_co_u32_e32 v44, vcc, s88, v2
	s_nop 1
	v_addc_co_u32_e32 v45, vcc, 0, v3, vcc
	global_load_dwordx4 v[40:43], v[40:41], off nt
	s_nop 0
	global_load_dwordx4 v[44:47], v[44:45], off nt
	v_add_co_u32_e32 v48, vcc, s89, v2
	s_nop 1
	v_addc_co_u32_e32 v49, vcc, 0, v3, vcc
	v_add_co_u32_e32 v52, vcc, s90, v2
	s_nop 1
	v_addc_co_u32_e32 v53, vcc, 0, v3, vcc
	global_load_dwordx4 v[48:51], v[48:49], off nt
	s_nop 0
	global_load_dwordx4 v[52:55], v[52:53], off nt
	v_add_co_u32_e32 v56, vcc, s91, v2
	s_nop 1
	v_addc_co_u32_e32 v57, vcc, 0, v3, vcc
	v_add_co_u32_e32 v60, vcc, s92, v2
	s_nop 1
	v_addc_co_u32_e32 v61, vcc, 0, v3, vcc
	global_load_dwordx4 v[56:59], v[56:57], off nt
	s_nop 0
	global_load_dwordx4 v[60:63], v[60:61], off nt
	v_add_co_u32_e32 v64, vcc, s93, v2
	s_nop 1
	v_addc_co_u32_e32 v65, vcc, 0, v3, vcc
	global_load_dwordx4 v[76:79], v[64:65], off nt
	v_add_co_u32_e32 v2, vcc, s94, v2
	s_nop 1
	v_addc_co_u32_e32 v3, vcc, 0, v3, vcc
	global_load_dwordx4 v[116:119], v[2:3], off nt
	v_lshl_add_u64 v[2:3], v[4:5], 1, s[28:29]
	v_add_u32_e32 v4, 0x1458, v84
	v_lshl_add_u64 v[2:3], v[2:3], 0, v[68:69]
	v_lshlrev_b32_e32 v68, 1, v70
	s_waitcnt vmcnt(15)
	ds_write2_b32 v84, v8, v9 offset1:1
	ds_write2_b32 v84, v10, v11 offset0:2 offset1:3
	s_waitcnt vmcnt(14)
	ds_write2_b32 v103, v12, v13 offset1:1
	ds_write2_b32 v104, v14, v15 offset1:1
	s_waitcnt vmcnt(13)
	ds_write2_b32 v105, v16, v17 offset1:1
	ds_write2_b32 v106, v18, v19 offset1:1
	s_waitcnt vmcnt(12)
	ds_write2_b32 v107, v20, v21 offset1:1
	ds_write2_b32 v108, v22, v23 offset1:1
	s_waitcnt vmcnt(11)
	ds_write2_b32 v109, v24, v25 offset1:1
	ds_write2_b32 v110, v26, v27 offset1:1
	s_waitcnt vmcnt(10)
	ds_write2_b32 v111, v28, v29 offset1:1
	ds_write2_b32 v4, v30, v31 offset1:1
	v_add_u32_e32 v4, 0x1860, v84
	v_lshl_add_u64 v[2:3], v[2:3], 0, v[68:69]
	s_waitcnt vmcnt(9)
	ds_write2_b32 v4, v32, v33 offset1:1
	v_add_u32_e32 v4, 0x1868, v84
	ds_write2_b32 v4, v34, v35 offset1:1
	v_add_u32_e32 v4, 0x1c70, v84
	s_waitcnt vmcnt(8)
	ds_write2_b32 v4, v36, v37 offset1:1
	v_add_u32_e32 v4, 0x1c78, v84
	ds_write2_b32 v4, v38, v39 offset1:1
	v_add_u32_e32 v4, 0x2080, v84
	s_waitcnt vmcnt(7)
	ds_write2_b32 v4, v40, v41 offset1:1
	v_add_u32_e32 v4, 0x2088, v84
	ds_write2_b32 v4, v42, v43 offset1:1
	v_add_u32_e32 v4, 0x2490, v84
	s_waitcnt vmcnt(6)
	ds_write2_b32 v4, v44, v45 offset1:1
	v_add_u32_e32 v4, 0x2498, v84
	ds_write2_b32 v4, v46, v47 offset1:1
	v_add_u32_e32 v4, 0x28a0, v84
	s_waitcnt vmcnt(5)
	ds_write2_b32 v4, v48, v49 offset1:1
	v_add_u32_e32 v4, 0x28a8, v84
	ds_write2_b32 v4, v50, v51 offset1:1
	v_add_u32_e32 v4, 0x2cb0, v84
	s_waitcnt vmcnt(4)
	ds_write2_b32 v4, v52, v53 offset1:1
	v_add_u32_e32 v4, 0x2cb8, v84
	ds_write2_b32 v4, v54, v55 offset1:1
	v_add_u32_e32 v4, 0x30c0, v84
	s_waitcnt vmcnt(3)
	ds_write2_b32 v4, v56, v57 offset1:1
	v_add_u32_e32 v4, 0x30c8, v84
	ds_write2_b32 v4, v58, v59 offset1:1
	v_add_u32_e32 v4, 0x34d0, v84
	s_waitcnt vmcnt(2)
	ds_write2_b32 v4, v60, v61 offset1:1
	v_add_u32_e32 v4, 0x34d8, v84
	ds_write2_b32 v4, v62, v63 offset1:1
	v_add_u32_e32 v4, 0x38e0, v84
	s_waitcnt vmcnt(1)
	ds_write2_b32 v4, v76, v77 offset1:1
	v_add_u32_e32 v4, 0x38e8, v84
	ds_write2_b32 v4, v78, v79 offset1:1
	v_add_u32_e32 v4, 0x3cf0, v84
	s_waitcnt vmcnt(0)
	ds_write2_b32 v4, v116, v117 offset1:1
	v_add_u32_e32 v4, 0x3cf8, v84
	ds_write2_b32 v4, v118, v119 offset1:1
	s_waitcnt lgkmcnt(0)
	ds_read2_b32 v[4:5], v7 offset0:199 offset1:207
	ds_read2_b32 v[12:13], v7 offset0:134 offset1:142
	ds_read2_b32 v[16:17], v7 offset0:4 offset1:12
	ds_read2_b32 v[14:15], v7 offset0:69 offset1:77
	ds_read2_b32 v[20:21], v86 offset0:130 offset1:138
	s_waitcnt lgkmcnt(4)
	v_bfe_u32 v8, v4, 16, 1
	v_add3_u32 v4, v4, v8, s95
	s_waitcnt lgkmcnt(3)
	v_bfe_u32 v8, v12, 16, 1
	v_add3_u32 v8, v12, v8, s95
	v_lshrrev_b32_e32 v8, 16, v8
	ds_read2_b32 v[18:19], v86 offset0:195 offset1:203
	v_and_or_b32 v11, v4, s96, v8
	s_waitcnt lgkmcnt(3)
	v_bfe_u32 v8, v16, 16, 1
	s_waitcnt lgkmcnt(2)
	v_bfe_u32 v4, v14, 16, 1
	v_add3_u32 v8, v16, v8, s95
	ds_read2_b32 v[24:25], v86 offset1:8
	v_add3_u32 v4, v14, v4, s95
	v_lshrrev_b32_e32 v8, 16, v8
	ds_read2_b32 v[22:23], v86 offset0:65 offset1:73
	v_and_or_b32 v10, v4, s96, v8
	s_waitcnt lgkmcnt(3)
	v_bfe_u32 v8, v20, 16, 1
	s_waitcnt lgkmcnt(2)
	v_bfe_u32 v4, v18, 16, 1
	v_add3_u32 v8, v20, v8, s95
	v_add3_u32 v4, v18, v4, s95
	v_lshrrev_b32_e32 v8, 16, v8
	v_and_or_b32 v9, v4, s96, v8
	s_waitcnt lgkmcnt(1)
	v_bfe_u32 v8, v24, 16, 1
	s_waitcnt lgkmcnt(0)
	v_bfe_u32 v4, v22, 16, 1
	v_add3_u32 v8, v24, v8, s95
	v_add3_u32 v4, v22, v4, s95
	v_lshrrev_b32_e32 v8, 16, v8
	v_and_or_b32 v8, v4, s96, v8
	v_or_b32_e32 v4, v6, v85
	v_lshlrev_b32_e32 v68, 12, v4
	v_bfe_u32 v4, v5, 16, 1
	v_add3_u32 v4, v5, v4, s95
	v_bfe_u32 v5, v13, 16, 1
	v_add3_u32 v5, v13, v5, s95
	v_lshl_add_u64 v[26:27], v[2:3], 0, v[68:69]
	v_lshrrev_b32_e32 v5, 16, v5
	global_store_dwordx4 v[26:27], v[8:11], off nt
	v_or_b32_e32 v12, v6, v87
	v_lshlrev_b32_e32 v68, 12, v12
	v_and_or_b32 v11, v4, s96, v5
	v_bfe_u32 v5, v17, 16, 1
	v_bfe_u32 v4, v15, 16, 1
	v_add3_u32 v5, v17, v5, s95
	v_add3_u32 v4, v15, v4, s95
	v_lshrrev_b32_e32 v5, 16, v5
	v_and_or_b32 v10, v4, s96, v5
	v_bfe_u32 v5, v21, 16, 1
	v_bfe_u32 v4, v19, 16, 1
	v_add3_u32 v5, v21, v5, s95
	v_add3_u32 v4, v19, v4, s95
	v_lshrrev_b32_e32 v5, 16, v5
	v_and_or_b32 v9, v4, s96, v5
	v_bfe_u32 v5, v25, 16, 1
	v_bfe_u32 v4, v23, 16, 1
	v_add3_u32 v5, v25, v5, s95
	v_add3_u32 v4, v23, v4, s95
	v_lshrrev_b32_e32 v5, 16, v5
	v_and_or_b32 v8, v4, s96, v5
	ds_read2_b32 v[4:5], v7 offset0:215 offset1:223
	ds_read2_b32 v[12:13], v7 offset0:150 offset1:158
	v_lshl_add_u64 v[14:15], v[2:3], 0, v[68:69]
	ds_read2_b32 v[16:17], v7 offset0:20 offset1:28
	global_store_dwordx4 v[14:15], v[8:11], off nt
	ds_read2_b32 v[14:15], v7 offset0:85 offset1:93
	ds_read2_b32 v[20:21], v86 offset0:146 offset1:154
	s_waitcnt lgkmcnt(4)
	v_bfe_u32 v8, v4, 16, 1
	v_add3_u32 v4, v4, v8, s95
	s_waitcnt lgkmcnt(3)
	v_bfe_u32 v8, v12, 16, 1
	v_add3_u32 v8, v12, v8, s95
	v_lshrrev_b32_e32 v8, 16, v8
	ds_read2_b32 v[18:19], v86 offset0:211 offset1:219
	v_and_or_b32 v11, v4, s96, v8
	s_waitcnt lgkmcnt(3)
	v_bfe_u32 v8, v16, 16, 1
	s_waitcnt lgkmcnt(2)
	v_bfe_u32 v4, v14, 16, 1
	v_add3_u32 v8, v16, v8, s95
	ds_read2_b32 v[24:25], v86 offset0:16 offset1:24
	v_add3_u32 v4, v14, v4, s95
	v_lshrrev_b32_e32 v8, 16, v8
	ds_read2_b32 v[22:23], v86 offset0:81 offset1:89
	v_and_or_b32 v10, v4, s96, v8
	s_waitcnt lgkmcnt(3)
	v_bfe_u32 v8, v20, 16, 1
	s_waitcnt lgkmcnt(2)
	v_bfe_u32 v4, v18, 16, 1
	v_add3_u32 v8, v20, v8, s95
	v_add3_u32 v4, v18, v4, s95
	v_lshrrev_b32_e32 v8, 16, v8
	v_and_or_b32 v9, v4, s96, v8
	s_waitcnt lgkmcnt(1)
	v_bfe_u32 v8, v24, 16, 1
	s_waitcnt lgkmcnt(0)
	v_bfe_u32 v4, v22, 16, 1
	v_add3_u32 v8, v24, v8, s95
	v_add3_u32 v4, v22, v4, s95
	v_lshrrev_b32_e32 v8, 16, v8
	v_and_or_b32 v8, v4, s96, v8
	v_or_b32_e32 v4, v6, v88
	v_lshlrev_b32_e32 v68, 12, v4
	v_bfe_u32 v4, v5, 16, 1
	v_add3_u32 v4, v5, v4, s95
	v_bfe_u32 v5, v13, 16, 1
	v_add3_u32 v5, v13, v5, s95
	v_lshl_add_u64 v[26:27], v[2:3], 0, v[68:69]
	v_lshrrev_b32_e32 v5, 16, v5
	global_store_dwordx4 v[26:27], v[8:11], off nt
	v_or_b32_e32 v12, v6, v89
	v_lshlrev_b32_e32 v68, 12, v12
	v_and_or_b32 v11, v4, s96, v5
	v_bfe_u32 v5, v17, 16, 1
	v_bfe_u32 v4, v15, 16, 1
	v_add3_u32 v5, v17, v5, s95
	v_add3_u32 v4, v15, v4, s95
	v_lshrrev_b32_e32 v5, 16, v5
	v_and_or_b32 v10, v4, s96, v5
	v_bfe_u32 v5, v21, 16, 1
	v_bfe_u32 v4, v19, 16, 1
	v_add3_u32 v5, v21, v5, s95
	v_add3_u32 v4, v19, v4, s95
	v_lshrrev_b32_e32 v5, 16, v5
	v_and_or_b32 v9, v4, s96, v5
	v_bfe_u32 v5, v25, 16, 1
	v_bfe_u32 v4, v23, 16, 1
	v_add3_u32 v5, v25, v5, s95
	v_add3_u32 v4, v23, v4, s95
	v_lshrrev_b32_e32 v5, 16, v5
	v_and_or_b32 v8, v4, s96, v5
	ds_read2_b32 v[4:5], v7 offset0:231 offset1:239
	ds_read2_b32 v[12:13], v7 offset0:166 offset1:174
	v_lshl_add_u64 v[14:15], v[2:3], 0, v[68:69]
	ds_read2_b32 v[16:17], v7 offset0:36 offset1:44
	global_store_dwordx4 v[14:15], v[8:11], off nt
	ds_read2_b32 v[14:15], v7 offset0:101 offset1:109
	ds_read2_b32 v[20:21], v86 offset0:162 offset1:170
	s_waitcnt lgkmcnt(4)
	v_bfe_u32 v8, v4, 16, 1
	v_add3_u32 v4, v4, v8, s95
	s_waitcnt lgkmcnt(3)
	v_bfe_u32 v8, v12, 16, 1
	v_add3_u32 v8, v12, v8, s95
	v_lshrrev_b32_e32 v8, 16, v8
	ds_read2_b32 v[18:19], v86 offset0:227 offset1:235
	v_and_or_b32 v11, v4, s96, v8
	s_waitcnt lgkmcnt(3)
	v_bfe_u32 v8, v16, 16, 1
	s_waitcnt lgkmcnt(2)
	v_bfe_u32 v4, v14, 16, 1
	v_add3_u32 v8, v16, v8, s95
	ds_read2_b32 v[24:25], v86 offset0:32 offset1:40
	v_add3_u32 v4, v14, v4, s95
	v_lshrrev_b32_e32 v8, 16, v8
	ds_read2_b32 v[22:23], v86 offset0:97 offset1:105
	v_and_or_b32 v10, v4, s96, v8
	s_waitcnt lgkmcnt(3)
	v_bfe_u32 v8, v20, 16, 1
	s_waitcnt lgkmcnt(2)
	v_bfe_u32 v4, v18, 16, 1
	v_add3_u32 v8, v20, v8, s95
	v_add3_u32 v4, v18, v4, s95
	v_lshrrev_b32_e32 v8, 16, v8
	v_and_or_b32 v9, v4, s96, v8
	s_waitcnt lgkmcnt(1)
	v_bfe_u32 v8, v24, 16, 1
	s_waitcnt lgkmcnt(0)
	v_bfe_u32 v4, v22, 16, 1
	v_add3_u32 v8, v24, v8, s95
	v_add3_u32 v4, v22, v4, s95
	v_lshrrev_b32_e32 v8, 16, v8
	v_and_or_b32 v8, v4, s96, v8
	v_or_b32_e32 v4, v6, v90
	v_lshlrev_b32_e32 v68, 12, v4
	v_bfe_u32 v4, v5, 16, 1
	v_add3_u32 v4, v5, v4, s95
	v_bfe_u32 v5, v13, 16, 1
	v_add3_u32 v5, v13, v5, s95
	v_lshl_add_u64 v[26:27], v[2:3], 0, v[68:69]
	v_lshrrev_b32_e32 v5, 16, v5
	global_store_dwordx4 v[26:27], v[8:11], off nt
	v_or_b32_e32 v12, v6, v91
	v_lshlrev_b32_e32 v68, 12, v12
	v_and_or_b32 v11, v4, s96, v5
	v_bfe_u32 v5, v17, 16, 1
	v_bfe_u32 v4, v15, 16, 1
	v_add3_u32 v5, v17, v5, s95
	v_add3_u32 v4, v15, v4, s95
	v_lshrrev_b32_e32 v5, 16, v5
	v_and_or_b32 v10, v4, s96, v5
	v_bfe_u32 v5, v21, 16, 1
	v_bfe_u32 v4, v19, 16, 1
	v_add3_u32 v5, v21, v5, s95
	v_add3_u32 v4, v19, v4, s95
	v_lshrrev_b32_e32 v5, 16, v5
	v_and_or_b32 v9, v4, s96, v5
	v_bfe_u32 v5, v25, 16, 1
	v_bfe_u32 v4, v23, 16, 1
	v_add3_u32 v5, v25, v5, s95
	v_add3_u32 v4, v23, v4, s95
	v_lshrrev_b32_e32 v5, 16, v5
	v_and_or_b32 v8, v4, s96, v5
	ds_read2_b32 v[4:5], v7 offset0:247 offset1:255
	ds_read2_b32 v[12:13], v7 offset0:182 offset1:190
	v_lshl_add_u64 v[14:15], v[2:3], 0, v[68:69]
	ds_read2_b32 v[16:17], v7 offset0:52 offset1:60
	global_store_dwordx4 v[14:15], v[8:11], off nt
	ds_read2_b32 v[14:15], v7 offset0:117 offset1:125
	ds_read2_b32 v[20:21], v86 offset0:178 offset1:186
	s_waitcnt lgkmcnt(4)
	v_bfe_u32 v8, v4, 16, 1
	v_add3_u32 v4, v4, v8, s95
	s_waitcnt lgkmcnt(3)
	v_bfe_u32 v8, v12, 16, 1
	v_add3_u32 v8, v12, v8, s95
	v_lshrrev_b32_e32 v7, 16, v8
	ds_read2_b32 v[18:19], v86 offset0:243 offset1:251
	v_and_or_b32 v11, v4, s96, v7
	s_waitcnt lgkmcnt(3)
	v_bfe_u32 v7, v16, 16, 1
	s_waitcnt lgkmcnt(2)
	v_bfe_u32 v4, v14, 16, 1
	v_add3_u32 v7, v16, v7, s95
	ds_read2_b32 v[24:25], v86 offset0:48 offset1:56
	v_add3_u32 v4, v14, v4, s95
	v_lshrrev_b32_e32 v7, 16, v7
	ds_read2_b32 v[22:23], v86 offset0:113 offset1:121
	v_and_or_b32 v10, v4, s96, v7
	s_waitcnt lgkmcnt(3)
	v_bfe_u32 v7, v20, 16, 1
	s_waitcnt lgkmcnt(2)
	v_bfe_u32 v4, v18, 16, 1
	v_add3_u32 v7, v20, v7, s95
	v_add3_u32 v4, v18, v4, s95
	v_lshrrev_b32_e32 v7, 16, v7
	v_and_or_b32 v9, v4, s96, v7
	s_waitcnt lgkmcnt(1)
	v_bfe_u32 v7, v24, 16, 1
	s_waitcnt lgkmcnt(0)
	v_bfe_u32 v4, v22, 16, 1
	v_add3_u32 v7, v24, v7, s95
	v_add3_u32 v4, v22, v4, s95
	v_lshrrev_b32_e32 v7, 16, v7
	v_and_or_b32 v8, v4, s96, v7
	v_or_b32_e32 v4, v6, v92
	v_lshlrev_b32_e32 v68, 12, v4
	v_bfe_u32 v4, v5, 16, 1
	v_add3_u32 v4, v5, v4, s95
	v_bfe_u32 v5, v13, 16, 1
	v_add3_u32 v5, v13, v5, s95
	v_lshl_add_u64 v[26:27], v[2:3], 0, v[68:69]
	v_lshrrev_b32_e32 v5, 16, v5
	global_store_dwordx4 v[26:27], v[8:11], off nt
	s_nop 1
	v_and_or_b32 v11, v4, s96, v5
	v_bfe_u32 v5, v17, 16, 1
	v_bfe_u32 v4, v15, 16, 1
	v_add3_u32 v5, v17, v5, s95
	v_add3_u32 v4, v15, v4, s95
	v_lshrrev_b32_e32 v5, 16, v5
	v_and_or_b32 v10, v4, s96, v5
	v_bfe_u32 v5, v21, 16, 1
	v_bfe_u32 v4, v19, 16, 1
	v_add3_u32 v5, v21, v5, s95
	v_add3_u32 v4, v19, v4, s95
	v_lshrrev_b32_e32 v5, 16, v5
	v_and_or_b32 v9, v4, s96, v5
	v_bfe_u32 v5, v25, 16, 1
	v_bfe_u32 v4, v23, 16, 1
	v_add3_u32 v5, v25, v5, s95
	v_add3_u32 v4, v23, v4, s95
	v_lshrrev_b32_e32 v5, 16, v5
	v_and_or_b32 v8, v4, s96, v5
	v_or_b32_e32 v4, v6, v93
	v_lshlrev_b32_e32 v68, 12, v4
	v_lshl_add_u64 v[2:3], v[2:3], 0, v[68:69]
	global_store_dwordx4 v[2:3], v[8:11], off nt
	s_waitcnt lgkmcnt(0)
	s_or_b64 exec, exec, s[4:5]
	s_and_b64 exec, exec, s[2:3]
	s_cbranch_execz .LBB0_95

.LBB0_65:
	s_waitcnt vmcnt(0)
	v_pk_mul_f32 v[2:3], v[2:3], v[10:11] op_sel_hi:[1,0]
	v_add_u32_e32 v8, 0x3cf0, v84
	ds_write2_b32 v8, v2, v3 offset1:1
	v_pk_mul_f32 v[2:3], v[4:5], v[10:11] op_sel_hi:[1,0]
	v_add_u32_e32 v4, 0x3cf8, v84
	ds_write2_b32 v4, v2, v3 offset1:1
	s_waitcnt lgkmcnt(0)
	v_add_u32_e32 v26, 0x400, v86
	ds_read2_b32 v[10:11], v26 offset0:134 offset1:142
	ds_read2_b32 v[8:9], v26 offset0:199 offset1:207
	ds_read2_b32 v[14:15], v26 offset0:4 offset1:12
	ds_read2_b32 v[12:13], v26 offset0:69 offset1:77
	v_readlane_b32 s4, v254, 10
	s_waitcnt lgkmcnt(3)
	v_bfe_u32 v5, v10, 16, 1
	v_readlane_b32 s5, v254, 11
	s_waitcnt lgkmcnt(2)
	v_bfe_u32 v4, v8, 16, 1
	v_add3_u32 v5, v10, v5, s95
	ds_read2_b32 v[18:19], v86 offset0:130 offset1:138
	v_lshl_add_u64 v[6:7], v[76:77], 1, s[4:5]
	v_lshlrev_b32_e32 v68, 1, v116
	v_add3_u32 v4, v8, v4, s95
	v_lshrrev_b32_e32 v5, 16, v5
	ds_read2_b32 v[16:17], v86 offset0:195 offset1:203
	v_lshl_add_u64 v[2:3], v[6:7], 0, v[68:69]
	v_and_or_b32 v7, v4, s96, v5
	s_waitcnt lgkmcnt(3)
	v_bfe_u32 v5, v14, 16, 1
	ds_read2_b32 v[22:23], v86 offset1:8
	s_waitcnt lgkmcnt(3)
	v_bfe_u32 v4, v12, 16, 1
	v_add3_u32 v5, v14, v5, s95
	ds_read2_b32 v[20:21], v86 offset0:65 offset1:73
	v_add3_u32 v4, v12, v4, s95
	v_lshrrev_b32_e32 v5, 16, v5
	v_and_or_b32 v6, v4, s96, v5
	s_waitcnt lgkmcnt(3)
	v_bfe_u32 v5, v18, 16, 1
	s_waitcnt lgkmcnt(2)
	v_bfe_u32 v4, v16, 16, 1
	v_add3_u32 v5, v18, v5, s95
	v_add3_u32 v4, v16, v4, s95
	v_lshrrev_b32_e32 v5, 16, v5
	s_waitcnt lgkmcnt(1)
	v_bfe_u32 v8, v22, 16, 1
	v_and_or_b32 v5, v4, s96, v5
	s_waitcnt lgkmcnt(0)
	v_bfe_u32 v4, v20, 16, 1
	v_add3_u32 v8, v22, v8, s95
	v_add3_u32 v4, v20, v4, s95
	v_lshrrev_b32_e32 v8, 16, v8
	v_lshlrev_b32_e32 v68, 1, v70
	v_and_or_b32 v4, v4, s96, v8
	v_or_b32_e32 v8, v115, v85
	v_lshl_add_u64 v[2:3], v[2:3], 0, v[68:69]
	v_lshlrev_b32_e32 v68, 12, v8
	v_lshl_add_u64 v[24:25], v[2:3], 0, v[68:69]
	global_store_dwordx4 v[24:25], v[4:7], off nt
	v_bfe_u32 v8, v23, 16, 1
	v_add3_u32 v8, v23, v8, s95
	v_bfe_u32 v5, v11, 16, 1
	v_bfe_u32 v4, v9, 16, 1
	v_add3_u32 v5, v11, v5, s95
	v_add3_u32 v4, v9, v4, s95
	v_lshrrev_b32_e32 v5, 16, v5
	v_and_or_b32 v7, v4, s96, v5
	v_bfe_u32 v5, v15, 16, 1
	v_bfe_u32 v4, v13, 16, 1
	v_add3_u32 v5, v15, v5, s95
	v_add3_u32 v4, v13, v4, s95
	v_lshrrev_b32_e32 v5, 16, v5
	v_and_or_b32 v6, v4, s96, v5
	v_bfe_u32 v5, v19, 16, 1
	v_bfe_u32 v4, v17, 16, 1
	v_add3_u32 v5, v19, v5, s95
	v_add3_u32 v4, v17, v4, s95
	v_lshrrev_b32_e32 v5, 16, v5
	v_and_or_b32 v5, v4, s96, v5
	v_bfe_u32 v4, v21, 16, 1
	v_or_b32_e32 v10, v115, v87
	v_add3_u32 v4, v21, v4, s95
	v_lshrrev_b32_e32 v8, 16, v8
	v_lshlrev_b32_e32 v68, 12, v10
	ds_read2_b32 v[10:11], v26 offset0:150 offset1:158
	v_and_or_b32 v4, v4, s96, v8
	ds_read2_b32 v[8:9], v26 offset0:215 offset1:223
	v_lshl_add_u64 v[12:13], v[2:3], 0, v[68:69]
	ds_read2_b32 v[14:15], v26 offset0:20 offset1:28
	global_store_dwordx4 v[12:13], v[4:7], off nt
	ds_read2_b32 v[12:13], v26 offset0:85 offset1:93
	ds_read2_b32 v[18:19], v86 offset0:146 offset1:154
	s_waitcnt lgkmcnt(4)
	v_bfe_u32 v5, v10, 16, 1
	s_waitcnt lgkmcnt(3)
	v_bfe_u32 v4, v8, 16, 1
	v_add3_u32 v5, v10, v5, s95
	v_add3_u32 v4, v8, v4, s95
	v_lshrrev_b32_e32 v5, 16, v5
	ds_read2_b32 v[16:17], v86 offset0:211 offset1:219
	v_and_or_b32 v7, v4, s96, v5
	s_waitcnt lgkmcnt(3)
	v_bfe_u32 v5, v14, 16, 1
	ds_read2_b32 v[22:23], v86 offset0:16 offset1:24
	s_waitcnt lgkmcnt(3)
	v_bfe_u32 v4, v12, 16, 1
	v_add3_u32 v5, v14, v5, s95
	ds_read2_b32 v[20:21], v86 offset0:81 offset1:89
	v_add3_u32 v4, v12, v4, s95
	v_lshrrev_b32_e32 v5, 16, v5
	v_and_or_b32 v6, v4, s96, v5
	s_waitcnt lgkmcnt(3)
	v_bfe_u32 v5, v18, 16, 1
	s_waitcnt lgkmcnt(2)
	v_bfe_u32 v4, v16, 16, 1
	v_add3_u32 v5, v18, v5, s95
	v_add3_u32 v4, v16, v4, s95
	v_lshrrev_b32_e32 v5, 16, v5
	s_waitcnt lgkmcnt(1)
	v_bfe_u32 v8, v22, 16, 1
	v_and_or_b32 v5, v4, s96, v5
	s_waitcnt lgkmcnt(0)
	v_bfe_u32 v4, v20, 16, 1
	v_add3_u32 v8, v22, v8, s95
	v_add3_u32 v4, v20, v4, s95
	v_lshrrev_b32_e32 v8, 16, v8
	v_and_or_b32 v4, v4, s96, v8
	v_or_b32_e32 v8, v115, v88
	v_lshlrev_b32_e32 v68, 12, v8
	v_lshl_add_u64 v[24:25], v[2:3], 0, v[68:69]
	global_store_dwordx4 v[24:25], v[4:7], off nt
	v_bfe_u32 v8, v23, 16, 1
	v_add3_u32 v8, v23, v8, s95
	v_bfe_u32 v5, v11, 16, 1
	v_bfe_u32 v4, v9, 16, 1
	v_add3_u32 v5, v11, v5, s95
	v_add3_u32 v4, v9, v4, s95
	v_lshrrev_b32_e32 v5, 16, v5
	v_and_or_b32 v7, v4, s96, v5
	v_bfe_u32 v5, v15, 16, 1
	v_bfe_u32 v4, v13, 16, 1
	v_add3_u32 v5, v15, v5, s95
	v_add3_u32 v4, v13, v4, s95
	v_lshrrev_b32_e32 v5, 16, v5
	v_and_or_b32 v6, v4, s96, v5
	v_bfe_u32 v5, v19, 16, 1
	v_bfe_u32 v4, v17, 16, 1
	v_add3_u32 v5, v19, v5, s95
	v_add3_u32 v4, v17, v4, s95
	v_lshrrev_b32_e32 v5, 16, v5
	v_and_or_b32 v5, v4, s96, v5
	v_bfe_u32 v4, v21, 16, 1
	v_or_b32_e32 v10, v115, v89
	v_add3_u32 v4, v21, v4, s95
	v_lshrrev_b32_e32 v8, 16, v8
	v_lshlrev_b32_e32 v68, 12, v10
	ds_read2_b32 v[10:11], v26 offset0:166 offset1:174
	v_and_or_b32 v4, v4, s96, v8
	ds_read2_b32 v[8:9], v26 offset0:231 offset1:239
	v_lshl_add_u64 v[12:13], v[2:3], 0, v[68:69]
	ds_read2_b32 v[14:15], v26 offset0:36 offset1:44
	global_store_dwordx4 v[12:13], v[4:7], off nt
	ds_read2_b32 v[12:13], v26 offset0:101 offset1:109
	ds_read2_b32 v[18:19], v86 offset0:162 offset1:170
	s_waitcnt lgkmcnt(4)
	v_bfe_u32 v5, v10, 16, 1
	s_waitcnt lgkmcnt(3)
	v_bfe_u32 v4, v8, 16, 1
	v_add3_u32 v5, v10, v5, s95
	v_add3_u32 v4, v8, v4, s95
	v_lshrrev_b32_e32 v5, 16, v5
	ds_read2_b32 v[16:17], v86 offset0:227 offset1:235
	v_and_or_b32 v7, v4, s96, v5
	s_waitcnt lgkmcnt(3)
	v_bfe_u32 v5, v14, 16, 1
	ds_read2_b32 v[22:23], v86 offset0:32 offset1:40
	s_waitcnt lgkmcnt(3)
	v_bfe_u32 v4, v12, 16, 1
	v_add3_u32 v5, v14, v5, s95
	ds_read2_b32 v[20:21], v86 offset0:97 offset1:105
	v_add3_u32 v4, v12, v4, s95
	v_lshrrev_b32_e32 v5, 16, v5
	v_and_or_b32 v6, v4, s96, v5
	s_waitcnt lgkmcnt(3)
	v_bfe_u32 v5, v18, 16, 1
	s_waitcnt lgkmcnt(2)
	v_bfe_u32 v4, v16, 16, 1
	v_add3_u32 v5, v18, v5, s95
	v_add3_u32 v4, v16, v4, s95
	v_lshrrev_b32_e32 v5, 16, v5
	s_waitcnt lgkmcnt(1)
	v_bfe_u32 v8, v22, 16, 1
	v_and_or_b32 v5, v4, s96, v5
	s_waitcnt lgkmcnt(0)
	v_bfe_u32 v4, v20, 16, 1
	v_add3_u32 v8, v22, v8, s95
	v_add3_u32 v4, v20, v4, s95
	v_lshrrev_b32_e32 v8, 16, v8
	v_and_or_b32 v4, v4, s96, v8
	v_or_b32_e32 v8, v115, v90
	v_lshlrev_b32_e32 v68, 12, v8
	v_lshl_add_u64 v[24:25], v[2:3], 0, v[68:69]
	global_store_dwordx4 v[24:25], v[4:7], off nt
	v_bfe_u32 v8, v23, 16, 1
	v_add3_u32 v8, v23, v8, s95
	v_bfe_u32 v5, v11, 16, 1
	v_bfe_u32 v4, v9, 16, 1
	v_add3_u32 v5, v11, v5, s95
	v_add3_u32 v4, v9, v4, s95
	v_lshrrev_b32_e32 v5, 16, v5
	v_and_or_b32 v7, v4, s96, v5
	v_bfe_u32 v5, v15, 16, 1
	v_bfe_u32 v4, v13, 16, 1
	v_add3_u32 v5, v15, v5, s95
	v_add3_u32 v4, v13, v4, s95
	v_lshrrev_b32_e32 v5, 16, v5
	v_and_or_b32 v6, v4, s96, v5
	v_bfe_u32 v5, v19, 16, 1
	v_bfe_u32 v4, v17, 16, 1
	v_add3_u32 v5, v19, v5, s95
	v_add3_u32 v4, v17, v4, s95
	v_lshrrev_b32_e32 v5, 16, v5
	v_and_or_b32 v5, v4, s96, v5
	v_bfe_u32 v4, v21, 16, 1
	v_or_b32_e32 v10, v115, v91
	v_add3_u32 v4, v21, v4, s95
	v_lshrrev_b32_e32 v8, 16, v8
	v_lshlrev_b32_e32 v68, 12, v10
	ds_read2_b32 v[10:11], v26 offset0:182 offset1:190
	v_and_or_b32 v4, v4, s96, v8
	ds_read2_b32 v[8:9], v26 offset0:247 offset1:255
	v_lshl_add_u64 v[12:13], v[2:3], 0, v[68:69]
	ds_read2_b32 v[14:15], v26 offset0:52 offset1:60
	global_store_dwordx4 v[12:13], v[4:7], off nt
	ds_read2_b32 v[12:13], v26 offset0:117 offset1:125
	ds_read2_b32 v[18:19], v86 offset0:178 offset1:186
	s_waitcnt lgkmcnt(4)
	v_bfe_u32 v5, v10, 16, 1
	s_waitcnt lgkmcnt(3)
	v_bfe_u32 v4, v8, 16, 1
	v_add3_u32 v5, v10, v5, s95
	v_add3_u32 v4, v8, v4, s95
	v_lshrrev_b32_e32 v5, 16, v5
	ds_read2_b32 v[16:17], v86 offset0:243 offset1:251
	v_and_or_b32 v7, v4, s96, v5
	s_waitcnt lgkmcnt(3)
	v_bfe_u32 v5, v14, 16, 1
	ds_read2_b32 v[22:23], v86 offset0:48 offset1:56
	s_waitcnt lgkmcnt(3)
	v_bfe_u32 v4, v12, 16, 1
	v_add3_u32 v5, v14, v5, s95
	ds_read2_b32 v[20:21], v86 offset0:113 offset1:121
	v_add3_u32 v4, v12, v4, s95
	v_lshrrev_b32_e32 v5, 16, v5
	v_and_or_b32 v6, v4, s96, v5
	s_waitcnt lgkmcnt(3)
	v_bfe_u32 v5, v18, 16, 1
	s_waitcnt lgkmcnt(2)
	v_bfe_u32 v4, v16, 16, 1
	v_add3_u32 v5, v18, v5, s95
	v_add3_u32 v4, v16, v4, s95
	v_lshrrev_b32_e32 v5, 16, v5
	s_waitcnt lgkmcnt(1)
	v_bfe_u32 v8, v22, 16, 1
	v_and_or_b32 v5, v4, s96, v5
	s_waitcnt lgkmcnt(0)
	v_bfe_u32 v4, v20, 16, 1
	v_add3_u32 v8, v22, v8, s95
	v_add3_u32 v4, v20, v4, s95
	v_lshrrev_b32_e32 v8, 16, v8
	v_and_or_b32 v4, v4, s96, v8
	v_or_b32_e32 v8, v115, v92
	v_lshlrev_b32_e32 v68, 12, v8
	v_lshl_add_u64 v[24:25], v[2:3], 0, v[68:69]
	global_store_dwordx4 v[24:25], v[4:7], off nt
	v_bfe_u32 v8, v23, 16, 1
	v_add3_u32 v8, v23, v8, s95
	v_bfe_u32 v5, v11, 16, 1
	v_bfe_u32 v4, v9, 16, 1
	v_add3_u32 v5, v11, v5, s95
	v_add3_u32 v4, v9, v4, s95
	v_lshrrev_b32_e32 v5, 16, v5
	v_and_or_b32 v7, v4, s96, v5
	v_bfe_u32 v5, v15, 16, 1
	v_bfe_u32 v4, v13, 16, 1
	v_add3_u32 v5, v15, v5, s95
	v_add3_u32 v4, v13, v4, s95
	v_lshrrev_b32_e32 v5, 16, v5
	v_and_or_b32 v6, v4, s96, v5
	v_bfe_u32 v5, v19, 16, 1
	v_bfe_u32 v4, v17, 16, 1
	v_add3_u32 v5, v19, v5, s95
	v_add3_u32 v4, v17, v4, s95
	v_lshrrev_b32_e32 v5, 16, v5
	v_and_or_b32 v5, v4, s96, v5
	v_bfe_u32 v4, v21, 16, 1
	v_add3_u32 v4, v21, v4, s95
	v_lshrrev_b32_e32 v8, 16, v8
	v_and_or_b32 v4, v4, s96, v8
	v_or_b32_e32 v8, v115, v93
	v_lshlrev_b32_e32 v68, 12, v8
	v_lshl_add_u64 v[2:3], v[2:3], 0, v[68:69]
	global_store_dwordx4 v[2:3], v[4:7], off nt
	s_waitcnt lgkmcnt(0)
	s_mov_b64 s[34:35], s[30:31]
	s_or_b64 exec, exec, s[68:69]
	s_and_b64 exec, exec, s[2:3]
	s_cbranch_execz .LBB0_95

.LBB0_70:
	v_lshlrev_b32_e32 v5, 1, v81
	v_and_b32_e32 v5, 0x1fc0, v5
	v_lshlrev_b32_e32 v4, 6, v81
	v_or_b32_e32 v6, v5, v83
	v_lshl_add_u64 v[2:3], v[76:77], 2, s[50:51]
	v_and_b32_e32 v4, 0x7c0, v4
	v_lshlrev_b32_e32 v68, 13, v6
	v_lshl_add_u64 v[2:3], v[2:3], 0, v[68:69]
	v_lshlrev_b32_e32 v68, 2, v4
	v_lshl_add_u64 v[2:3], v[2:3], 0, v[68:69]
	v_mov_b32_e32 v73, v69
	v_lshl_add_u64 v[2:3], v[2:3], 0, v[72:73]
	v_add_co_u32_e32 v10, vcc, s78, v2
	v_lshlrev_b32_e32 v68, 1, v5
	s_nop 0
	v_addc_co_u32_e32 v11, vcc, 0, v3, vcc
	v_add_co_u32_e32 v14, vcc, s79, v2
	global_load_dwordx4 v[6:9], v[2:3], off nt
	s_nop 0
	global_load_dwordx4 v[10:13], v[10:11], off nt
	v_addc_co_u32_e32 v15, vcc, 0, v3, vcc
	v_add_co_u32_e32 v18, vcc, s82, v2
	v_add_u32_e32 v5, 0x400, v86
	s_nop 0
	v_addc_co_u32_e32 v19, vcc, 0, v3, vcc
	v_add_co_u32_e32 v22, vcc, s83, v2
	global_load_dwordx4 v[14:17], v[14:15], off nt
	s_nop 0
	global_load_dwordx4 v[18:21], v[18:19], off nt
	v_addc_co_u32_e32 v23, vcc, 0, v3, vcc
	v_add_co_u32_e32 v26, vcc, s84, v2
	s_nop 1
	v_addc_co_u32_e32 v27, vcc, 0, v3, vcc
	v_add_co_u32_e32 v30, vcc, s85, v2
	global_load_dwordx4 v[22:25], v[22:23], off nt
	s_nop 0
	global_load_dwordx4 v[26:29], v[26:27], off nt
	v_addc_co_u32_e32 v31, vcc, 0, v3, vcc
	v_add_co_u32_e32 v34, vcc, s86, v2
	s_nop 1
	v_addc_co_u32_e32 v35, vcc, 0, v3, vcc
	global_load_dwordx4 v[30:33], v[30:31], off nt
	s_nop 0
	global_load_dwordx4 v[34:37], v[34:35], off nt
	v_add_co_u32_e32 v38, vcc, s87, v2
	s_nop 1
	v_addc_co_u32_e32 v39, vcc, 0, v3, vcc
	v_add_co_u32_e32 v42, vcc, s88, v2
	s_nop 1
	v_addc_co_u32_e32 v43, vcc, 0, v3, vcc
	global_load_dwordx4 v[38:41], v[38:39], off nt
	s_nop 0
	global_load_dwordx4 v[42:45], v[42:43], off nt
	v_add_co_u32_e32 v46, vcc, s89, v2
	s_nop 1
	v_addc_co_u32_e32 v47, vcc, 0, v3, vcc
	v_add_co_u32_e32 v50, vcc, s90, v2
	s_nop 1
	v_addc_co_u32_e32 v51, vcc, 0, v3, vcc
	global_load_dwordx4 v[46:49], v[46:47], off nt
	s_nop 0
	global_load_dwordx4 v[50:53], v[50:51], off nt
	v_add_co_u32_e32 v54, vcc, s91, v2
	s_nop 1
	v_addc_co_u32_e32 v55, vcc, 0, v3, vcc
	v_add_co_u32_e32 v58, vcc, s92, v2
	s_nop 1
	v_addc_co_u32_e32 v59, vcc, 0, v3, vcc
	global_load_dwordx4 v[54:57], v[54:55], off nt
	s_nop 0
	global_load_dwordx4 v[58:61], v[58:59], off nt
	v_add_co_u32_e32 v62, vcc, s93, v2
	s_nop 1
	v_addc_co_u32_e32 v63, vcc, 0, v3, vcc
	global_load_dwordx4 v[62:65], v[62:63], off nt
	v_add_co_u32_e32 v2, vcc, s94, v2
	s_nop 1
	v_addc_co_u32_e32 v3, vcc, 0, v3, vcc
	global_load_dwordx4 v[116:119], v[2:3], off nt
	v_lshl_add_u64 v[2:3], v[76:77], 1, s[34:35]
	v_lshl_add_u64 v[2:3], v[2:3], 0, v[68:69]
	v_lshlrev_b32_e32 v68, 1, v70
	v_lshl_add_u64 v[2:3], v[2:3], 0, v[68:69]
	s_waitcnt vmcnt(15)
	ds_write2_b32 v84, v6, v7 offset1:1
	ds_write2_b32 v84, v8, v9 offset0:2 offset1:3
	s_waitcnt vmcnt(14)
	ds_write2_b32 v103, v10, v11 offset1:1
	ds_write2_b32 v104, v12, v13 offset1:1
	s_waitcnt vmcnt(13)
	ds_write2_b32 v105, v14, v15 offset1:1
	ds_write2_b32 v106, v16, v17 offset1:1
	s_waitcnt vmcnt(12)
	ds_write2_b32 v107, v18, v19 offset1:1
	ds_write2_b32 v108, v20, v21 offset1:1
	s_waitcnt vmcnt(11)
	ds_write2_b32 v109, v22, v23 offset1:1
	ds_write2_b32 v110, v24, v25 offset1:1
	s_waitcnt vmcnt(10)
	ds_write2_b32 v111, v26, v27 offset1:1
	v_add_u32_e32 v6, 0x1458, v84
	ds_write2_b32 v6, v28, v29 offset1:1
	v_add_u32_e32 v6, 0x1860, v84
	s_waitcnt vmcnt(9)
	ds_write2_b32 v6, v30, v31 offset1:1
	v_add_u32_e32 v6, 0x1868, v84
	ds_write2_b32 v6, v32, v33 offset1:1
	v_add_u32_e32 v6, 0x1c70, v84
	s_waitcnt vmcnt(8)
	ds_write2_b32 v6, v34, v35 offset1:1
	v_add_u32_e32 v6, 0x1c78, v84
	ds_write2_b32 v6, v36, v37 offset1:1
	v_add_u32_e32 v6, 0x2080, v84
	s_waitcnt vmcnt(7)
	ds_write2_b32 v6, v38, v39 offset1:1
	v_add_u32_e32 v6, 0x2088, v84
	ds_write2_b32 v6, v40, v41 offset1:1
	v_add_u32_e32 v6, 0x2490, v84
	s_waitcnt vmcnt(6)
	ds_write2_b32 v6, v42, v43 offset1:1
	v_add_u32_e32 v6, 0x2498, v84
	ds_write2_b32 v6, v44, v45 offset1:1
	v_add_u32_e32 v6, 0x28a0, v84
	s_waitcnt vmcnt(5)
	ds_write2_b32 v6, v46, v47 offset1:1
	v_add_u32_e32 v6, 0x28a8, v84
	ds_write2_b32 v6, v48, v49 offset1:1
	v_add_u32_e32 v6, 0x2cb0, v84
	s_waitcnt vmcnt(4)
	ds_write2_b32 v6, v50, v51 offset1:1
	v_add_u32_e32 v6, 0x2cb8, v84
	ds_write2_b32 v6, v52, v53 offset1:1
	v_add_u32_e32 v6, 0x30c0, v84
	s_waitcnt vmcnt(3)
	ds_write2_b32 v6, v54, v55 offset1:1
	v_add_u32_e32 v6, 0x30c8, v84
	ds_write2_b32 v6, v56, v57 offset1:1
	v_add_u32_e32 v6, 0x34d0, v84
	s_waitcnt vmcnt(2)
	ds_write2_b32 v6, v58, v59 offset1:1
	v_add_u32_e32 v6, 0x34d8, v84
	ds_write2_b32 v6, v60, v61 offset1:1
	v_add_u32_e32 v6, 0x38e0, v84
	s_waitcnt vmcnt(1)
	ds_write2_b32 v6, v62, v63 offset1:1
	v_add_u32_e32 v6, 0x38e8, v84
	ds_write2_b32 v6, v64, v65 offset1:1
	v_add_u32_e32 v6, 0x3cf0, v84
	s_waitcnt vmcnt(0)
	ds_write2_b32 v6, v116, v117 offset1:1
	v_add_u32_e32 v6, 0x3cf8, v84
	ds_write2_b32 v6, v118, v119 offset1:1
	s_waitcnt lgkmcnt(0)
	ds_read2_b32 v[12:13], v5 offset0:134 offset1:142
	ds_read2_b32 v[10:11], v5 offset0:199 offset1:207
	ds_read2_b32 v[16:17], v5 offset0:4 offset1:12
	ds_read2_b32 v[14:15], v5 offset0:69 offset1:77
	ds_read2_b32 v[20:21], v86 offset0:130 offset1:138
	s_waitcnt lgkmcnt(4)
	v_bfe_u32 v7, v12, 16, 1
	s_waitcnt lgkmcnt(3)
	v_bfe_u32 v6, v10, 16, 1
	v_add3_u32 v7, v12, v7, s95
	v_add3_u32 v6, v10, v6, s95
	v_lshrrev_b32_e32 v7, 16, v7
	ds_read2_b32 v[18:19], v86 offset0:195 offset1:203
	v_and_or_b32 v9, v6, s96, v7
	s_waitcnt lgkmcnt(3)
	v_bfe_u32 v7, v16, 16, 1
	ds_read2_b32 v[24:25], v86 offset1:8
	s_waitcnt lgkmcnt(3)
	v_bfe_u32 v6, v14, 16, 1
	v_add3_u32 v7, v16, v7, s95
	ds_read2_b32 v[22:23], v86 offset0:65 offset1:73
	v_add3_u32 v6, v14, v6, s95
	v_lshrrev_b32_e32 v7, 16, v7
	v_and_or_b32 v8, v6, s96, v7
	s_waitcnt lgkmcnt(3)
	v_bfe_u32 v7, v20, 16, 1
	s_waitcnt lgkmcnt(2)
	v_bfe_u32 v6, v18, 16, 1
	v_add3_u32 v7, v20, v7, s95
	v_add3_u32 v6, v18, v6, s95
	v_lshrrev_b32_e32 v7, 16, v7
	s_waitcnt lgkmcnt(1)
	v_bfe_u32 v10, v24, 16, 1
	v_and_or_b32 v7, v6, s96, v7
	s_waitcnt lgkmcnt(0)
	v_bfe_u32 v6, v22, 16, 1
	v_add3_u32 v10, v24, v10, s95
	v_add3_u32 v6, v22, v6, s95
	v_lshrrev_b32_e32 v10, 16, v10
	v_and_or_b32 v6, v6, s96, v10
	v_or_b32_e32 v10, v4, v85
	v_lshlrev_b32_e32 v68, 14, v10
	v_lshl_add_u64 v[26:27], v[2:3], 0, v[68:69]
	global_store_dwordx4 v[26:27], v[6:9], off nt
	v_bfe_u32 v10, v25, 16, 1
	v_add3_u32 v10, v25, v10, s95
	v_bfe_u32 v7, v13, 16, 1
	v_bfe_u32 v6, v11, 16, 1
	v_add3_u32 v7, v13, v7, s95
	v_add3_u32 v6, v11, v6, s95
	v_lshrrev_b32_e32 v7, 16, v7
	v_and_or_b32 v9, v6, s96, v7
	v_bfe_u32 v7, v17, 16, 1
	v_bfe_u32 v6, v15, 16, 1
	v_add3_u32 v7, v17, v7, s95
	v_add3_u32 v6, v15, v6, s95
	v_lshrrev_b32_e32 v7, 16, v7
	v_and_or_b32 v8, v6, s96, v7
	v_bfe_u32 v7, v21, 16, 1
	v_bfe_u32 v6, v19, 16, 1
	v_add3_u32 v7, v21, v7, s95
	v_add3_u32 v6, v19, v6, s95
	v_lshrrev_b32_e32 v7, 16, v7
	v_and_or_b32 v7, v6, s96, v7
	v_bfe_u32 v6, v23, 16, 1
	v_or_b32_e32 v12, v4, v87
	v_add3_u32 v6, v23, v6, s95
	v_lshrrev_b32_e32 v10, 16, v10
	v_lshlrev_b32_e32 v68, 14, v12
	ds_read2_b32 v[12:13], v5 offset0:150 offset1:158
	v_and_or_b32 v6, v6, s96, v10
	ds_read2_b32 v[10:11], v5 offset0:215 offset1:223
	v_lshl_add_u64 v[14:15], v[2:3], 0, v[68:69]
	ds_read2_b32 v[16:17], v5 offset0:20 offset1:28
	global_store_dwordx4 v[14:15], v[6:9], off nt
	ds_read2_b32 v[14:15], v5 offset0:85 offset1:93
	ds_read2_b32 v[20:21], v86 offset0:146 offset1:154
	s_waitcnt lgkmcnt(4)
	v_bfe_u32 v7, v12, 16, 1
	s_waitcnt lgkmcnt(3)
	v_bfe_u32 v6, v10, 16, 1
	v_add3_u32 v7, v12, v7, s95
	v_add3_u32 v6, v10, v6, s95
	v_lshrrev_b32_e32 v7, 16, v7
	ds_read2_b32 v[18:19], v86 offset0:211 offset1:219
	v_and_or_b32 v9, v6, s96, v7
	s_waitcnt lgkmcnt(3)
	v_bfe_u32 v7, v16, 16, 1
	ds_read2_b32 v[24:25], v86 offset0:16 offset1:24
	s_waitcnt lgkmcnt(3)
	v_bfe_u32 v6, v14, 16, 1
	v_add3_u32 v7, v16, v7, s95
	ds_read2_b32 v[22:23], v86 offset0:81 offset1:89
	v_add3_u32 v6, v14, v6, s95
	v_lshrrev_b32_e32 v7, 16, v7
	v_and_or_b32 v8, v6, s96, v7
	s_waitcnt lgkmcnt(3)
	v_bfe_u32 v7, v20, 16, 1
	s_waitcnt lgkmcnt(2)
	v_bfe_u32 v6, v18, 16, 1
	v_add3_u32 v7, v20, v7, s95
	v_add3_u32 v6, v18, v6, s95
	v_lshrrev_b32_e32 v7, 16, v7
	s_waitcnt lgkmcnt(1)
	v_bfe_u32 v10, v24, 16, 1
	v_and_or_b32 v7, v6, s96, v7
	s_waitcnt lgkmcnt(0)
	v_bfe_u32 v6, v22, 16, 1
	v_add3_u32 v10, v24, v10, s95
	v_add3_u32 v6, v22, v6, s95
	v_lshrrev_b32_e32 v10, 16, v10
	v_and_or_b32 v6, v6, s96, v10
	v_or_b32_e32 v10, v4, v88
	v_lshlrev_b32_e32 v68, 14, v10
	v_lshl_add_u64 v[26:27], v[2:3], 0, v[68:69]
	global_store_dwordx4 v[26:27], v[6:9], off nt
	v_bfe_u32 v10, v25, 16, 1
	v_add3_u32 v10, v25, v10, s95
	v_bfe_u32 v7, v13, 16, 1
	v_bfe_u32 v6, v11, 16, 1
	v_add3_u32 v7, v13, v7, s95
	v_add3_u32 v6, v11, v6, s95
	v_lshrrev_b32_e32 v7, 16, v7
	v_and_or_b32 v9, v6, s96, v7
	v_bfe_u32 v7, v17, 16, 1
	v_bfe_u32 v6, v15, 16, 1
	v_add3_u32 v7, v17, v7, s95
	v_add3_u32 v6, v15, v6, s95
	v_lshrrev_b32_e32 v7, 16, v7
	v_and_or_b32 v8, v6, s96, v7
	v_bfe_u32 v7, v21, 16, 1
	v_bfe_u32 v6, v19, 16, 1
	v_add3_u32 v7, v21, v7, s95
	v_add3_u32 v6, v19, v6, s95
	v_lshrrev_b32_e32 v7, 16, v7
	v_and_or_b32 v7, v6, s96, v7
	v_bfe_u32 v6, v23, 16, 1
	v_or_b32_e32 v12, v4, v89
	v_add3_u32 v6, v23, v6, s95
	v_lshrrev_b32_e32 v10, 16, v10
	v_lshlrev_b32_e32 v68, 14, v12
	ds_read2_b32 v[12:13], v5 offset0:166 offset1:174
	v_and_or_b32 v6, v6, s96, v10
	ds_read2_b32 v[10:11], v5 offset0:231 offset1:239
	v_lshl_add_u64 v[14:15], v[2:3], 0, v[68:69]
	ds_read2_b32 v[16:17], v5 offset0:36 offset1:44
	global_store_dwordx4 v[14:15], v[6:9], off nt
	ds_read2_b32 v[14:15], v5 offset0:101 offset1:109
	ds_read2_b32 v[20:21], v86 offset0:162 offset1:170
	s_waitcnt lgkmcnt(4)
	v_bfe_u32 v7, v12, 16, 1
	s_waitcnt lgkmcnt(3)
	v_bfe_u32 v6, v10, 16, 1
	v_add3_u32 v7, v12, v7, s95
	v_add3_u32 v6, v10, v6, s95
	v_lshrrev_b32_e32 v7, 16, v7
	ds_read2_b32 v[18:19], v86 offset0:227 offset1:235
	v_and_or_b32 v9, v6, s96, v7
	s_waitcnt lgkmcnt(3)
	v_bfe_u32 v7, v16, 16, 1
	ds_read2_b32 v[24:25], v86 offset0:32 offset1:40
	s_waitcnt lgkmcnt(3)
	v_bfe_u32 v6, v14, 16, 1
	v_add3_u32 v7, v16, v7, s95
	ds_read2_b32 v[22:23], v86 offset0:97 offset1:105
	v_add3_u32 v6, v14, v6, s95
	v_lshrrev_b32_e32 v7, 16, v7
	v_and_or_b32 v8, v6, s96, v7
	s_waitcnt lgkmcnt(3)
	v_bfe_u32 v7, v20, 16, 1
	s_waitcnt lgkmcnt(2)
	v_bfe_u32 v6, v18, 16, 1
	v_add3_u32 v7, v20, v7, s95
	v_add3_u32 v6, v18, v6, s95
	v_lshrrev_b32_e32 v7, 16, v7
	s_waitcnt lgkmcnt(1)
	v_bfe_u32 v10, v24, 16, 1
	v_and_or_b32 v7, v6, s96, v7
	s_waitcnt lgkmcnt(0)
	v_bfe_u32 v6, v22, 16, 1
	v_add3_u32 v10, v24, v10, s95
	v_add3_u32 v6, v22, v6, s95
	v_lshrrev_b32_e32 v10, 16, v10
	v_and_or_b32 v6, v6, s96, v10
	v_or_b32_e32 v10, v4, v90
	v_lshlrev_b32_e32 v68, 14, v10
	v_lshl_add_u64 v[26:27], v[2:3], 0, v[68:69]
	global_store_dwordx4 v[26:27], v[6:9], off nt
	v_bfe_u32 v10, v25, 16, 1
	v_add3_u32 v10, v25, v10, s95
	v_bfe_u32 v7, v13, 16, 1
	v_bfe_u32 v6, v11, 16, 1
	v_add3_u32 v7, v13, v7, s95
	v_add3_u32 v6, v11, v6, s95
	v_lshrrev_b32_e32 v7, 16, v7
	v_and_or_b32 v9, v6, s96, v7
	v_bfe_u32 v7, v17, 16, 1
	v_bfe_u32 v6, v15, 16, 1
	v_add3_u32 v7, v17, v7, s95
	v_add3_u32 v6, v15, v6, s95
	v_lshrrev_b32_e32 v7, 16, v7
	v_and_or_b32 v8, v6, s96, v7
	v_bfe_u32 v7, v21, 16, 1
	v_bfe_u32 v6, v19, 16, 1
	v_add3_u32 v7, v21, v7, s95
	v_add3_u32 v6, v19, v6, s95
	v_lshrrev_b32_e32 v7, 16, v7
	v_and_or_b32 v7, v6, s96, v7
	v_bfe_u32 v6, v23, 16, 1
	v_or_b32_e32 v12, v4, v91
	v_add3_u32 v6, v23, v6, s95
	v_lshrrev_b32_e32 v10, 16, v10
	v_lshlrev_b32_e32 v68, 14, v12
	ds_read2_b32 v[12:13], v5 offset0:182 offset1:190
	v_and_or_b32 v6, v6, s96, v10
	ds_read2_b32 v[10:11], v5 offset0:247 offset1:255
	v_lshl_add_u64 v[14:15], v[2:3], 0, v[68:69]
	ds_read2_b32 v[16:17], v5 offset0:52 offset1:60
	global_store_dwordx4 v[14:15], v[6:9], off nt
	ds_read2_b32 v[14:15], v5 offset0:117 offset1:125
	ds_read2_b32 v[20:21], v86 offset0:178 offset1:186
	s_waitcnt lgkmcnt(4)
	v_bfe_u32 v7, v12, 16, 1
	s_waitcnt lgkmcnt(3)
	v_bfe_u32 v6, v10, 16, 1
	v_add3_u32 v7, v12, v7, s95
	v_add3_u32 v6, v10, v6, s95
	v_lshrrev_b32_e32 v5, 16, v7
	ds_read2_b32 v[18:19], v86 offset0:243 offset1:251
	v_and_or_b32 v9, v6, s96, v5
	s_waitcnt lgkmcnt(3)
	v_bfe_u32 v6, v16, 16, 1
	s_waitcnt lgkmcnt(2)
	v_bfe_u32 v5, v14, 16, 1
	v_add3_u32 v6, v16, v6, s95
	ds_read2_b32 v[24:25], v86 offset0:48 offset1:56
	v_add3_u32 v5, v14, v5, s95
	v_lshrrev_b32_e32 v6, 16, v6
	ds_read2_b32 v[22:23], v86 offset0:113 offset1:121
	v_and_or_b32 v8, v5, s96, v6
	s_waitcnt lgkmcnt(3)
	v_bfe_u32 v6, v20, 16, 1
	s_waitcnt lgkmcnt(2)
	v_bfe_u32 v5, v18, 16, 1
	v_add3_u32 v6, v20, v6, s95
	v_add3_u32 v5, v18, v5, s95
	v_lshrrev_b32_e32 v6, 16, v6
	v_and_or_b32 v7, v5, s96, v6
	s_waitcnt lgkmcnt(1)
	v_bfe_u32 v6, v24, 16, 1
	s_waitcnt lgkmcnt(0)
	v_bfe_u32 v5, v22, 16, 1
	v_add3_u32 v6, v24, v6, s95
	v_add3_u32 v5, v22, v5, s95
	v_lshrrev_b32_e32 v6, 16, v6
	v_and_or_b32 v6, v5, s96, v6
	v_or_b32_e32 v5, v4, v92
	v_lshlrev_b32_e32 v68, 14, v5
	v_lshl_add_u64 v[26:27], v[2:3], 0, v[68:69]
	global_store_dwordx4 v[26:27], v[6:9], off nt
	v_bfe_u32 v5, v11, 16, 1
	v_add3_u32 v5, v11, v5, s95
	v_bfe_u32 v6, v13, 16, 1
	v_add3_u32 v6, v13, v6, s95
	v_lshrrev_b32_e32 v6, 16, v6
	v_and_or_b32 v9, v5, s96, v6
	v_bfe_u32 v6, v17, 16, 1
	v_bfe_u32 v5, v15, 16, 1
	v_add3_u32 v6, v17, v6, s95
	v_add3_u32 v5, v15, v5, s95
	v_lshrrev_b32_e32 v6, 16, v6
	v_and_or_b32 v8, v5, s96, v6
	v_bfe_u32 v6, v21, 16, 1
	v_bfe_u32 v5, v19, 16, 1
	v_add3_u32 v6, v21, v6, s95
	v_add3_u32 v5, v19, v5, s95
	v_lshrrev_b32_e32 v6, 16, v6
	v_and_or_b32 v7, v5, s96, v6
	v_bfe_u32 v6, v25, 16, 1
	v_bfe_u32 v5, v23, 16, 1
	v_add3_u32 v6, v25, v6, s95
	v_or_b32_e32 v4, v4, v93
	v_add3_u32 v5, v23, v5, s95
	v_lshrrev_b32_e32 v6, 16, v6
	v_lshlrev_b32_e32 v68, 14, v4
	v_and_or_b32 v6, v5, s96, v6
	v_lshl_add_u64 v[2:3], v[2:3], 0, v[68:69]
	global_store_dwordx4 v[2:3], v[6:9], off nt
	s_waitcnt lgkmcnt(0)
	s_or_b64 exec, exec, s[4:5]
	s_and_b64 exec, exec, s[2:3]
	s_cbranch_execz .LBB0_95
.LBB0_71:
	v_cmp_lt_u32_e64 s[2:3], s58, v81
	s_and_saveexec_b64 s[4:5], s[2:3]
	s_xor_b64 s[4:5], exec, s[4:5]
	v_add_u32_e32 v81, 0xffffff00, v81
	s_or_saveexec_b64 s[4:5], s[4:5]
	v_lshlrev_b32_e32 v4, 1, v74
	v_lshlrev_b64 v[2:3], 20, v[74:75]
	v_ashrrev_i32_e32 v5, 31, v4
	s_xor_b64 exec, exec, s[4:5]
	s_cbranch_execz .LBB0_75
	v_lshrrev_b32_e32 v80, 2, v81
	v_lshl_add_u64 v[6:7], v[2:3], 2, s[20:21]
	v_lshl_or_b32 v68, v80, 16, v94
	v_lshlrev_b32_e32 v8, 8, v81
	v_lshl_add_u64 v[6:7], v[6:7], 0, v[68:69]
	v_and_b32_e32 v68, 0x300, v8
	v_lshl_add_u64 v[6:7], v[6:7], 0, v[68:69]
	v_mov_b32_e32 v73, v69
	v_lshl_add_u64 v[76:77], v[6:7], 0, v[72:73]
	s_movk_i32 s30, 0x2000
	v_add_co_u32_e32 v14, vcc, s30, v76
	s_movk_i32 s30, 0x4000
	s_nop 0
	v_addc_co_u32_e32 v15, vcc, 0, v77, vcc
	v_add_co_u32_e32 v30, vcc, s30, v76
	s_movk_i32 s30, 0x6000
	s_nop 0
	v_addc_co_u32_e32 v31, vcc, 0, v77, vcc
	v_add_co_u32_e32 v22, vcc, s78, v76
	global_load_dwordx4 v[6:9], v[76:77], off nt
	s_nop 0
	v_addc_co_u32_e32 v23, vcc, 0, v77, vcc
	v_add_co_u32_e32 v38, vcc, s30, v76
	s_mov_b32 s30, 0xa000
	s_nop 0
	v_addc_co_u32_e32 v39, vcc, 0, v77, vcc
	v_add_co_u32_e32 v46, vcc, s30, v76
	global_load_dwordx4 v[10:13], v[14:15], off offset:-4096 nt
	s_nop 0
	global_load_dwordx4 v[14:17], v[14:15], off nt
	s_nop 0
	global_load_dwordx4 v[18:21], v[22:23], off offset:-4096 nt
	s_nop 0
	global_load_dwordx4 v[22:25], v[22:23], off nt
	s_nop 0
	global_load_dwordx4 v[26:29], v[30:31], off offset:-4096 nt
	s_nop 0
	global_load_dwordx4 v[30:33], v[30:31], off nt
	s_nop 0
	global_load_dwordx4 v[34:37], v[38:39], off offset:-4096 nt
	s_nop 0
	global_load_dwordx4 v[38:41], v[38:39], off nt
	v_addc_co_u32_e32 v47, vcc, 0, v77, vcc
	global_load_dwordx4 v[42:45], v[46:47], off offset:-4096 nt
	s_nop 0
	global_load_dwordx4 v[46:49], v[46:47], off nt
	s_mov_b32 s30, 0xc000
	v_add_co_u32_e32 v54, vcc, s30, v76
	s_mov_b32 s30, 0xe000
	s_nop 0
	v_addc_co_u32_e32 v55, vcc, 0, v77, vcc
	global_load_dwordx4 v[50:53], v[54:55], off offset:-4096 nt
	s_nop 0
	global_load_dwordx4 v[54:57], v[54:55], off nt
	v_add_co_u32_e32 v62, vcc, s30, v76
	s_mov_b32 s30, 0xf000
	s_nop 0
	v_addc_co_u32_e32 v63, vcc, 0, v77, vcc
	global_load_dwordx4 v[58:61], v[62:63], off offset:-4096 nt
	s_nop 0
	global_load_dwordx4 v[62:65], v[62:63], off nt
	v_add_co_u32_e32 v76, vcc, s30, v76
	v_add_u32_e32 v73, 0x1458, v84
	s_nop 0
	v_addc_co_u32_e32 v77, vcc, 0, v77, vcc
	global_load_dwordx4 v[76:79], v[76:77], off nt
	v_add_u32_e32 v115, 0x1860, v84
	v_add_u32_e32 v116, 0x1868, v84
	v_add_u32_e32 v117, 0x1c70, v84
	v_add_u32_e32 v118, 0x1c78, v84
	v_add_u32_e32 v119, 0x2080, v84
	v_add_u32_e32 v120, 0x2088, v84
	v_add_u32_e32 v121, 0x2490, v84
	s_waitcnt vmcnt(15)
	ds_write2_b32 v84, v6, v7 offset1:1
	ds_write2_b32 v84, v8, v9 offset0:2 offset1:3
	s_waitcnt vmcnt(12)
	ds_write2_b32 v117, v18, v19 offset1:1
	ds_write2_b32 v118, v20, v21 offset1:1
	s_waitcnt vmcnt(11)
	ds_write2_b32 v119, v22, v23 offset1:1
	ds_write2_b32 v120, v24, v25 offset1:1
	ds_write2_b32 v103, v10, v11 offset1:1
	ds_write2_b32 v104, v12, v13 offset1:1
	ds_write2_b32 v105, v14, v15 offset1:1
	ds_write2_b32 v106, v16, v17 offset1:1
	s_waitcnt vmcnt(10)
	ds_write2_b32 v107, v26, v27 offset1:1
	ds_write2_b32 v108, v28, v29 offset1:1
	s_waitcnt vmcnt(9)
	ds_write2_b32 v109, v30, v31 offset1:1
	ds_write2_b32 v110, v32, v33 offset1:1
	s_waitcnt vmcnt(8)
	ds_write2_b32 v111, v34, v35 offset1:1
	ds_write2_b32 v73, v36, v37 offset1:1
	s_waitcnt vmcnt(7)
	ds_write2_b32 v115, v38, v39 offset1:1
	ds_write2_b32 v116, v40, v41 offset1:1
	s_waitcnt vmcnt(6)
	ds_write2_b32 v121, v42, v43 offset1:1
	v_add_u32_e32 v6, 0x2498, v84
	ds_write2_b32 v6, v44, v45 offset1:1
	v_add_u32_e32 v6, 0x28a0, v84
	s_waitcnt vmcnt(5)
	ds_write2_b32 v6, v46, v47 offset1:1
	v_add_u32_e32 v6, 0x28a8, v84
	ds_write2_b32 v6, v48, v49 offset1:1
	v_add_u32_e32 v6, 0x2cb0, v84
	s_waitcnt vmcnt(4)
	ds_write2_b32 v6, v50, v51 offset1:1
	v_add_u32_e32 v6, 0x2cb8, v84
	ds_write2_b32 v6, v52, v53 offset1:1
	v_add_u32_e32 v6, 0x30c0, v84
	s_waitcnt vmcnt(3)
	ds_write2_b32 v6, v54, v55 offset1:1
	v_add_u32_e32 v6, 0x30c8, v84
	ds_write2_b32 v6, v56, v57 offset1:1
	v_add_u32_e32 v6, 0x34d0, v84
	s_waitcnt vmcnt(2)
	ds_write2_b32 v6, v58, v59 offset1:1
	v_add_u32_e32 v6, 0x34d8, v84
	ds_write2_b32 v6, v60, v61 offset1:1
	v_add_u32_e32 v6, 0x38e0, v84
	s_waitcnt vmcnt(1)
	ds_write2_b32 v6, v62, v63 offset1:1
	v_add_u32_e32 v6, 0x38e8, v84
	ds_write2_b32 v6, v64, v65 offset1:1
	v_add_u32_e32 v6, 0x3cf0, v84
	s_waitcnt vmcnt(0)
	ds_write2_b32 v6, v76, v77 offset1:1
	v_add_u32_e32 v6, 0x3cf8, v84
	ds_write2_b32 v6, v78, v79 offset1:1
	s_waitcnt lgkmcnt(0)
	ds_read2_b32 v[12:13], v86 offset1:8
	ds_read2_b32 v[14:15], v86 offset0:65 offset1:73
	ds_read2_b32 v[16:17], v86 offset0:130 offset1:138
	ds_read2_b32 v[18:19], v86 offset0:195 offset1:203
	v_add_u32_e32 v30, 0x400, v86
	s_waitcnt lgkmcnt(3)
	v_bfe_u32 v8, v12, 16, 1
	v_add3_u32 v8, v12, v8, s95
	s_waitcnt lgkmcnt(2)
	v_bfe_u32 v9, v14, 16, 1
	ds_read2_b32 v[20:21], v30 offset0:4 offset1:12
	v_lshrrev_b32_e32 v8, 16, v8
	v_add3_u32 v9, v14, v9, s95
	ds_read2_b32 v[22:23], v30 offset0:69 offset1:77
	v_and_or_b32 v8, v9, s96, v8
	s_waitcnt lgkmcnt(3)
	v_bfe_u32 v9, v16, 16, 1
	v_add3_u32 v9, v16, v9, s95
	s_waitcnt lgkmcnt(2)
	v_bfe_u32 v10, v18, 16, 1
	ds_read2_b32 v[24:25], v30 offset0:134 offset1:142
	v_lshrrev_b32_e32 v9, 16, v9
	v_add3_u32 v10, v18, v10, s95
	ds_read2_b32 v[26:27], v30 offset0:199 offset1:207
	v_and_or_b32 v9, v10, s96, v9
	s_waitcnt lgkmcnt(3)
	v_bfe_u32 v10, v20, 16, 1
	v_add3_u32 v10, v20, v10, s95
	s_waitcnt lgkmcnt(2)
	v_bfe_u32 v11, v22, 16, 1
	v_lshrrev_b32_e32 v10, 16, v10
	v_add3_u32 v11, v22, v11, s95
	v_and_or_b32 v10, v11, s96, v10
	s_waitcnt lgkmcnt(1)
	v_bfe_u32 v11, v24, 16, 1
	v_add3_u32 v11, v24, v11, s95
	s_waitcnt lgkmcnt(0)
	v_bfe_u32 v12, v26, 16, 1
	v_lshrrev_b32_e32 v11, 16, v11
	v_add3_u32 v12, v26, v12, s95
	v_and_or_b32 v11, v12, s96, v11
	v_lshlrev_b32_e32 v12, 11, v80
	v_or3_b32 v31, v12, v68, v100
	v_lshlrev_b64 v[6:7], 21, v[4:5]
	v_or_b32_e32 v12, v31, v95
	v_lshl_add_u64 v[6:7], s[52:53], 0, v[6:7]
	v_lshlrev_b32_e32 v68, 4, v12
	v_lshl_add_u64 v[28:29], v[6:7], 0, v[68:69]
	global_store_dwordx4 v[28:29], v[8:11], off nt
	v_bfe_u32 v12, v27, 16, 1
	v_or_b32_e32 v14, v31, v96
	v_bfe_u32 v8, v13, 16, 1
	v_add3_u32 v8, v13, v8, s95
	v_bfe_u32 v9, v15, 16, 1
	v_lshrrev_b32_e32 v8, 16, v8
	v_add3_u32 v9, v15, v9, s95
	v_and_or_b32 v8, v9, s96, v8
	v_bfe_u32 v9, v17, 16, 1
	v_add3_u32 v9, v17, v9, s95
	v_bfe_u32 v10, v19, 16, 1
	v_lshrrev_b32_e32 v9, 16, v9
	v_add3_u32 v10, v19, v10, s95
	v_and_or_b32 v9, v10, s96, v9
	v_bfe_u32 v10, v21, 16, 1
	v_add3_u32 v10, v21, v10, s95
	v_bfe_u32 v11, v23, 16, 1
	v_lshrrev_b32_e32 v10, 16, v10
	v_add3_u32 v11, v23, v11, s95
	v_and_or_b32 v10, v11, s96, v10
	v_bfe_u32 v11, v25, 16, 1
	v_add3_u32 v11, v25, v11, s95
	v_lshrrev_b32_e32 v11, 16, v11
	v_add3_u32 v12, v27, v12, s95
	v_lshlrev_b32_e32 v68, 4, v14
	v_and_or_b32 v11, v12, s96, v11
	ds_read2_b32 v[12:13], v86 offset0:16 offset1:24
	v_lshl_add_u64 v[14:15], v[6:7], 0, v[68:69]
	global_store_dwordx4 v[14:15], v[8:11], off nt
	ds_read2_b32 v[14:15], v86 offset0:81 offset1:89
	ds_read2_b32 v[16:17], v86 offset0:146 offset1:154
	ds_read2_b32 v[18:19], v86 offset0:211 offset1:219
	s_waitcnt lgkmcnt(3)
	v_bfe_u32 v8, v12, 16, 1
	v_add3_u32 v8, v12, v8, s95
	s_waitcnt lgkmcnt(2)
	v_bfe_u32 v9, v14, 16, 1
	ds_read2_b32 v[20:21], v30 offset0:20 offset1:28
	v_lshrrev_b32_e32 v8, 16, v8
	v_add3_u32 v9, v14, v9, s95
	ds_read2_b32 v[22:23], v30 offset0:85 offset1:93
	v_and_or_b32 v8, v9, s96, v8
	s_waitcnt lgkmcnt(3)
	v_bfe_u32 v9, v16, 16, 1
	v_add3_u32 v9, v16, v9, s95
	s_waitcnt lgkmcnt(2)
	v_bfe_u32 v10, v18, 16, 1
	ds_read2_b32 v[24:25], v30 offset0:150 offset1:158
	v_lshrrev_b32_e32 v9, 16, v9
	v_add3_u32 v10, v18, v10, s95
	ds_read2_b32 v[26:27], v30 offset0:215 offset1:223
	v_and_or_b32 v9, v10, s96, v9
	s_waitcnt lgkmcnt(3)
	v_bfe_u32 v10, v20, 16, 1
	v_add3_u32 v10, v20, v10, s95
	s_waitcnt lgkmcnt(2)
	v_bfe_u32 v11, v22, 16, 1
	v_lshrrev_b32_e32 v10, 16, v10
	v_add3_u32 v11, v22, v11, s95
	v_and_or_b32 v10, v11, s96, v10
	s_waitcnt lgkmcnt(1)
	v_bfe_u32 v11, v24, 16, 1
	v_add3_u32 v11, v24, v11, s95
	s_waitcnt lgkmcnt(0)
	v_bfe_u32 v12, v26, 16, 1
	v_or_b32_e32 v14, 64, v31
	v_lshrrev_b32_e32 v11, 16, v11
	v_add3_u32 v12, v26, v12, s95
	v_or_b32_e32 v68, v14, v95
	v_and_or_b32 v11, v12, s96, v11
	v_lshl_add_u64 v[28:29], v[68:69], 4, v[6:7]
	global_store_dwordx4 v[28:29], v[8:11], off nt
	v_bfe_u32 v12, v27, 16, 1
	v_add3_u32 v12, v27, v12, s95
	v_bfe_u32 v8, v13, 16, 1
	v_add3_u32 v8, v13, v8, s95
	v_bfe_u32 v9, v15, 16, 1
	v_lshrrev_b32_e32 v8, 16, v8
	v_add3_u32 v9, v15, v9, s95
	v_and_or_b32 v8, v9, s96, v8
	v_bfe_u32 v9, v17, 16, 1
	v_add3_u32 v9, v17, v9, s95
	v_bfe_u32 v10, v19, 16, 1
	v_lshrrev_b32_e32 v9, 16, v9
	v_add3_u32 v10, v19, v10, s95
	v_and_or_b32 v9, v10, s96, v9
	v_bfe_u32 v10, v21, 16, 1
	v_add3_u32 v10, v21, v10, s95
	v_bfe_u32 v11, v23, 16, 1
	v_lshrrev_b32_e32 v10, 16, v10
	v_add3_u32 v11, v23, v11, s95
	v_and_or_b32 v10, v11, s96, v10
	v_bfe_u32 v11, v25, 16, 1
	v_add3_u32 v11, v25, v11, s95
	v_lshrrev_b32_e32 v11, 16, v11
	v_or_b32_e32 v68, v14, v97
	v_and_or_b32 v11, v12, s96, v11
	ds_read2_b32 v[12:13], v86 offset0:32 offset1:40
	v_lshl_add_u64 v[14:15], v[68:69], 4, v[6:7]
	global_store_dwordx4 v[14:15], v[8:11], off nt
	ds_read2_b32 v[14:15], v86 offset0:97 offset1:105
	ds_read2_b32 v[16:17], v86 offset0:162 offset1:170
	ds_read2_b32 v[18:19], v86 offset0:227 offset1:235
	s_waitcnt lgkmcnt(3)
	v_bfe_u32 v8, v12, 16, 1
	v_add3_u32 v8, v12, v8, s95
	s_waitcnt lgkmcnt(2)
	v_bfe_u32 v9, v14, 16, 1
	ds_read2_b32 v[20:21], v30 offset0:36 offset1:44
	v_lshrrev_b32_e32 v8, 16, v8
	v_add3_u32 v9, v14, v9, s95
	ds_read2_b32 v[22:23], v30 offset0:101 offset1:109
	v_and_or_b32 v8, v9, s96, v8
	s_waitcnt lgkmcnt(3)
	v_bfe_u32 v9, v16, 16, 1
	v_add3_u32 v9, v16, v9, s95
	s_waitcnt lgkmcnt(2)
	v_bfe_u32 v10, v18, 16, 1
	ds_read2_b32 v[24:25], v30 offset0:166 offset1:174
	v_lshrrev_b32_e32 v9, 16, v9
	v_add3_u32 v10, v18, v10, s95
	ds_read2_b32 v[26:27], v30 offset0:231 offset1:239
	v_and_or_b32 v9, v10, s96, v9
	s_waitcnt lgkmcnt(3)
	v_bfe_u32 v10, v20, 16, 1
	v_add3_u32 v10, v20, v10, s95
	s_waitcnt lgkmcnt(2)
	v_bfe_u32 v11, v22, 16, 1
	v_lshrrev_b32_e32 v10, 16, v10
	v_add3_u32 v11, v22, v11, s95
	v_and_or_b32 v10, v11, s96, v10
	s_waitcnt lgkmcnt(1)
	v_bfe_u32 v11, v24, 16, 1
	v_add3_u32 v11, v24, v11, s95
	s_waitcnt lgkmcnt(0)
	v_bfe_u32 v12, v26, 16, 1
	v_or_b32_e32 v14, 0x80, v31
	v_lshrrev_b32_e32 v11, 16, v11
	v_add3_u32 v12, v26, v12, s95
	v_or_b32_e32 v68, v14, v95
	v_and_or_b32 v11, v12, s96, v11
	v_lshl_add_u64 v[28:29], v[68:69], 4, v[6:7]
	global_store_dwordx4 v[28:29], v[8:11], off nt
	v_bfe_u32 v12, v27, 16, 1
	v_add3_u32 v12, v27, v12, s95
	v_bfe_u32 v8, v13, 16, 1
	v_add3_u32 v8, v13, v8, s95
	v_bfe_u32 v9, v15, 16, 1
	v_lshrrev_b32_e32 v8, 16, v8
	v_add3_u32 v9, v15, v9, s95
	v_and_or_b32 v8, v9, s96, v8
	v_bfe_u32 v9, v17, 16, 1
	v_add3_u32 v9, v17, v9, s95
	v_bfe_u32 v10, v19, 16, 1
	v_lshrrev_b32_e32 v9, 16, v9
	v_add3_u32 v10, v19, v10, s95
	v_and_or_b32 v9, v10, s96, v9
	v_bfe_u32 v10, v21, 16, 1
	v_add3_u32 v10, v21, v10, s95
	v_bfe_u32 v11, v23, 16, 1
	v_lshrrev_b32_e32 v10, 16, v10
	v_add3_u32 v11, v23, v11, s95
	v_and_or_b32 v10, v11, s96, v10
	v_bfe_u32 v11, v25, 16, 1
	v_add3_u32 v11, v25, v11, s95
	v_lshrrev_b32_e32 v11, 16, v11
	v_or_b32_e32 v68, v14, v98
	v_and_or_b32 v11, v12, s96, v11
	ds_read2_b32 v[12:13], v86 offset0:48 offset1:56
	v_lshl_add_u64 v[14:15], v[68:69], 4, v[6:7]
	global_store_dwordx4 v[14:15], v[8:11], off nt
	ds_read2_b32 v[14:15], v86 offset0:113 offset1:121
	ds_read2_b32 v[16:17], v86 offset0:178 offset1:186
	ds_read2_b32 v[18:19], v86 offset0:243 offset1:251
	s_waitcnt lgkmcnt(3)
	v_bfe_u32 v8, v12, 16, 1
	v_add3_u32 v8, v12, v8, s95
	s_waitcnt lgkmcnt(2)
	v_bfe_u32 v9, v14, 16, 1
	ds_read2_b32 v[20:21], v30 offset0:52 offset1:60
	v_lshrrev_b32_e32 v8, 16, v8
	v_add3_u32 v9, v14, v9, s95
	ds_read2_b32 v[22:23], v30 offset0:117 offset1:125
	v_and_or_b32 v8, v9, s96, v8
	s_waitcnt lgkmcnt(3)
	v_bfe_u32 v9, v16, 16, 1
	v_add3_u32 v9, v16, v9, s95
	s_waitcnt lgkmcnt(2)
	v_bfe_u32 v10, v18, 16, 1
	ds_read2_b32 v[24:25], v30 offset0:182 offset1:190
	v_lshrrev_b32_e32 v9, 16, v9
	v_add3_u32 v10, v18, v10, s95
	ds_read2_b32 v[26:27], v30 offset0:247 offset1:255
	v_and_or_b32 v9, v10, s96, v9
	s_waitcnt lgkmcnt(3)
	v_bfe_u32 v10, v20, 16, 1
	v_add3_u32 v10, v20, v10, s95
	s_waitcnt lgkmcnt(2)
	v_bfe_u32 v11, v22, 16, 1
	v_lshrrev_b32_e32 v10, 16, v10
	v_add3_u32 v11, v22, v11, s95
	v_and_or_b32 v10, v11, s96, v10
	s_waitcnt lgkmcnt(1)
	v_bfe_u32 v11, v24, 16, 1
	v_add3_u32 v11, v24, v11, s95
	s_waitcnt lgkmcnt(0)
	v_bfe_u32 v12, v26, 16, 1
	v_lshrrev_b32_e32 v11, 16, v11
	v_add3_u32 v12, v26, v12, s95
	v_and_or_b32 v11, v12, s96, v11
	v_or_b32_e32 v12, 0xc0, v31
	v_or_b32_e32 v68, v12, v95
	v_lshl_add_u64 v[28:29], v[68:69], 4, v[6:7]
	global_store_dwordx4 v[28:29], v[8:11], off nt
	v_or_b32_e32 v68, v12, v99
	v_lshl_add_u64 v[6:7], v[68:69], 4, v[6:7]
	v_bfe_u32 v8, v13, 16, 1
	v_add3_u32 v8, v13, v8, s95
	v_bfe_u32 v9, v15, 16, 1
	v_lshrrev_b32_e32 v8, 16, v8
	v_add3_u32 v9, v15, v9, s95
	v_and_or_b32 v8, v9, s96, v8
	v_bfe_u32 v9, v17, 16, 1
	v_add3_u32 v9, v17, v9, s95
	v_bfe_u32 v10, v19, 16, 1
	v_lshrrev_b32_e32 v9, 16, v9
	v_add3_u32 v10, v19, v10, s95
	v_and_or_b32 v9, v10, s96, v9
	v_bfe_u32 v10, v21, 16, 1
	v_add3_u32 v10, v21, v10, s95
	v_bfe_u32 v11, v23, 16, 1
	v_lshrrev_b32_e32 v10, 16, v10
	v_add3_u32 v11, v23, v11, s95
	v_and_or_b32 v10, v11, s96, v10
	v_bfe_u32 v11, v25, 16, 1
	v_add3_u32 v11, v25, v11, s95
	v_bfe_u32 v13, v27, 16, 1
	v_lshrrev_b32_e32 v11, 16, v11
	v_add3_u32 v13, v27, v13, s95
	v_and_or_b32 v11, v13, s96, v11
	global_store_dwordx4 v[6:7], v[8:11], off nt
	s_waitcnt lgkmcnt(0)

.LBB0_88:
	v_lshlrev_b32_e32 v11, 5, v81
	v_and_b32_e32 v11, 0xc0, v11
	v_lshlrev_b32_e32 v10, 6, v81
	v_or_b32_e32 v12, v11, v83
	v_lshl_add_u64 v[8:9], v[6:7], 2, s[22:23]
	v_and_b32_e32 v10, 64, v10
	v_lshlrev_b32_e32 v68, 9, v12
	v_lshl_add_u64 v[8:9], v[8:9], 0, v[68:69]
	v_lshlrev_b32_e32 v68, 2, v10
	v_lshl_add_u64 v[8:9], v[8:9], 0, v[68:69]
	v_mov_b32_e32 v73, v69
	v_lshl_add_u64 v[8:9], v[8:9], 0, v[72:73]
	s_movk_i32 s2, 0x1000
	v_add_co_u32_e64 v24, s[2:3], s2, v8
	global_load_dwordx4 v[12:15], v[8:9], off nt
	global_load_dwordx4 v[16:19], v[8:9], off offset:2048 nt
	v_addc_co_u32_e64 v25, s[2:3], 0, v9, s[2:3]
	s_movk_i32 s2, 0x2000
	s_nop 0
	v_add_co_u32_e64 v32, s[2:3], s2, v8
	v_add_u32_e32 v68, 0x1c70, v84
	s_nop 0
	v_addc_co_u32_e64 v33, s[2:3], 0, v9, s[2:3]
	s_movk_i32 s2, 0x3000
	s_nop 0
	v_add_co_u32_e64 v36, s[2:3], s2, v8
	global_load_dwordx4 v[20:23], v[32:33], off offset:-4096 nt
	s_nop 0
	global_load_dwordx4 v[24:27], v[24:25], off offset:2048 nt
	s_nop 0
	global_load_dwordx4 v[28:31], v[32:33], off nt
	s_nop 0
	global_load_dwordx4 v[32:35], v[32:33], off offset:2048 nt
	v_addc_co_u32_e64 v37, s[2:3], 0, v9, s[2:3]
	s_movk_i32 s2, 0x4000
	s_nop 0
	v_add_co_u32_e64 v48, s[2:3], s2, v8
	v_add_u32_e32 v73, 0x1c78, v84
	s_nop 0
	v_addc_co_u32_e64 v49, s[2:3], 0, v9, s[2:3]
	s_movk_i32 s2, 0x6000
	s_nop 0
	v_add_co_u32_e64 v64, s[2:3], s2, v8
	global_load_dwordx4 v[36:39], v[36:37], off offset:2048 nt
	s_nop 0
	global_load_dwordx4 v[40:43], v[48:49], off offset:-4096 nt
	global_load_dwordx4 v[44:47], v[48:49], off nt
	v_addc_co_u32_e64 v65, s[2:3], 0, v9, s[2:3]
	global_load_dwordx4 v[48:51], v[48:49], off offset:2048 nt
	s_nop 0
	global_load_dwordx4 v[52:55], v[64:65], off offset:-4096 nt
	s_movk_i32 s2, 0x5000
	v_add_co_u32_e64 v56, s[2:3], s2, v8
	v_add_u32_e32 v78, 0x2080, v84
	s_nop 0
	v_addc_co_u32_e64 v57, s[2:3], 0, v9, s[2:3]
	global_load_dwordx4 v[56:59], v[56:57], off offset:2048 nt
	s_nop 0
	global_load_dwordx4 v[60:63], v[64:65], off nt
	global_load_dwordx4 v[74:77], v[64:65], off offset:2048 nt
	s_movk_i32 s2, 0x7000
	v_add_co_u32_e64 v8, s[2:3], s2, v8
	v_add_u32_e32 v64, 0x1860, v84
	s_nop 0
	v_addc_co_u32_e64 v9, s[2:3], 0, v9, s[2:3]
	global_load_dwordx4 v[116:119], v[8:9], off nt
	global_load_dwordx4 v[120:123], v[8:9], off offset:2048 nt
	v_lshlrev_b64 v[8:9], 16, v[4:5]
	v_add_u32_e32 v5, 0x1458, v84
	v_add_u32_e32 v65, 0x1868, v84
	v_add_u32_e32 v79, 0x2088, v84
	v_add_u32_e32 v80, 0x2490, v84
	v_add_u32_e32 v115, 0x2498, v84
	v_add_u32_e32 v124, 0x28a0, v84
	v_lshl_add_u64 v[8:9], s[0:1], 0, v[8:9]
	s_waitcnt vmcnt(15)
	ds_write2_b32 v84, v12, v13 offset1:1
	ds_write2_b32 v84, v14, v15 offset0:2 offset1:3
	s_waitcnt vmcnt(14)
	ds_write2_b32 v103, v16, v17 offset1:1
	ds_write2_b32 v104, v18, v19 offset1:1
	s_waitcnt vmcnt(13)
	ds_write2_b32 v105, v20, v21 offset1:1
	ds_write2_b32 v106, v22, v23 offset1:1
	s_waitcnt vmcnt(12)
	ds_write2_b32 v107, v24, v25 offset1:1
	ds_write2_b32 v108, v26, v27 offset1:1
	s_waitcnt vmcnt(11)
	ds_write2_b32 v109, v28, v29 offset1:1
	ds_write2_b32 v110, v30, v31 offset1:1
	s_waitcnt vmcnt(10)
	ds_write2_b32 v111, v32, v33 offset1:1
	ds_write2_b32 v5, v34, v35 offset1:1
	s_waitcnt vmcnt(8)
	ds_write2_b32 v64, v40, v41 offset1:1
	ds_write2_b32 v65, v42, v43 offset1:1
	ds_write2_b32 v68, v36, v37 offset1:1
	ds_write2_b32 v73, v38, v39 offset1:1
	s_waitcnt vmcnt(7)
	ds_write2_b32 v78, v44, v45 offset1:1
	ds_write2_b32 v79, v46, v47 offset1:1
	s_waitcnt vmcnt(6)
	ds_write2_b32 v80, v48, v49 offset1:1
	ds_write2_b32 v115, v50, v51 offset1:1
	s_waitcnt vmcnt(5)
	ds_write2_b32 v124, v52, v53 offset1:1
	v_add_u32_e32 v5, 0x28a8, v84
	ds_write2_b32 v5, v54, v55 offset1:1
	v_add_u32_e32 v5, 0x2cb0, v84
	v_lshlrev_b32_e32 v68, 1, v11
	s_waitcnt vmcnt(4)
	ds_write2_b32 v5, v56, v57 offset1:1
	v_add_u32_e32 v5, 0x2cb8, v84
	ds_write2_b32 v5, v58, v59 offset1:1
	v_add_u32_e32 v5, 0x30c0, v84
	s_waitcnt vmcnt(3)
	ds_write2_b32 v5, v60, v61 offset1:1
	v_add_u32_e32 v5, 0x30c8, v84
	ds_write2_b32 v5, v62, v63 offset1:1
	v_add_u32_e32 v5, 0x34d0, v84
	s_waitcnt vmcnt(2)
	ds_write2_b32 v5, v74, v75 offset1:1
	v_add_u32_e32 v5, 0x34d8, v84
	ds_write2_b32 v5, v76, v77 offset1:1
	v_add_u32_e32 v5, 0x38e0, v84
	s_waitcnt vmcnt(1)
	ds_write2_b32 v5, v116, v117 offset1:1
	v_add_u32_e32 v5, 0x38e8, v84
	ds_write2_b32 v5, v118, v119 offset1:1
	v_add_u32_e32 v5, 0x3cf0, v84
	s_waitcnt vmcnt(0)
	ds_write2_b32 v5, v120, v121 offset1:1
	v_add_u32_e32 v5, 0x3cf8, v84
	ds_write2_b32 v5, v122, v123 offset1:1
	s_waitcnt lgkmcnt(0)
	v_add_u32_e32 v5, 0x400, v86
	ds_read2_b32 v[18:19], v5 offset0:134 offset1:142
	ds_read2_b32 v[16:17], v5 offset0:199 offset1:207
	ds_read2_b32 v[22:23], v5 offset0:4 offset1:12
	ds_read2_b32 v[20:21], v5 offset0:69 offset1:77
	ds_read2_b32 v[26:27], v86 offset0:130 offset1:138
	s_waitcnt lgkmcnt(4)
	v_bfe_u32 v12, v18, 16, 1
	s_waitcnt lgkmcnt(3)
	v_bfe_u32 v11, v16, 16, 1
	v_add3_u32 v12, v18, v12, s95
	v_add3_u32 v11, v16, v11, s95
	v_lshrrev_b32_e32 v12, 16, v12
	ds_read2_b32 v[24:25], v86 offset0:195 offset1:203
	v_and_or_b32 v15, v11, s96, v12
	s_waitcnt lgkmcnt(3)
	v_bfe_u32 v12, v22, 16, 1
	s_waitcnt lgkmcnt(2)
	v_bfe_u32 v11, v20, 16, 1
	v_add3_u32 v12, v22, v12, s95
	ds_read2_b32 v[30:31], v86 offset1:8
	v_add3_u32 v11, v20, v11, s95
	v_lshrrev_b32_e32 v12, 16, v12
	ds_read2_b32 v[28:29], v86 offset0:65 offset1:73
	v_and_or_b32 v14, v11, s96, v12
	s_waitcnt lgkmcnt(3)
	v_bfe_u32 v12, v26, 16, 1
	s_waitcnt lgkmcnt(2)
	v_bfe_u32 v11, v24, 16, 1
	v_add3_u32 v12, v26, v12, s95
	v_add3_u32 v11, v24, v11, s95
	v_lshrrev_b32_e32 v12, 16, v12
	v_and_or_b32 v13, v11, s96, v12
	s_waitcnt lgkmcnt(1)
	v_bfe_u32 v12, v30, 16, 1
	s_waitcnt lgkmcnt(0)
	v_bfe_u32 v11, v28, 16, 1
	v_add3_u32 v12, v30, v12, s95
	v_add3_u32 v11, v28, v11, s95
	v_lshrrev_b32_e32 v12, 16, v12
	v_lshl_add_u64 v[8:9], v[8:9], 0, v[68:69]
	v_lshlrev_b32_e32 v68, 1, v70
	v_and_or_b32 v12, v11, s96, v12
	v_or_b32_e32 v11, v10, v85
	v_lshl_add_u64 v[8:9], v[8:9], 0, v[68:69]
	v_lshlrev_b32_e32 v68, 9, v11
	v_lshl_add_u64 v[32:33], v[8:9], 0, v[68:69]
	global_store_dwordx4 v[32:33], v[12:15], off nt
	v_bfe_u32 v11, v17, 16, 1
	v_add3_u32 v11, v17, v11, s95
	v_bfe_u32 v12, v19, 16, 1
	v_add3_u32 v12, v19, v12, s95
	v_lshrrev_b32_e32 v12, 16, v12
	v_and_or_b32 v15, v11, s96, v12
	v_bfe_u32 v12, v23, 16, 1
	v_bfe_u32 v11, v21, 16, 1
	v_add3_u32 v12, v23, v12, s95
	v_add3_u32 v11, v21, v11, s95
	v_lshrrev_b32_e32 v12, 16, v12
	v_and_or_b32 v14, v11, s96, v12
	v_bfe_u32 v12, v27, 16, 1
	v_bfe_u32 v11, v25, 16, 1
	v_add3_u32 v12, v27, v12, s95
	v_add3_u32 v11, v25, v11, s95
	v_lshrrev_b32_e32 v12, 16, v12
	v_and_or_b32 v13, v11, s96, v12
	v_bfe_u32 v12, v31, 16, 1
	v_bfe_u32 v11, v29, 16, 1
	v_add3_u32 v12, v31, v12, s95
	v_add3_u32 v11, v29, v11, s95
	v_lshrrev_b32_e32 v12, 16, v12
	ds_read2_b32 v[18:19], v5 offset0:150 offset1:158
	v_and_or_b32 v12, v11, s96, v12
	v_or_b32_e32 v11, v10, v87
	ds_read2_b32 v[16:17], v5 offset0:215 offset1:223
	v_lshlrev_b32_e32 v68, 9, v11
	v_lshl_add_u64 v[20:21], v[8:9], 0, v[68:69]
	ds_read2_b32 v[22:23], v5 offset0:20 offset1:28
	global_store_dwordx4 v[20:21], v[12:15], off nt
	ds_read2_b32 v[20:21], v5 offset0:85 offset1:93
	s_waitcnt lgkmcnt(2)
	v_bfe_u32 v11, v16, 16, 1
	v_bfe_u32 v12, v18, 16, 1
	v_add3_u32 v12, v18, v12, s95
	ds_read2_b32 v[26:27], v86 offset0:146 offset1:154
	v_add3_u32 v11, v16, v11, s95
	v_lshrrev_b32_e32 v12, 16, v12
	ds_read2_b32 v[24:25], v86 offset0:211 offset1:219
	v_and_or_b32 v15, v11, s96, v12
	s_waitcnt lgkmcnt(3)
	v_bfe_u32 v12, v22, 16, 1
	s_waitcnt lgkmcnt(2)
	v_bfe_u32 v11, v20, 16, 1
	v_add3_u32 v12, v22, v12, s95
	ds_read2_b32 v[30:31], v86 offset0:16 offset1:24
	v_add3_u32 v11, v20, v11, s95
	v_lshrrev_b32_e32 v12, 16, v12
	ds_read2_b32 v[28:29], v86 offset0:81 offset1:89
	v_and_or_b32 v14, v11, s96, v12
	s_waitcnt lgkmcnt(3)
	v_bfe_u32 v12, v26, 16, 1
	s_waitcnt lgkmcnt(2)
	v_bfe_u32 v11, v24, 16, 1
	v_add3_u32 v12, v26, v12, s95
	v_add3_u32 v11, v24, v11, s95
	v_lshrrev_b32_e32 v12, 16, v12
	v_and_or_b32 v13, v11, s96, v12
	s_waitcnt lgkmcnt(1)
	v_bfe_u32 v12, v30, 16, 1
	s_waitcnt lgkmcnt(0)
	v_bfe_u32 v11, v28, 16, 1
	v_add3_u32 v12, v30, v12, s95
	v_add3_u32 v11, v28, v11, s95
	v_lshrrev_b32_e32 v12, 16, v12
	v_and_or_b32 v12, v11, s96, v12
	v_or_b32_e32 v11, v10, v88
	v_lshlrev_b32_e32 v68, 9, v11
	v_lshl_add_u64 v[32:33], v[8:9], 0, v[68:69]
	global_store_dwordx4 v[32:33], v[12:15], off nt
	v_bfe_u32 v11, v17, 16, 1
	v_add3_u32 v11, v17, v11, s95
	v_bfe_u32 v12, v19, 16, 1
	v_add3_u32 v12, v19, v12, s95
	v_lshrrev_b32_e32 v12, 16, v12
	v_and_or_b32 v15, v11, s96, v12
	v_bfe_u32 v12, v23, 16, 1
	v_bfe_u32 v11, v21, 16, 1
	v_add3_u32 v12, v23, v12, s95
	v_add3_u32 v11, v21, v11, s95
	v_lshrrev_b32_e32 v12, 16, v12
	v_and_or_b32 v14, v11, s96, v12
	v_bfe_u32 v12, v27, 16, 1
	v_bfe_u32 v11, v25, 16, 1
	v_add3_u32 v12, v27, v12, s95
	v_add3_u32 v11, v25, v11, s95
	v_lshrrev_b32_e32 v12, 16, v12
	v_and_or_b32 v13, v11, s96, v12
	v_bfe_u32 v12, v31, 16, 1
	v_bfe_u32 v11, v29, 16, 1
	v_add3_u32 v12, v31, v12, s95
	v_add3_u32 v11, v29, v11, s95
	v_lshrrev_b32_e32 v12, 16, v12
	ds_read2_b32 v[18:19], v5 offset0:166 offset1:174
	v_and_or_b32 v12, v11, s96, v12
	v_or_b32_e32 v11, v10, v89
	ds_read2_b32 v[16:17], v5 offset0:231 offset1:239
	v_lshlrev_b32_e32 v68, 9, v11
	v_lshl_add_u64 v[20:21], v[8:9], 0, v[68:69]
	ds_read2_b32 v[22:23], v5 offset0:36 offset1:44
	global_store_dwordx4 v[20:21], v[12:15], off nt
	ds_read2_b32 v[20:21], v5 offset0:101 offset1:109
	s_waitcnt lgkmcnt(2)
	v_bfe_u32 v11, v16, 16, 1
	v_bfe_u32 v12, v18, 16, 1
	v_add3_u32 v12, v18, v12, s95
	ds_read2_b32 v[26:27], v86 offset0:162 offset1:170
	v_add3_u32 v11, v16, v11, s95
	v_lshrrev_b32_e32 v12, 16, v12
	ds_read2_b32 v[24:25], v86 offset0:227 offset1:235
	v_and_or_b32 v15, v11, s96, v12
	s_waitcnt lgkmcnt(3)
	v_bfe_u32 v12, v22, 16, 1
	s_waitcnt lgkmcnt(2)
	v_bfe_u32 v11, v20, 16, 1
	v_add3_u32 v12, v22, v12, s95
	ds_read2_b32 v[30:31], v86 offset0:32 offset1:40
	v_add3_u32 v11, v20, v11, s95
	v_lshrrev_b32_e32 v12, 16, v12
	ds_read2_b32 v[28:29], v86 offset0:97 offset1:105
	v_and_or_b32 v14, v11, s96, v12
	s_waitcnt lgkmcnt(3)
	v_bfe_u32 v12, v26, 16, 1
	s_waitcnt lgkmcnt(2)
	v_bfe_u32 v11, v24, 16, 1
	v_add3_u32 v12, v26, v12, s95
	v_add3_u32 v11, v24, v11, s95
	v_lshrrev_b32_e32 v12, 16, v12
	v_and_or_b32 v13, v11, s96, v12
	s_waitcnt lgkmcnt(1)
	v_bfe_u32 v12, v30, 16, 1
	s_waitcnt lgkmcnt(0)
	v_bfe_u32 v11, v28, 16, 1
	v_add3_u32 v12, v30, v12, s95
	v_add3_u32 v11, v28, v11, s95
	v_lshrrev_b32_e32 v12, 16, v12
	v_and_or_b32 v12, v11, s96, v12
	v_or_b32_e32 v11, v10, v90
	v_lshlrev_b32_e32 v68, 9, v11
	v_lshl_add_u64 v[32:33], v[8:9], 0, v[68:69]
	global_store_dwordx4 v[32:33], v[12:15], off nt
	v_bfe_u32 v11, v17, 16, 1
	v_add3_u32 v11, v17, v11, s95
	v_bfe_u32 v12, v19, 16, 1
	v_add3_u32 v12, v19, v12, s95
	v_lshrrev_b32_e32 v12, 16, v12
	v_and_or_b32 v15, v11, s96, v12
	v_bfe_u32 v12, v23, 16, 1
	v_bfe_u32 v11, v21, 16, 1
	v_add3_u32 v12, v23, v12, s95
	v_add3_u32 v11, v21, v11, s95
	v_lshrrev_b32_e32 v12, 16, v12
	v_and_or_b32 v14, v11, s96, v12
	v_bfe_u32 v12, v27, 16, 1
	v_bfe_u32 v11, v25, 16, 1
	v_add3_u32 v12, v27, v12, s95
	v_add3_u32 v11, v25, v11, s95
	v_lshrrev_b32_e32 v12, 16, v12
	v_and_or_b32 v13, v11, s96, v12
	v_bfe_u32 v12, v31, 16, 1
	v_bfe_u32 v11, v29, 16, 1
	v_add3_u32 v12, v31, v12, s95
	v_add3_u32 v11, v29, v11, s95
	v_lshrrev_b32_e32 v12, 16, v12
	ds_read2_b32 v[18:19], v5 offset0:182 offset1:190
	v_and_or_b32 v12, v11, s96, v12
	v_or_b32_e32 v11, v10, v91
	ds_read2_b32 v[16:17], v5 offset0:247 offset1:255
	v_lshlrev_b32_e32 v68, 9, v11
	v_lshl_add_u64 v[20:21], v[8:9], 0, v[68:69]
	ds_read2_b32 v[22:23], v5 offset0:52 offset1:60
	global_store_dwordx4 v[20:21], v[12:15], off nt
	ds_read2_b32 v[20:21], v5 offset0:117 offset1:125
	s_waitcnt lgkmcnt(2)
	v_bfe_u32 v11, v16, 16, 1
	v_bfe_u32 v12, v18, 16, 1
	v_add3_u32 v12, v18, v12, s95
	ds_read2_b32 v[26:27], v86 offset0:178 offset1:186
	v_add3_u32 v11, v16, v11, s95
	v_lshrrev_b32_e32 v5, 16, v12
	ds_read2_b32 v[24:25], v86 offset0:243 offset1:251
	v_and_or_b32 v15, v11, s96, v5
	s_waitcnt lgkmcnt(3)
	v_bfe_u32 v11, v22, 16, 1
	s_waitcnt lgkmcnt(2)
	v_bfe_u32 v5, v20, 16, 1
	v_add3_u32 v11, v22, v11, s95
	ds_read2_b32 v[30:31], v86 offset0:48 offset1:56
	v_add3_u32 v5, v20, v5, s95
	v_lshrrev_b32_e32 v11, 16, v11
	ds_read2_b32 v[28:29], v86 offset0:113 offset1:121
	v_and_or_b32 v14, v5, s96, v11
	s_waitcnt lgkmcnt(3)
	v_bfe_u32 v11, v26, 16, 1
	s_waitcnt lgkmcnt(2)
	v_bfe_u32 v5, v24, 16, 1
	v_add3_u32 v11, v26, v11, s95
	v_add3_u32 v5, v24, v5, s95
	v_lshrrev_b32_e32 v11, 16, v11
	v_and_or_b32 v13, v5, s96, v11
	s_waitcnt lgkmcnt(1)
	v_bfe_u32 v11, v30, 16, 1
	s_waitcnt lgkmcnt(0)
	v_bfe_u32 v5, v28, 16, 1
	v_add3_u32 v11, v30, v11, s95
	v_add3_u32 v5, v28, v5, s95
	v_lshrrev_b32_e32 v11, 16, v11
	v_and_or_b32 v12, v5, s96, v11
	v_or_b32_e32 v5, v10, v92
	v_bfe_u32 v11, v19, 16, 1
	v_lshlrev_b32_e32 v68, 9, v5
	v_bfe_u32 v5, v17, 16, 1
	v_add3_u32 v11, v19, v11, s95
	v_lshl_add_u64 v[32:33], v[8:9], 0, v[68:69]
	v_add3_u32 v5, v17, v5, s95
	v_lshrrev_b32_e32 v11, 16, v11
	global_store_dwordx4 v[32:33], v[12:15], off nt
	s_nop 1
	v_and_or_b32 v15, v5, s96, v11
	v_bfe_u32 v11, v23, 16, 1
	v_bfe_u32 v5, v21, 16, 1
	v_add3_u32 v11, v23, v11, s95
	v_add3_u32 v5, v21, v5, s95
	v_lshrrev_b32_e32 v11, 16, v11
	v_and_or_b32 v14, v5, s96, v11
	v_bfe_u32 v11, v27, 16, 1
	v_bfe_u32 v5, v25, 16, 1
	v_add3_u32 v11, v27, v11, s95
	v_add3_u32 v5, v25, v5, s95
	v_lshrrev_b32_e32 v11, 16, v11
	v_and_or_b32 v13, v5, s96, v11
	v_bfe_u32 v11, v31, 16, 1
	v_bfe_u32 v5, v29, 16, 1
	v_add3_u32 v11, v31, v11, s95
	v_add3_u32 v5, v29, v5, s95
	v_lshrrev_b32_e32 v11, 16, v11
	v_and_or_b32 v12, v5, s96, v11
	v_or_b32_e32 v5, v10, v93
	v_lshlrev_b32_e32 v68, 9, v5
	v_lshl_add_u64 v[8:9], v[8:9], 0, v[68:69]
	global_store_dwordx4 v[8:9], v[12:15], off nt
	s_waitcnt lgkmcnt(0)
	s_or_b64 exec, exec, s[4:5]
	s_and_b64 exec, exec, vcc
	s_cbranch_execz .LBB0_95
.LBB0_89:
	v_or_b32_e32 v4, 1, v4
	v_ashrrev_i32_e32 v5, 31, v4
	v_cmp_lt_u32_e64 s[2:3], s58, v81
	v_cmp_gt_u32_e32 vcc, s59, v81
	s_and_saveexec_b64 s[4:5], vcc
	s_xor_b64 s[4:5], exec, s[4:5]
	s_cbranch_execz .LBB0_91
	v_lshrrev_b32_e32 v78, 2, v81
	v_lshl_add_u64 v[2:3], v[2:3], 2, s[26:27]
	v_lshl_or_b32 v68, v78, 16, v94
	v_lshlrev_b32_e32 v8, 8, v81
	v_lshl_add_u64 v[2:3], v[2:3], 0, v[68:69]
	v_and_b32_e32 v68, 0x300, v8
	v_lshl_add_u64 v[2:3], v[2:3], 0, v[68:69]
	v_mov_b32_e32 v73, v69
	v_lshl_add_u64 v[2:3], v[2:3], 0, v[72:73]
	s_movk_i32 s30, 0x2000
	v_add_co_u32_e32 v16, vcc, s30, v2
	s_movk_i32 s30, 0x4000
	s_nop 0
	v_addc_co_u32_e32 v17, vcc, 0, v3, vcc
	v_add_co_u32_e32 v32, vcc, s30, v2
	s_movk_i32 s30, 0x6000
	s_nop 0
	v_addc_co_u32_e32 v33, vcc, 0, v3, vcc
	v_add_co_u32_e32 v24, vcc, s78, v2
	global_load_dwordx4 v[8:11], v[2:3], off nt
	s_nop 0
	v_addc_co_u32_e32 v25, vcc, 0, v3, vcc
	v_add_co_u32_e32 v40, vcc, s30, v2
	s_mov_b32 s30, 0xa000
	s_nop 0
	v_addc_co_u32_e32 v41, vcc, 0, v3, vcc
	v_add_co_u32_e32 v48, vcc, s30, v2
	global_load_dwordx4 v[12:15], v[16:17], off offset:-4096 nt
	s_nop 0
	global_load_dwordx4 v[16:19], v[16:17], off nt
	s_nop 0
	global_load_dwordx4 v[20:23], v[24:25], off offset:-4096 nt
	s_nop 0
	global_load_dwordx4 v[24:27], v[24:25], off nt
	s_nop 0
	global_load_dwordx4 v[28:31], v[32:33], off offset:-4096 nt
	s_nop 0
	global_load_dwordx4 v[32:35], v[32:33], off nt
	s_nop 0
	global_load_dwordx4 v[36:39], v[40:41], off offset:-4096 nt
	s_nop 0
	global_load_dwordx4 v[40:43], v[40:41], off nt
	v_addc_co_u32_e32 v49, vcc, 0, v3, vcc
	global_load_dwordx4 v[44:47], v[48:49], off offset:-4096 nt
	s_nop 0
	global_load_dwordx4 v[48:51], v[48:49], off nt
	s_mov_b32 s30, 0xc000
	v_add_co_u32_e32 v56, vcc, s30, v2
	s_mov_b32 s30, 0xe000
	s_nop 0
	v_addc_co_u32_e32 v57, vcc, 0, v3, vcc
	global_load_dwordx4 v[52:55], v[56:57], off offset:-4096 nt
	s_nop 0
	global_load_dwordx4 v[56:59], v[56:57], off nt
	v_add_co_u32_e32 v64, vcc, s30, v2
	s_mov_b32 s30, 0xf000
	s_nop 0
	v_addc_co_u32_e32 v65, vcc, 0, v3, vcc
	global_load_dwordx4 v[60:63], v[64:65], off offset:-4096 nt
	global_load_dwordx4 v[74:77], v[64:65], off nt
	v_add_co_u32_e32 v2, vcc, s30, v2
	v_add_u32_e32 v64, 0x1868, v84
	s_nop 0
	v_addc_co_u32_e32 v3, vcc, 0, v3, vcc
	global_load_dwordx4 v[116:119], v[2:3], off nt
	v_add_u32_e32 v2, 0x1458, v84
	v_add_u32_e32 v3, 0x1860, v84
	v_add_u32_e32 v65, 0x1c70, v84
	v_add_u32_e32 v73, 0x1c78, v84
	v_add_u32_e32 v79, 0x2080, v84
	v_add_u32_e32 v80, 0x2088, v84
	v_add_u32_e32 v115, 0x2490, v84
	s_waitcnt vmcnt(15)
	ds_write2_b32 v84, v8, v9 offset1:1
	ds_write2_b32 v84, v10, v11 offset0:2 offset1:3
	s_waitcnt vmcnt(12)
	ds_write2_b32 v65, v20, v21 offset1:1
	ds_write2_b32 v73, v22, v23 offset1:1
	s_waitcnt vmcnt(11)
	ds_write2_b32 v79, v24, v25 offset1:1
	ds_write2_b32 v80, v26, v27 offset1:1
	ds_write2_b32 v103, v12, v13 offset1:1
	ds_write2_b32 v104, v14, v15 offset1:1
	ds_write2_b32 v105, v16, v17 offset1:1
	ds_write2_b32 v106, v18, v19 offset1:1
	s_waitcnt vmcnt(10)
	ds_write2_b32 v107, v28, v29 offset1:1
	ds_write2_b32 v108, v30, v31 offset1:1
	s_waitcnt vmcnt(9)
	ds_write2_b32 v109, v32, v33 offset1:1
	ds_write2_b32 v110, v34, v35 offset1:1
	s_waitcnt vmcnt(8)
	ds_write2_b32 v111, v36, v37 offset1:1
	ds_write2_b32 v2, v38, v39 offset1:1
	s_waitcnt vmcnt(7)
	ds_write2_b32 v3, v40, v41 offset1:1
	ds_write2_b32 v64, v42, v43 offset1:1
	s_waitcnt vmcnt(6)
	ds_write2_b32 v115, v44, v45 offset1:1
	v_add_u32_e32 v2, 0x2498, v84
	ds_write2_b32 v2, v46, v47 offset1:1
	v_add_u32_e32 v2, 0x28a0, v84
	s_waitcnt vmcnt(5)
	ds_write2_b32 v2, v48, v49 offset1:1
	v_add_u32_e32 v2, 0x28a8, v84
	ds_write2_b32 v2, v50, v51 offset1:1
	v_add_u32_e32 v2, 0x2cb0, v84
	s_waitcnt vmcnt(4)
	ds_write2_b32 v2, v52, v53 offset1:1
	v_add_u32_e32 v2, 0x2cb8, v84
	ds_write2_b32 v2, v54, v55 offset1:1
	v_add_u32_e32 v2, 0x30c0, v84
	s_waitcnt vmcnt(3)
	ds_write2_b32 v2, v56, v57 offset1:1
	v_add_u32_e32 v2, 0x30c8, v84
	ds_write2_b32 v2, v58, v59 offset1:1
	v_add_u32_e32 v2, 0x34d0, v84
	s_waitcnt vmcnt(2)
	ds_write2_b32 v2, v60, v61 offset1:1
	v_add_u32_e32 v2, 0x34d8, v84
	ds_write2_b32 v2, v62, v63 offset1:1
	v_add_u32_e32 v2, 0x38e0, v84
	s_waitcnt vmcnt(1)
	ds_write2_b32 v2, v74, v75 offset1:1
	v_add_u32_e32 v2, 0x38e8, v84
	ds_write2_b32 v2, v76, v77 offset1:1
	v_add_u32_e32 v2, 0x3cf0, v84
	s_waitcnt vmcnt(0)
	ds_write2_b32 v2, v116, v117 offset1:1
	v_add_u32_e32 v2, 0x3cf8, v84
	ds_write2_b32 v2, v118, v119 offset1:1
	s_waitcnt lgkmcnt(0)
	ds_read2_b32 v[12:13], v86 offset1:8
	ds_read2_b32 v[14:15], v86 offset0:65 offset1:73
	ds_read2_b32 v[16:17], v86 offset0:130 offset1:138
	ds_read2_b32 v[18:19], v86 offset0:195 offset1:203
	v_add_u32_e32 v30, 0x400, v86
	s_waitcnt lgkmcnt(3)
	v_bfe_u32 v8, v12, 16, 1
	v_add3_u32 v8, v12, v8, s95
	s_waitcnt lgkmcnt(2)
	v_bfe_u32 v9, v14, 16, 1
	ds_read2_b32 v[20:21], v30 offset0:4 offset1:12
	v_lshrrev_b32_e32 v8, 16, v8
	v_add3_u32 v9, v14, v9, s95
	ds_read2_b32 v[22:23], v30 offset0:69 offset1:77
	v_and_or_b32 v8, v9, s96, v8
	s_waitcnt lgkmcnt(3)
	v_bfe_u32 v9, v16, 16, 1
	v_add3_u32 v9, v16, v9, s95
	s_waitcnt lgkmcnt(2)
	v_bfe_u32 v10, v18, 16, 1
	ds_read2_b32 v[24:25], v30 offset0:134 offset1:142
	v_lshrrev_b32_e32 v9, 16, v9
	v_add3_u32 v10, v18, v10, s95
	ds_read2_b32 v[26:27], v30 offset0:199 offset1:207
	v_and_or_b32 v9, v10, s96, v9
	s_waitcnt lgkmcnt(3)
	v_bfe_u32 v10, v20, 16, 1
	v_add3_u32 v10, v20, v10, s95
	s_waitcnt lgkmcnt(2)
	v_bfe_u32 v11, v22, 16, 1
	v_lshrrev_b32_e32 v10, 16, v10
	v_add3_u32 v11, v22, v11, s95
	v_and_or_b32 v10, v11, s96, v10
	s_waitcnt lgkmcnt(1)
	v_bfe_u32 v11, v24, 16, 1
	v_add3_u32 v11, v24, v11, s95
	s_waitcnt lgkmcnt(0)
	v_bfe_u32 v12, v26, 16, 1
	v_lshrrev_b32_e32 v11, 16, v11
	v_add3_u32 v12, v26, v12, s95
	v_and_or_b32 v11, v12, s96, v11
	v_lshlrev_b32_e32 v12, 11, v78
	v_or3_b32 v31, v12, v68, v100
	v_lshlrev_b64 v[2:3], 21, v[4:5]
	v_or_b32_e32 v12, v31, v95
	v_lshl_add_u64 v[2:3], s[52:53], 0, v[2:3]
	v_lshlrev_b32_e32 v68, 4, v12
	v_lshl_add_u64 v[28:29], v[2:3], 0, v[68:69]
	global_store_dwordx4 v[28:29], v[8:11], off nt
	v_bfe_u32 v12, v27, 16, 1
	v_or_b32_e32 v14, v31, v96
	v_bfe_u32 v8, v13, 16, 1
	v_add3_u32 v8, v13, v8, s95
	v_bfe_u32 v9, v15, 16, 1
	v_lshrrev_b32_e32 v8, 16, v8
	v_add3_u32 v9, v15, v9, s95
	v_and_or_b32 v8, v9, s96, v8
	v_bfe_u32 v9, v17, 16, 1
	v_add3_u32 v9, v17, v9, s95
	v_bfe_u32 v10, v19, 16, 1
	v_lshrrev_b32_e32 v9, 16, v9
	v_add3_u32 v10, v19, v10, s95
	v_and_or_b32 v9, v10, s96, v9
	v_bfe_u32 v10, v21, 16, 1
	v_add3_u32 v10, v21, v10, s95
	v_bfe_u32 v11, v23, 16, 1
	v_lshrrev_b32_e32 v10, 16, v10
	v_add3_u32 v11, v23, v11, s95
	v_and_or_b32 v10, v11, s96, v10
	v_bfe_u32 v11, v25, 16, 1
	v_add3_u32 v11, v25, v11, s95
	v_lshrrev_b32_e32 v11, 16, v11
	v_add3_u32 v12, v27, v12, s95
	v_lshlrev_b32_e32 v68, 4, v14
	v_and_or_b32 v11, v12, s96, v11
	ds_read2_b32 v[12:13], v86 offset0:16 offset1:24
	v_lshl_add_u64 v[14:15], v[2:3], 0, v[68:69]
	global_store_dwordx4 v[14:15], v[8:11], off nt
	ds_read2_b32 v[14:15], v86 offset0:81 offset1:89
	ds_read2_b32 v[16:17], v86 offset0:146 offset1:154
	ds_read2_b32 v[18:19], v86 offset0:211 offset1:219
	s_waitcnt lgkmcnt(3)
	v_bfe_u32 v8, v12, 16, 1
	v_add3_u32 v8, v12, v8, s95
	s_waitcnt lgkmcnt(2)
	v_bfe_u32 v9, v14, 16, 1
	ds_read2_b32 v[20:21], v30 offset0:20 offset1:28
	v_lshrrev_b32_e32 v8, 16, v8
	v_add3_u32 v9, v14, v9, s95
	ds_read2_b32 v[22:23], v30 offset0:85 offset1:93
	v_and_or_b32 v8, v9, s96, v8
	s_waitcnt lgkmcnt(3)
	v_bfe_u32 v9, v16, 16, 1
	v_add3_u32 v9, v16, v9, s95
	s_waitcnt lgkmcnt(2)
	v_bfe_u32 v10, v18, 16, 1
	ds_read2_b32 v[24:25], v30 offset0:150 offset1:158
	v_lshrrev_b32_e32 v9, 16, v9
	v_add3_u32 v10, v18, v10, s95
	ds_read2_b32 v[26:27], v30 offset0:215 offset1:223
	v_and_or_b32 v9, v10, s96, v9
	s_waitcnt lgkmcnt(3)
	v_bfe_u32 v10, v20, 16, 1
	v_add3_u32 v10, v20, v10, s95
	s_waitcnt lgkmcnt(2)
	v_bfe_u32 v11, v22, 16, 1
	v_lshrrev_b32_e32 v10, 16, v10
	v_add3_u32 v11, v22, v11, s95
	v_and_or_b32 v10, v11, s96, v10
	s_waitcnt lgkmcnt(1)
	v_bfe_u32 v11, v24, 16, 1
	v_add3_u32 v11, v24, v11, s95
	s_waitcnt lgkmcnt(0)
	v_bfe_u32 v12, v26, 16, 1
	v_or_b32_e32 v14, 64, v31
	v_lshrrev_b32_e32 v11, 16, v11
	v_add3_u32 v12, v26, v12, s95
	v_or_b32_e32 v68, v14, v95
	v_and_or_b32 v11, v12, s96, v11
	v_lshl_add_u64 v[28:29], v[68:69], 4, v[2:3]
	global_store_dwordx4 v[28:29], v[8:11], off nt
	v_bfe_u32 v12, v27, 16, 1
	v_add3_u32 v12, v27, v12, s95
	v_bfe_u32 v8, v13, 16, 1
	v_add3_u32 v8, v13, v8, s95
	v_bfe_u32 v9, v15, 16, 1
	v_lshrrev_b32_e32 v8, 16, v8
	v_add3_u32 v9, v15, v9, s95
	v_and_or_b32 v8, v9, s96, v8
	v_bfe_u32 v9, v17, 16, 1
	v_add3_u32 v9, v17, v9, s95
	v_bfe_u32 v10, v19, 16, 1
	v_lshrrev_b32_e32 v9, 16, v9
	v_add3_u32 v10, v19, v10, s95
	v_and_or_b32 v9, v10, s96, v9
	v_bfe_u32 v10, v21, 16, 1
	v_add3_u32 v10, v21, v10, s95
	v_bfe_u32 v11, v23, 16, 1
	v_lshrrev_b32_e32 v10, 16, v10
	v_add3_u32 v11, v23, v11, s95
	v_and_or_b32 v10, v11, s96, v10
	v_bfe_u32 v11, v25, 16, 1
	v_add3_u32 v11, v25, v11, s95
	v_lshrrev_b32_e32 v11, 16, v11
	v_or_b32_e32 v68, v14, v97
	v_and_or_b32 v11, v12, s96, v11
	ds_read2_b32 v[12:13], v86 offset0:32 offset1:40
	v_lshl_add_u64 v[14:15], v[68:69], 4, v[2:3]
	global_store_dwordx4 v[14:15], v[8:11], off nt
	ds_read2_b32 v[14:15], v86 offset0:97 offset1:105
	ds_read2_b32 v[16:17], v86 offset0:162 offset1:170
	ds_read2_b32 v[18:19], v86 offset0:227 offset1:235
	s_waitcnt lgkmcnt(3)
	v_bfe_u32 v8, v12, 16, 1
	v_add3_u32 v8, v12, v8, s95
	s_waitcnt lgkmcnt(2)
	v_bfe_u32 v9, v14, 16, 1
	ds_read2_b32 v[20:21], v30 offset0:36 offset1:44
	v_lshrrev_b32_e32 v8, 16, v8
	v_add3_u32 v9, v14, v9, s95
	ds_read2_b32 v[22:23], v30 offset0:101 offset1:109
	v_and_or_b32 v8, v9, s96, v8
	s_waitcnt lgkmcnt(3)
	v_bfe_u32 v9, v16, 16, 1
	v_add3_u32 v9, v16, v9, s95
	s_waitcnt lgkmcnt(2)
	v_bfe_u32 v10, v18, 16, 1
	ds_read2_b32 v[24:25], v30 offset0:166 offset1:174
	v_lshrrev_b32_e32 v9, 16, v9
	v_add3_u32 v10, v18, v10, s95
	ds_read2_b32 v[26:27], v30 offset0:231 offset1:239
	v_and_or_b32 v9, v10, s96, v9
	s_waitcnt lgkmcnt(3)
	v_bfe_u32 v10, v20, 16, 1
	v_add3_u32 v10, v20, v10, s95
	s_waitcnt lgkmcnt(2)
	v_bfe_u32 v11, v22, 16, 1
	v_lshrrev_b32_e32 v10, 16, v10
	v_add3_u32 v11, v22, v11, s95
	v_and_or_b32 v10, v11, s96, v10
	s_waitcnt lgkmcnt(1)
	v_bfe_u32 v11, v24, 16, 1
	v_add3_u32 v11, v24, v11, s95
	s_waitcnt lgkmcnt(0)
	v_bfe_u32 v12, v26, 16, 1
	v_or_b32_e32 v14, 0x80, v31
	v_lshrrev_b32_e32 v11, 16, v11
	v_add3_u32 v12, v26, v12, s95
	v_or_b32_e32 v68, v14, v95
	v_and_or_b32 v11, v12, s96, v11
	v_lshl_add_u64 v[28:29], v[68:69], 4, v[2:3]
	global_store_dwordx4 v[28:29], v[8:11], off nt
	v_bfe_u32 v12, v27, 16, 1
	v_add3_u32 v12, v27, v12, s95
	v_bfe_u32 v8, v13, 16, 1
	v_add3_u32 v8, v13, v8, s95
	v_bfe_u32 v9, v15, 16, 1
	v_lshrrev_b32_e32 v8, 16, v8
	v_add3_u32 v9, v15, v9, s95
	v_and_or_b32 v8, v9, s96, v8
	v_bfe_u32 v9, v17, 16, 1
	v_add3_u32 v9, v17, v9, s95
	v_bfe_u32 v10, v19, 16, 1
	v_lshrrev_b32_e32 v9, 16, v9
	v_add3_u32 v10, v19, v10, s95
	v_and_or_b32 v9, v10, s96, v9
	v_bfe_u32 v10, v21, 16, 1
	v_add3_u32 v10, v21, v10, s95
	v_bfe_u32 v11, v23, 16, 1
	v_lshrrev_b32_e32 v10, 16, v10
	v_add3_u32 v11, v23, v11, s95
	v_and_or_b32 v10, v11, s96, v10
	v_bfe_u32 v11, v25, 16, 1
	v_add3_u32 v11, v25, v11, s95
	v_lshrrev_b32_e32 v11, 16, v11
	v_or_b32_e32 v68, v14, v98
	v_and_or_b32 v11, v12, s96, v11
	ds_read2_b32 v[12:13], v86 offset0:48 offset1:56
	v_lshl_add_u64 v[14:15], v[68:69], 4, v[2:3]
	global_store_dwordx4 v[14:15], v[8:11], off nt
	ds_read2_b32 v[14:15], v86 offset0:113 offset1:121
	ds_read2_b32 v[16:17], v86 offset0:178 offset1:186
	ds_read2_b32 v[18:19], v86 offset0:243 offset1:251
	s_waitcnt lgkmcnt(3)
	v_bfe_u32 v8, v12, 16, 1
	v_add3_u32 v8, v12, v8, s95
	s_waitcnt lgkmcnt(2)
	v_bfe_u32 v9, v14, 16, 1
	ds_read2_b32 v[20:21], v30 offset0:52 offset1:60
	v_lshrrev_b32_e32 v8, 16, v8
	v_add3_u32 v9, v14, v9, s95
	ds_read2_b32 v[22:23], v30 offset0:117 offset1:125
	v_and_or_b32 v8, v9, s96, v8
	s_waitcnt lgkmcnt(3)
	v_bfe_u32 v9, v16, 16, 1
	v_add3_u32 v9, v16, v9, s95
	s_waitcnt lgkmcnt(2)
	v_bfe_u32 v10, v18, 16, 1
	ds_read2_b32 v[24:25], v30 offset0:182 offset1:190
	v_lshrrev_b32_e32 v9, 16, v9
	v_add3_u32 v10, v18, v10, s95
	ds_read2_b32 v[26:27], v30 offset0:247 offset1:255
	v_and_or_b32 v9, v10, s96, v9
	s_waitcnt lgkmcnt(3)
	v_bfe_u32 v10, v20, 16, 1
	v_add3_u32 v10, v20, v10, s95
	s_waitcnt lgkmcnt(2)
	v_bfe_u32 v11, v22, 16, 1
	v_lshrrev_b32_e32 v10, 16, v10
	v_add3_u32 v11, v22, v11, s95
	v_and_or_b32 v10, v11, s96, v10
	s_waitcnt lgkmcnt(1)
	v_bfe_u32 v11, v24, 16, 1
	v_add3_u32 v11, v24, v11, s95
	s_waitcnt lgkmcnt(0)
	v_bfe_u32 v12, v26, 16, 1
	v_lshrrev_b32_e32 v11, 16, v11
	v_add3_u32 v12, v26, v12, s95
	v_and_or_b32 v11, v12, s96, v11
	v_or_b32_e32 v12, 0xc0, v31
	v_or_b32_e32 v68, v12, v95
	v_lshl_add_u64 v[28:29], v[68:69], 4, v[2:3]
	global_store_dwordx4 v[28:29], v[8:11], off nt
	v_or_b32_e32 v68, v12, v99
	v_lshl_add_u64 v[2:3], v[68:69], 4, v[2:3]
	v_bfe_u32 v8, v13, 16, 1
	v_add3_u32 v8, v13, v8, s95
	v_bfe_u32 v9, v15, 16, 1
	v_lshrrev_b32_e32 v8, 16, v8
	v_add3_u32 v9, v15, v9, s95
	v_and_or_b32 v8, v9, s96, v8
	v_bfe_u32 v9, v17, 16, 1
	v_add3_u32 v9, v17, v9, s95
	v_bfe_u32 v10, v19, 16, 1
	v_lshrrev_b32_e32 v9, 16, v9
	v_add3_u32 v10, v19, v10, s95
	v_and_or_b32 v9, v10, s96, v9
	v_bfe_u32 v10, v21, 16, 1
	v_add3_u32 v10, v21, v10, s95
	v_bfe_u32 v11, v23, 16, 1
	v_lshrrev_b32_e32 v10, 16, v10
	v_add3_u32 v11, v23, v11, s95
	v_and_or_b32 v10, v11, s96, v10
	v_bfe_u32 v11, v25, 16, 1
	v_add3_u32 v11, v25, v11, s95
	v_bfe_u32 v13, v27, 16, 1
	v_lshrrev_b32_e32 v11, 16, v11
	v_add3_u32 v13, v27, v13, s95
	v_and_or_b32 v11, v13, s96, v11
	global_store_dwordx4 v[2:3], v[8:11], off nt
	s_waitcnt lgkmcnt(0)
.LBB0_91:
	s_andn2_saveexec_b64 s[4:5], s[4:5]
	v_add_u32_e32 v81, 0xffffff00, v81
	s_or_b64 exec, exec, s[4:5]
	v_cmp_gt_u32_e32 vcc, 8, v81
	s_and_b64 s[2:3], s[2:3], vcc
	s_and_b64 exec, exec, s[2:3]
	s_cbranch_execz .LBB0_95
	v_lshl_add_u64 v[2:3], v[6:7], 2, s[36:37]
	v_lshlrev_b32_e32 v7, 5, v81
	v_and_b32_e32 v7, 0xc0, v7
	v_lshlrev_b32_e32 v6, 6, v81
	v_or_b32_e32 v8, v7, v83
	v_and_b32_e32 v6, 64, v6
	v_lshlrev_b32_e32 v68, 9, v8
	v_lshl_add_u64 v[2:3], v[2:3], 0, v[68:69]
	v_lshlrev_b32_e32 v68, 2, v6
	v_lshl_add_u64 v[2:3], v[2:3], 0, v[68:69]
	v_mov_b32_e32 v73, v69
	v_lshl_add_u64 v[2:3], v[2:3], 0, v[72:73]
	s_movk_i32 s2, 0x1000
	v_add_co_u32_e32 v20, vcc, s2, v2
	s_movk_i32 s2, 0x2000
	s_nop 0
	v_addc_co_u32_e32 v21, vcc, 0, v3, vcc
	v_add_co_u32_e32 v28, vcc, s2, v2
	s_movk_i32 s2, 0x3000
	s_nop 0
	v_addc_co_u32_e32 v29, vcc, 0, v3, vcc
	v_add_co_u32_e32 v32, vcc, s2, v2
	s_movk_i32 s2, 0x4000
	s_nop 0
	v_addc_co_u32_e32 v33, vcc, 0, v3, vcc
	v_add_co_u32_e32 v44, vcc, s2, v2
	s_movk_i32 s2, 0x6000
	s_nop 0
	v_addc_co_u32_e32 v45, vcc, 0, v3, vcc
	v_add_co_u32_e32 v60, vcc, s2, v2
	global_load_dwordx4 v[8:11], v[2:3], off nt
	global_load_dwordx4 v[12:15], v[2:3], off offset:2048 nt
	global_load_dwordx4 v[16:19], v[28:29], off offset:-4096 nt
	s_nop 0
	global_load_dwordx4 v[20:23], v[20:21], off offset:2048 nt
	s_nop 0
	global_load_dwordx4 v[24:27], v[28:29], off nt
	s_nop 0
	global_load_dwordx4 v[28:31], v[28:29], off offset:2048 nt
	s_nop 0
	global_load_dwordx4 v[32:35], v[32:33], off offset:2048 nt
	s_nop 0
	global_load_dwordx4 v[36:39], v[44:45], off offset:-4096 nt
	global_load_dwordx4 v[40:43], v[44:45], off nt
	v_addc_co_u32_e32 v61, vcc, 0, v3, vcc
	global_load_dwordx4 v[44:47], v[44:45], off offset:2048 nt
	s_nop 0
	global_load_dwordx4 v[48:51], v[60:61], off offset:-4096 nt
	s_movk_i32 s2, 0x5000
	v_add_co_u32_e32 v52, vcc, s2, v2
	s_movk_i32 s2, 0x7000
	s_nop 0
	v_addc_co_u32_e32 v53, vcc, 0, v3, vcc
	global_load_dwordx4 v[52:55], v[52:53], off offset:2048 nt
	s_nop 0
	global_load_dwordx4 v[56:59], v[60:61], off nt
	s_nop 0
	global_load_dwordx4 v[60:63], v[60:61], off offset:2048 nt
	v_add_co_u32_e32 v2, vcc, s2, v2
	v_add_u32_e32 v64, 0x1868, v84
	s_nop 0
	v_addc_co_u32_e32 v3, vcc, 0, v3, vcc
	global_load_dwordx4 v[74:77], v[2:3], off nt
	global_load_dwordx4 v[78:81], v[2:3], off offset:2048 nt
	v_lshlrev_b64 v[2:3], 16, v[4:5]
	v_add_u32_e32 v4, 0x1458, v84
	v_add_u32_e32 v5, 0x1860, v84
	v_add_u32_e32 v65, 0x1c70, v84
	v_add_u32_e32 v68, 0x1c78, v84
	v_add_u32_e32 v73, 0x2080, v84
	v_add_u32_e32 v115, 0x2088, v84
	v_add_u32_e32 v116, 0x2490, v84
	v_add_u32_e32 v117, 0x2498, v84
	v_add_u32_e32 v118, 0x28a0, v84
	v_lshl_add_u64 v[2:3], s[0:1], 0, v[2:3]
	s_waitcnt vmcnt(15)
	ds_write2_b32 v84, v8, v9 offset1:1
	ds_write2_b32 v84, v10, v11 offset0:2 offset1:3
	s_waitcnt vmcnt(14)
	ds_write2_b32 v103, v12, v13 offset1:1
	ds_write2_b32 v104, v14, v15 offset1:1
	s_waitcnt vmcnt(13)
	ds_write2_b32 v105, v16, v17 offset1:1
	ds_write2_b32 v106, v18, v19 offset1:1
	s_waitcnt vmcnt(12)
	ds_write2_b32 v107, v20, v21 offset1:1
	ds_write2_b32 v108, v22, v23 offset1:1
	s_waitcnt vmcnt(11)
	ds_write2_b32 v109, v24, v25 offset1:1
	ds_write2_b32 v110, v26, v27 offset1:1
	s_waitcnt vmcnt(10)
	ds_write2_b32 v111, v28, v29 offset1:1
	ds_write2_b32 v4, v30, v31 offset1:1
	s_waitcnt vmcnt(8)
	ds_write2_b32 v5, v36, v37 offset1:1
	ds_write2_b32 v64, v38, v39 offset1:1
	ds_write2_b32 v65, v32, v33 offset1:1
	ds_write2_b32 v68, v34, v35 offset1:1
	s_waitcnt vmcnt(7)
	ds_write2_b32 v73, v40, v41 offset1:1
	ds_write2_b32 v115, v42, v43 offset1:1
	s_waitcnt vmcnt(6)
	ds_write2_b32 v116, v44, v45 offset1:1
	ds_write2_b32 v117, v46, v47 offset1:1
	s_waitcnt vmcnt(5)
	ds_write2_b32 v118, v48, v49 offset1:1
	v_add_u32_e32 v4, 0x28a8, v84
	ds_write2_b32 v4, v50, v51 offset1:1
	v_add_u32_e32 v4, 0x2cb0, v84
	v_lshlrev_b32_e32 v68, 1, v7
	s_waitcnt vmcnt(4)
	ds_write2_b32 v4, v52, v53 offset1:1
	v_add_u32_e32 v4, 0x2cb8, v84
	ds_write2_b32 v4, v54, v55 offset1:1
	v_add_u32_e32 v4, 0x30c0, v84
	s_waitcnt vmcnt(3)
	ds_write2_b32 v4, v56, v57 offset1:1
	v_add_u32_e32 v4, 0x30c8, v84
	ds_write2_b32 v4, v58, v59 offset1:1
	v_add_u32_e32 v4, 0x34d0, v84
	s_waitcnt vmcnt(2)
	ds_write2_b32 v4, v60, v61 offset1:1
	v_add_u32_e32 v4, 0x34d8, v84
	ds_write2_b32 v4, v62, v63 offset1:1
	v_add_u32_e32 v4, 0x38e0, v84
	s_waitcnt vmcnt(1)
	ds_write2_b32 v4, v74, v75 offset1:1
	v_add_u32_e32 v4, 0x38e8, v84
	ds_write2_b32 v4, v76, v77 offset1:1
	v_add_u32_e32 v4, 0x3cf0, v84
	s_waitcnt vmcnt(0)
	ds_write2_b32 v4, v78, v79 offset1:1
	v_add_u32_e32 v4, 0x3cf8, v84
	ds_write2_b32 v4, v80, v81 offset1:1
	s_waitcnt lgkmcnt(0)
	v_add_u32_e32 v7, 0x400, v86
	ds_read2_b32 v[4:5], v7 offset0:199 offset1:207
	ds_read2_b32 v[12:13], v7 offset0:134 offset1:142
	ds_read2_b32 v[16:17], v7 offset0:4 offset1:12
	ds_read2_b32 v[14:15], v7 offset0:69 offset1:77
	ds_read2_b32 v[20:21], v86 offset0:130 offset1:138
	s_waitcnt lgkmcnt(4)
	v_bfe_u32 v8, v4, 16, 1
	v_add3_u32 v4, v4, v8, s95
	s_waitcnt lgkmcnt(3)
	v_bfe_u32 v8, v12, 16, 1
	v_add3_u32 v8, v12, v8, s95
	v_lshrrev_b32_e32 v8, 16, v8
	ds_read2_b32 v[18:19], v86 offset0:195 offset1:203
	v_and_or_b32 v11, v4, s96, v8
	s_waitcnt lgkmcnt(3)
	v_bfe_u32 v8, v16, 16, 1
	s_waitcnt lgkmcnt(2)
	v_bfe_u32 v4, v14, 16, 1
	v_add3_u32 v8, v16, v8, s95
	ds_read2_b32 v[24:25], v86 offset1:8
	v_add3_u32 v4, v14, v4, s95
	v_lshrrev_b32_e32 v8, 16, v8
	ds_read2_b32 v[22:23], v86 offset0:65 offset1:73
	v_and_or_b32 v10, v4, s96, v8
	s_waitcnt lgkmcnt(3)
	v_bfe_u32 v8, v20, 16, 1
	s_waitcnt lgkmcnt(2)
	v_bfe_u32 v4, v18, 16, 1
	v_add3_u32 v8, v20, v8, s95
	v_add3_u32 v4, v18, v4, s95
	v_lshrrev_b32_e32 v8, 16, v8
	v_and_or_b32 v9, v4, s96, v8
	s_waitcnt lgkmcnt(1)
	v_bfe_u32 v8, v24, 16, 1
	s_waitcnt lgkmcnt(0)
	v_bfe_u32 v4, v22, 16, 1
	v_add3_u32 v8, v24, v8, s95
	v_add3_u32 v4, v22, v4, s95
	v_lshrrev_b32_e32 v8, 16, v8
	v_lshl_add_u64 v[2:3], v[2:3], 0, v[68:69]
	v_lshlrev_b32_e32 v68, 1, v70
	v_and_or_b32 v8, v4, s96, v8
	v_or_b32_e32 v4, v6, v85
	v_lshl_add_u64 v[2:3], v[2:3], 0, v[68:69]
	v_lshlrev_b32_e32 v68, 9, v4
	v_bfe_u32 v4, v5, 16, 1
	v_add3_u32 v4, v5, v4, s95
	v_bfe_u32 v5, v13, 16, 1
	v_add3_u32 v5, v13, v5, s95
	v_lshl_add_u64 v[26:27], v[2:3], 0, v[68:69]
	v_lshrrev_b32_e32 v5, 16, v5
	global_store_dwordx4 v[26:27], v[8:11], off nt
	v_or_b32_e32 v12, v6, v87
	v_lshlrev_b32_e32 v68, 9, v12
	v_and_or_b32 v11, v4, s96, v5
	v_bfe_u32 v5, v17, 16, 1
	v_bfe_u32 v4, v15, 16, 1
	v_add3_u32 v5, v17, v5, s95
	v_add3_u32 v4, v15, v4, s95
	v_lshrrev_b32_e32 v5, 16, v5
	v_and_or_b32 v10, v4, s96, v5
	v_bfe_u32 v5, v21, 16, 1
	v_bfe_u32 v4, v19, 16, 1
	v_add3_u32 v5, v21, v5, s95
	v_add3_u32 v4, v19, v4, s95
	v_lshrrev_b32_e32 v5, 16, v5
	v_and_or_b32 v9, v4, s96, v5
	v_bfe_u32 v5, v25, 16, 1
	v_bfe_u32 v4, v23, 16, 1
	v_add3_u32 v5, v25, v5, s95
	v_add3_u32 v4, v23, v4, s95
	v_lshrrev_b32_e32 v5, 16, v5
	v_and_or_b32 v8, v4, s96, v5
	ds_read2_b32 v[4:5], v7 offset0:215 offset1:223
	ds_read2_b32 v[12:13], v7 offset0:150 offset1:158
	v_lshl_add_u64 v[14:15], v[2:3], 0, v[68:69]
	ds_read2_b32 v[16:17], v7 offset0:20 offset1:28
	global_store_dwordx4 v[14:15], v[8:11], off nt
	ds_read2_b32 v[14:15], v7 offset0:85 offset1:93
	ds_read2_b32 v[20:21], v86 offset0:146 offset1:154
	s_waitcnt lgkmcnt(4)
	v_bfe_u32 v8, v4, 16, 1
	v_add3_u32 v4, v4, v8, s95
	s_waitcnt lgkmcnt(3)
	v_bfe_u32 v8, v12, 16, 1
	v_add3_u32 v8, v12, v8, s95
	v_lshrrev_b32_e32 v8, 16, v8
	ds_read2_b32 v[18:19], v86 offset0:211 offset1:219
	v_and_or_b32 v11, v4, s96, v8
	s_waitcnt lgkmcnt(3)
	v_bfe_u32 v8, v16, 16, 1
	s_waitcnt lgkmcnt(2)
	v_bfe_u32 v4, v14, 16, 1
	v_add3_u32 v8, v16, v8, s95
	ds_read2_b32 v[24:25], v86 offset0:16 offset1:24
	v_add3_u32 v4, v14, v4, s95
	v_lshrrev_b32_e32 v8, 16, v8
	ds_read2_b32 v[22:23], v86 offset0:81 offset1:89
	v_and_or_b32 v10, v4, s96, v8
	s_waitcnt lgkmcnt(3)
	v_bfe_u32 v8, v20, 16, 1
	s_waitcnt lgkmcnt(2)
	v_bfe_u32 v4, v18, 16, 1
	v_add3_u32 v8, v20, v8, s95
	v_add3_u32 v4, v18, v4, s95
	v_lshrrev_b32_e32 v8, 16, v8
	v_and_or_b32 v9, v4, s96, v8
	s_waitcnt lgkmcnt(1)
	v_bfe_u32 v8, v24, 16, 1
	s_waitcnt lgkmcnt(0)
	v_bfe_u32 v4, v22, 16, 1
	v_add3_u32 v8, v24, v8, s95
	v_add3_u32 v4, v22, v4, s95
	v_lshrrev_b32_e32 v8, 16, v8
	v_and_or_b32 v8, v4, s96, v8
	v_or_b32_e32 v4, v6, v88
	v_lshlrev_b32_e32 v68, 9, v4
	v_bfe_u32 v4, v5, 16, 1
	v_add3_u32 v4, v5, v4, s95
	v_bfe_u32 v5, v13, 16, 1
	v_add3_u32 v5, v13, v5, s95
	v_lshl_add_u64 v[26:27], v[2:3], 0, v[68:69]
	v_lshrrev_b32_e32 v5, 16, v5
	global_store_dwordx4 v[26:27], v[8:11], off nt
	v_or_b32_e32 v12, v6, v89
	v_lshlrev_b32_e32 v68, 9, v12
	v_and_or_b32 v11, v4, s96, v5
	v_bfe_u32 v5, v17, 16, 1
	v_bfe_u32 v4, v15, 16, 1
	v_add3_u32 v5, v17, v5, s95
	v_add3_u32 v4, v15, v4, s95
	v_lshrrev_b32_e32 v5, 16, v5
	v_and_or_b32 v10, v4, s96, v5
	v_bfe_u32 v5, v21, 16, 1
	v_bfe_u32 v4, v19, 16, 1
	v_add3_u32 v5, v21, v5, s95
	v_add3_u32 v4, v19, v4, s95
	v_lshrrev_b32_e32 v5, 16, v5
	v_and_or_b32 v9, v4, s96, v5
	v_bfe_u32 v5, v25, 16, 1
	v_bfe_u32 v4, v23, 16, 1
	v_add3_u32 v5, v25, v5, s95
	v_add3_u32 v4, v23, v4, s95
	v_lshrrev_b32_e32 v5, 16, v5
	v_and_or_b32 v8, v4, s96, v5
	ds_read2_b32 v[4:5], v7 offset0:231 offset1:239
	ds_read2_b32 v[12:13], v7 offset0:166 offset1:174
	v_lshl_add_u64 v[14:15], v[2:3], 0, v[68:69]
	ds_read2_b32 v[16:17], v7 offset0:36 offset1:44
	global_store_dwordx4 v[14:15], v[8:11], off nt
	ds_read2_b32 v[14:15], v7 offset0:101 offset1:109
	ds_read2_b32 v[20:21], v86 offset0:162 offset1:170
	s_waitcnt lgkmcnt(4)
	v_bfe_u32 v8, v4, 16, 1
	v_add3_u32 v4, v4, v8, s95
	s_waitcnt lgkmcnt(3)
	v_bfe_u32 v8, v12, 16, 1
	v_add3_u32 v8, v12, v8, s95
	v_lshrrev_b32_e32 v8, 16, v8
	ds_read2_b32 v[18:19], v86 offset0:227 offset1:235
	v_and_or_b32 v11, v4, s96, v8
	s_waitcnt lgkmcnt(3)
	v_bfe_u32 v8, v16, 16, 1
	s_waitcnt lgkmcnt(2)
	v_bfe_u32 v4, v14, 16, 1
	v_add3_u32 v8, v16, v8, s95
	ds_read2_b32 v[24:25], v86 offset0:32 offset1:40
	v_add3_u32 v4, v14, v4, s95
	v_lshrrev_b32_e32 v8, 16, v8
	ds_read2_b32 v[22:23], v86 offset0:97 offset1:105
	v_and_or_b32 v10, v4, s96, v8
	s_waitcnt lgkmcnt(3)
	v_bfe_u32 v8, v20, 16, 1
	s_waitcnt lgkmcnt(2)
	v_bfe_u32 v4, v18, 16, 1
	v_add3_u32 v8, v20, v8, s95
	v_add3_u32 v4, v18, v4, s95
	v_lshrrev_b32_e32 v8, 16, v8
	v_and_or_b32 v9, v4, s96, v8
	s_waitcnt lgkmcnt(1)
	v_bfe_u32 v8, v24, 16, 1
	s_waitcnt lgkmcnt(0)
	v_bfe_u32 v4, v22, 16, 1
	v_add3_u32 v8, v24, v8, s95
	v_add3_u32 v4, v22, v4, s95
	v_lshrrev_b32_e32 v8, 16, v8
	v_and_or_b32 v8, v4, s96, v8
	v_or_b32_e32 v4, v6, v90
	v_lshlrev_b32_e32 v68, 9, v4
	v_bfe_u32 v4, v5, 16, 1
	v_add3_u32 v4, v5, v4, s95
	v_bfe_u32 v5, v13, 16, 1
	v_add3_u32 v5, v13, v5, s95
	v_lshl_add_u64 v[26:27], v[2:3], 0, v[68:69]
	v_lshrrev_b32_e32 v5, 16, v5
	global_store_dwordx4 v[26:27], v[8:11], off nt
	v_or_b32_e32 v12, v6, v91
	v_lshlrev_b32_e32 v68, 9, v12
	v_and_or_b32 v11, v4, s96, v5
	v_bfe_u32 v5, v17, 16, 1
	v_bfe_u32 v4, v15, 16, 1
	v_add3_u32 v5, v17, v5, s95
	v_add3_u32 v4, v15, v4, s95
	v_lshrrev_b32_e32 v5, 16, v5
	v_and_or_b32 v10, v4, s96, v5
	v_bfe_u32 v5, v21, 16, 1
	v_bfe_u32 v4, v19, 16, 1
	v_add3_u32 v5, v21, v5, s95
	v_add3_u32 v4, v19, v4, s95
	v_lshrrev_b32_e32 v5, 16, v5
	v_and_or_b32 v9, v4, s96, v5
	v_bfe_u32 v5, v25, 16, 1
	v_bfe_u32 v4, v23, 16, 1
	v_add3_u32 v5, v25, v5, s95
	v_add3_u32 v4, v23, v4, s95
	v_lshrrev_b32_e32 v5, 16, v5
	v_and_or_b32 v8, v4, s96, v5
	ds_read2_b32 v[4:5], v7 offset0:247 offset1:255
	ds_read2_b32 v[12:13], v7 offset0:182 offset1:190
	v_lshl_add_u64 v[14:15], v[2:3], 0, v[68:69]
	ds_read2_b32 v[16:17], v7 offset0:52 offset1:60
	global_store_dwordx4 v[14:15], v[8:11], off nt
	ds_read2_b32 v[14:15], v7 offset0:117 offset1:125
	ds_read2_b32 v[20:21], v86 offset0:178 offset1:186
	s_waitcnt lgkmcnt(4)
	v_bfe_u32 v8, v4, 16, 1
	v_add3_u32 v4, v4, v8, s95
	s_waitcnt lgkmcnt(3)
	v_bfe_u32 v8, v12, 16, 1
	v_add3_u32 v8, v12, v8, s95
	v_lshrrev_b32_e32 v7, 16, v8
	ds_read2_b32 v[18:19], v86 offset0:243 offset1:251
	v_and_or_b32 v11, v4, s96, v7
	s_waitcnt lgkmcnt(3)
	v_bfe_u32 v7, v16, 16, 1
	s_waitcnt lgkmcnt(2)
	v_bfe_u32 v4, v14, 16, 1
	v_add3_u32 v7, v16, v7, s95
	ds_read2_b32 v[24:25], v86 offset0:48 offset1:56
	v_add3_u32 v4, v14, v4, s95
	v_lshrrev_b32_e32 v7, 16, v7
	ds_read2_b32 v[22:23], v86 offset0:113 offset1:121
	v_and_or_b32 v10, v4, s96, v7
	s_waitcnt lgkmcnt(3)
	v_bfe_u32 v7, v20, 16, 1
	s_waitcnt lgkmcnt(2)
	v_bfe_u32 v4, v18, 16, 1
	v_add3_u32 v7, v20, v7, s95
	v_add3_u32 v4, v18, v4, s95
	v_lshrrev_b32_e32 v7, 16, v7
	v_and_or_b32 v9, v4, s96, v7
	s_waitcnt lgkmcnt(1)
	v_bfe_u32 v7, v24, 16, 1
	s_waitcnt lgkmcnt(0)
	v_bfe_u32 v4, v22, 16, 1
	v_add3_u32 v7, v24, v7, s95
	v_add3_u32 v4, v22, v4, s95
	v_lshrrev_b32_e32 v7, 16, v7
	v_and_or_b32 v8, v4, s96, v7
	v_or_b32_e32 v4, v6, v92
	v_lshlrev_b32_e32 v68, 9, v4
	v_bfe_u32 v4, v5, 16, 1
	v_add3_u32 v4, v5, v4, s95
	v_bfe_u32 v5, v13, 16, 1
	v_add3_u32 v5, v13, v5, s95
	v_lshl_add_u64 v[26:27], v[2:3], 0, v[68:69]
	v_lshrrev_b32_e32 v5, 16, v5
	global_store_dwordx4 v[26:27], v[8:11], off nt
	s_nop 1
	v_and_or_b32 v11, v4, s96, v5
	v_bfe_u32 v5, v17, 16, 1
	v_bfe_u32 v4, v15, 16, 1
	v_add3_u32 v5, v17, v5, s95
	v_add3_u32 v4, v15, v4, s95
	v_lshrrev_b32_e32 v5, 16, v5
	v_and_or_b32 v10, v4, s96, v5
	v_bfe_u32 v5, v21, 16, 1
	v_bfe_u32 v4, v19, 16, 1
	v_add3_u32 v5, v21, v5, s95
	v_add3_u32 v4, v19, v4, s95
	v_lshrrev_b32_e32 v5, 16, v5
	v_and_or_b32 v9, v4, s96, v5
	v_bfe_u32 v5, v25, 16, 1
	v_bfe_u32 v4, v23, 16, 1
	v_add3_u32 v5, v25, v5, s95
	v_add3_u32 v4, v23, v4, s95
	v_lshrrev_b32_e32 v5, 16, v5
	v_and_or_b32 v8, v4, s96, v5
	v_or_b32_e32 v4, v6, v93
	v_lshlrev_b32_e32 v68, 9, v4
	v_lshl_add_u64 v[2:3], v[2:3], 0, v[68:69]
	global_store_dwordx4 v[2:3], v[8:11], off nt
	s_waitcnt lgkmcnt(0)

.LBB0_153:
	v_mov_b64_e32 v[4:5], s[56:57]
	s_mov_b32 s2, 0x4100000
	v_mad_i64_i32 v[6:7], s[2:3], v74, s2, v[4:5]
	s_waitcnt vmcnt(0)
	v_pk_mul_f32 v[4:5], v[54:55], v[2:3] op_sel_hi:[1,0]
	v_add_u32_e32 v3, 0x3cf0, v84
	ds_write2_b32 v3, v4, v5 offset1:1
	v_pk_mul_f32 v[2:3], v[56:57], v[2:3] op_sel_hi:[1,0]
	v_add_u32_e32 v4, 0x3cf8, v84
	ds_write2_b32 v4, v2, v3 offset1:1
	s_waitcnt lgkmcnt(0)
	v_add_u32_e32 v4, 0x400, v86
	ds_read2_b32 v[12:13], v4 offset0:134 offset1:142
	ds_read2_b32 v[10:11], v4 offset0:150 offset1:199
	ds_read2_b32 v[16:17], v4 offset0:4 offset1:12
	v_ashrrev_i32_e32 v77, 31, v76
	ds_read2_b32 v[14:15], v4 offset0:20 offset1:69
	v_lshl_add_u64 v[2:3], v[76:77], 1, v[6:7]
	s_waitcnt lgkmcnt(3)
	v_bfe_u32 v6, v12, 16, 1
	s_waitcnt lgkmcnt(2)
	v_bfe_u32 v5, v11, 16, 1
	v_add3_u32 v6, v12, v6, s95
	ds_read2_b32 v[20:21], v86 offset0:130 offset1:138
	v_add3_u32 v5, v11, v5, s95
	v_lshrrev_b32_e32 v6, 16, v6
	ds_read2_b32 v[18:19], v86 offset0:146 offset1:195
	v_and_or_b32 v9, v5, s96, v6
	s_waitcnt lgkmcnt(3)
	v_bfe_u32 v6, v16, 16, 1
	s_waitcnt lgkmcnt(2)
	v_bfe_u32 v5, v15, 16, 1
	v_add3_u32 v6, v16, v6, s95
	ds_read2_b32 v[24:25], v86 offset1:8
	v_add3_u32 v5, v15, v5, s95
	v_lshrrev_b32_e32 v6, 16, v6
	ds_read2_b32 v[22:23], v86 offset0:16 offset1:65
	v_and_or_b32 v8, v5, s96, v6
	s_waitcnt lgkmcnt(3)
	v_bfe_u32 v6, v20, 16, 1
	s_waitcnt lgkmcnt(2)
	v_bfe_u32 v5, v19, 16, 1
	v_add3_u32 v6, v20, v6, s95
	v_add3_u32 v5, v19, v5, s95
	v_lshrrev_b32_e32 v6, 16, v6
	v_and_or_b32 v7, v5, s96, v6
	s_waitcnt lgkmcnt(1)
	v_bfe_u32 v6, v24, 16, 1
	v_or_b32_e32 v26, v115, v85
	v_lshlrev_b32_e32 v68, 1, v70
	s_waitcnt lgkmcnt(0)
	v_bfe_u32 v5, v23, 16, 1
	v_add3_u32 v6, v24, v6, s95
	ds_read2_b32 v[28:29], v4 offset0:207 offset1:215
	v_ashrrev_i32_e32 v27, 31, v26
	v_lshl_add_u64 v[2:3], v[2:3], 0, v[68:69]
	v_add3_u32 v5, v23, v5, s95
	v_lshrrev_b32_e32 v6, 16, v6
	v_lshlrev_b64 v[26:27], 12, v[26:27]
	v_and_or_b32 v6, v5, s96, v6
	v_lshl_add_u64 v[26:27], v[2:3], 0, v[26:27]
	global_store_dwordx4 v[26:27], v[6:9], off nt
	ds_read2_b32 v[26:27], v4 offset0:77 offset1:85
	s_waitcnt lgkmcnt(1)
	v_bfe_u32 v5, v28, 16, 1
	v_bfe_u32 v6, v13, 16, 1
	v_add3_u32 v6, v13, v6, s95
	v_add3_u32 v5, v28, v5, s95
	v_lshrrev_b32_e32 v6, 16, v6
	ds_read2_b32 v[12:13], v86 offset0:203 offset1:211
	v_and_or_b32 v9, v5, s96, v6
	v_bfe_u32 v6, v17, 16, 1
	s_waitcnt lgkmcnt(1)
	v_bfe_u32 v5, v26, 16, 1
	v_add3_u32 v6, v17, v6, s95
	v_add3_u32 v5, v26, v5, s95
	v_lshrrev_b32_e32 v6, 16, v6
	ds_read2_b32 v[16:17], v86 offset0:73 offset1:81
	v_and_or_b32 v8, v5, s96, v6
	v_bfe_u32 v6, v21, 16, 1
	s_waitcnt lgkmcnt(1)
	v_bfe_u32 v5, v12, 16, 1
	v_add3_u32 v6, v21, v6, s95
	v_add3_u32 v5, v12, v5, s95
	v_lshrrev_b32_e32 v6, 16, v6
	v_and_or_b32 v7, v5, s96, v6
	v_bfe_u32 v6, v25, 16, 1
	v_or_b32_e32 v20, v115, v87
	s_waitcnt lgkmcnt(0)
	v_bfe_u32 v5, v16, 16, 1
	v_add3_u32 v6, v25, v6, s95
	v_ashrrev_i32_e32 v21, 31, v20
	v_add3_u32 v5, v16, v5, s95
	v_lshrrev_b32_e32 v6, 16, v6
	v_lshlrev_b64 v[20:21], 12, v[20:21]
	v_and_or_b32 v6, v5, s96, v6
	v_lshl_add_u64 v[20:21], v[2:3], 0, v[20:21]
	global_store_dwordx4 v[20:21], v[6:9], off nt
	v_bfe_u32 v5, v29, 16, 1
	v_add3_u32 v5, v29, v5, s95
	v_bfe_u32 v6, v10, 16, 1
	v_add3_u32 v6, v10, v6, s95
	v_lshrrev_b32_e32 v6, 16, v6
	v_and_or_b32 v9, v5, s96, v6
	v_bfe_u32 v6, v14, 16, 1
	v_bfe_u32 v5, v27, 16, 1
	v_add3_u32 v6, v14, v6, s95
	v_add3_u32 v5, v27, v5, s95
	v_lshrrev_b32_e32 v6, 16, v6
	v_and_or_b32 v8, v5, s96, v6
	v_bfe_u32 v6, v18, 16, 1
	v_bfe_u32 v5, v13, 16, 1
	v_add3_u32 v6, v18, v6, s95
	v_add3_u32 v5, v13, v5, s95
	v_lshrrev_b32_e32 v6, 16, v6
	v_and_or_b32 v7, v5, s96, v6
	v_bfe_u32 v6, v22, 16, 1
	v_or_b32_e32 v10, v115, v88
	v_bfe_u32 v5, v17, 16, 1
	v_add3_u32 v6, v22, v6, s95
	v_ashrrev_i32_e32 v11, 31, v10
	v_add3_u32 v5, v17, v5, s95
	v_lshrrev_b32_e32 v6, 16, v6
	v_lshlrev_b64 v[10:11], 12, v[10:11]
	v_and_or_b32 v6, v5, s96, v6
	v_lshl_add_u64 v[10:11], v[2:3], 0, v[10:11]
	v_cmp_lt_u32_e32 vcc, v89, v116
	global_store_dwordx4 v[10:11], v[6:9], off nt
	s_and_saveexec_b64 s[2:3], vcc
	s_cbranch_execnz .LBB0_158
	s_or_b64 exec, exec, s[2:3]
	v_cmp_lt_u32_e32 vcc, v90, v116
	s_and_saveexec_b64 s[2:3], vcc
	s_cbranch_execnz .LBB0_159

.LBB0_158:
	ds_read2_b32 v[6:7], v4 offset0:158 offset1:223
	ds_read2_b32 v[10:11], v4 offset0:28 offset1:93
	s_waitcnt lgkmcnt(1)
	v_bfe_u32 v8, v6, 16, 1
	v_bfe_u32 v5, v7, 16, 1
	v_add3_u32 v6, v6, v8, s95
	v_add3_u32 v5, v7, v5, s95
	v_lshrrev_b32_e32 v6, 16, v6
	v_and_or_b32 v9, v5, s96, v6
	ds_read2_b32 v[6:7], v86 offset0:154 offset1:219
	s_waitcnt lgkmcnt(1)
	v_bfe_u32 v8, v10, 16, 1
	v_bfe_u32 v12, v11, 16, 1
	v_add3_u32 v8, v10, v8, s95
	v_add3_u32 v5, v11, v12, s95
	v_lshrrev_b32_e32 v8, 16, v8
	ds_read2_b32 v[10:11], v86 offset0:24 offset1:89
	v_and_or_b32 v8, v5, s96, v8
	s_waitcnt lgkmcnt(1)
	v_bfe_u32 v5, v7, 16, 1
	v_add3_u32 v5, v7, v5, s95
	v_bfe_u32 v7, v6, 16, 1
	v_add3_u32 v6, v6, v7, s95
	v_lshrrev_b32_e32 v6, 16, v6
	v_and_or_b32 v7, v5, s96, v6
	s_waitcnt lgkmcnt(0)
	v_bfe_u32 v6, v10, 16, 1
	v_bfe_u32 v5, v11, 16, 1
	v_add3_u32 v6, v10, v6, s95
	v_or_b32_e32 v10, v115, v89
	v_add3_u32 v5, v11, v5, s95
	v_ashrrev_i32_e32 v11, 31, v10
	v_lshrrev_b32_e32 v6, 16, v6
	v_lshlrev_b64 v[10:11], 12, v[10:11]
	v_and_or_b32 v6, v5, s96, v6
	v_lshl_add_u64 v[10:11], v[2:3], 0, v[10:11]
	global_store_dwordx4 v[10:11], v[6:9], off nt
	s_or_b64 exec, exec, s[2:3]
	v_cmp_lt_u32_e32 vcc, v90, v116
	s_and_saveexec_b64 s[2:3], vcc
	s_cbranch_execz .LBB0_155
.LBB0_159:
	ds_read2_b32 v[6:7], v4 offset0:166 offset1:231
	ds_read2_b32 v[10:11], v4 offset0:36 offset1:101
	s_waitcnt lgkmcnt(1)
	v_bfe_u32 v8, v6, 16, 1
	v_bfe_u32 v5, v7, 16, 1
	v_add3_u32 v6, v6, v8, s95
	v_add3_u32 v5, v7, v5, s95
	v_lshrrev_b32_e32 v6, 16, v6
	v_and_or_b32 v9, v5, s96, v6
	ds_read2_b32 v[6:7], v86 offset0:162 offset1:227
	s_waitcnt lgkmcnt(1)
	v_bfe_u32 v8, v10, 16, 1
	v_bfe_u32 v12, v11, 16, 1
	v_add3_u32 v8, v10, v8, s95
	v_add3_u32 v5, v11, v12, s95
	v_lshrrev_b32_e32 v8, 16, v8
	ds_read2_b32 v[10:11], v86 offset0:32 offset1:97
	v_and_or_b32 v8, v5, s96, v8
	s_waitcnt lgkmcnt(1)
	v_bfe_u32 v5, v7, 16, 1
	v_add3_u32 v5, v7, v5, s95
	v_bfe_u32 v7, v6, 16, 1
	v_add3_u32 v6, v6, v7, s95
	v_lshrrev_b32_e32 v6, 16, v6
	v_and_or_b32 v7, v5, s96, v6
	s_waitcnt lgkmcnt(0)
	v_bfe_u32 v6, v10, 16, 1
	v_bfe_u32 v5, v11, 16, 1
	v_add3_u32 v6, v10, v6, s95
	v_or_b32_e32 v10, v115, v90
	v_add3_u32 v5, v11, v5, s95
	v_ashrrev_i32_e32 v11, 31, v10
	v_lshrrev_b32_e32 v6, 16, v6
	v_lshlrev_b64 v[10:11], 12, v[10:11]
	v_and_or_b32 v6, v5, s96, v6
	v_lshl_add_u64 v[10:11], v[2:3], 0, v[10:11]
	global_store_dwordx4 v[10:11], v[6:9], off nt
	s_or_b64 exec, exec, s[2:3]
	v_cmp_lt_u32_e32 vcc, v91, v116
	s_and_saveexec_b64 s[2:3], vcc
	s_cbranch_execz .LBB0_156
.LBB0_160:
	ds_read2_b32 v[6:7], v4 offset0:174 offset1:239
	ds_read2_b32 v[10:11], v4 offset0:44 offset1:109
	s_waitcnt lgkmcnt(1)
	v_bfe_u32 v8, v6, 16, 1
	v_bfe_u32 v5, v7, 16, 1
	v_add3_u32 v6, v6, v8, s95
	v_add3_u32 v5, v7, v5, s95
	v_lshrrev_b32_e32 v6, 16, v6
	v_and_or_b32 v9, v5, s96, v6
	ds_read2_b32 v[6:7], v86 offset0:170 offset1:235
	s_waitcnt lgkmcnt(1)
	v_bfe_u32 v8, v10, 16, 1
	v_bfe_u32 v12, v11, 16, 1
	v_add3_u32 v8, v10, v8, s95
	v_add3_u32 v5, v11, v12, s95
	v_lshrrev_b32_e32 v8, 16, v8
	ds_read2_b32 v[10:11], v86 offset0:40 offset1:105
	v_and_or_b32 v8, v5, s96, v8
	s_waitcnt lgkmcnt(1)
	v_bfe_u32 v5, v7, 16, 1
	v_add3_u32 v5, v7, v5, s95
	v_bfe_u32 v7, v6, 16, 1
	v_add3_u32 v6, v6, v7, s95
	v_lshrrev_b32_e32 v6, 16, v6
	v_and_or_b32 v7, v5, s96, v6
	s_waitcnt lgkmcnt(0)
	v_bfe_u32 v6, v10, 16, 1
	v_bfe_u32 v5, v11, 16, 1
	v_add3_u32 v6, v10, v6, s95
	v_or_b32_e32 v10, v115, v91
	v_add3_u32 v5, v11, v5, s95
	v_ashrrev_i32_e32 v11, 31, v10
	v_lshrrev_b32_e32 v6, 16, v6
	v_lshlrev_b64 v[10:11], 12, v[10:11]
	v_and_or_b32 v6, v5, s96, v6
	v_lshl_add_u64 v[10:11], v[2:3], 0, v[10:11]
	global_store_dwordx4 v[10:11], v[6:9], off nt
	s_or_b64 exec, exec, s[2:3]
	v_cmp_lt_u32_e32 vcc, v92, v116
	s_and_saveexec_b64 s[2:3], vcc
	s_cbranch_execz .LBB0_157
.LBB0_161:
	ds_read2_b32 v[6:7], v4 offset0:182 offset1:247
	ds_read2_b32 v[10:11], v4 offset0:52 offset1:117
	s_waitcnt lgkmcnt(1)
	v_bfe_u32 v8, v6, 16, 1
	v_bfe_u32 v5, v7, 16, 1
	v_add3_u32 v6, v6, v8, s95
	v_add3_u32 v5, v7, v5, s95
	v_lshrrev_b32_e32 v6, 16, v6
	v_and_or_b32 v9, v5, s96, v6
	ds_read2_b32 v[6:7], v86 offset0:178 offset1:243
	s_waitcnt lgkmcnt(1)
	v_bfe_u32 v8, v10, 16, 1
	v_bfe_u32 v12, v11, 16, 1
	v_add3_u32 v8, v10, v8, s95
	v_add3_u32 v5, v11, v12, s95
	v_lshrrev_b32_e32 v8, 16, v8
	ds_read2_b32 v[10:11], v86 offset0:48 offset1:113
	v_and_or_b32 v8, v5, s96, v8
	s_waitcnt lgkmcnt(1)
	v_bfe_u32 v5, v7, 16, 1
	v_add3_u32 v5, v7, v5, s95
	v_bfe_u32 v7, v6, 16, 1
	v_add3_u32 v6, v6, v7, s95
	v_lshrrev_b32_e32 v6, 16, v6
	v_and_or_b32 v7, v5, s96, v6
	s_waitcnt lgkmcnt(0)
	v_bfe_u32 v6, v10, 16, 1
	v_bfe_u32 v5, v11, 16, 1
	v_add3_u32 v6, v10, v6, s95
	v_or_b32_e32 v10, v115, v92
	v_add3_u32 v5, v11, v5, s95
	v_ashrrev_i32_e32 v11, 31, v10
	v_lshrrev_b32_e32 v6, 16, v6
	v_lshlrev_b64 v[10:11], 12, v[10:11]
	v_and_or_b32 v6, v5, s96, v6
	v_lshl_add_u64 v[10:11], v[2:3], 0, v[10:11]
	global_store_dwordx4 v[10:11], v[6:9], off nt
	s_or_b64 exec, exec, s[2:3]
	v_cmp_lt_u32_e32 vcc, v93, v116
	s_and_saveexec_b64 s[2:3], vcc
	s_cbranch_execz .LBB0_14
.LBB0_162:
	ds_read2_b32 v[6:7], v4 offset0:190 offset1:255
	ds_read2_b32 v[4:5], v4 offset0:60 offset1:125
	s_waitcnt lgkmcnt(1)
	v_bfe_u32 v8, v7, 16, 1
	v_bfe_u32 v9, v6, 16, 1
	v_add3_u32 v7, v7, v8, s95
	v_add3_u32 v6, v6, v9, s95
	ds_read2_b32 v[8:9], v86 offset0:186 offset1:251
	s_waitcnt lgkmcnt(1)
	v_bfe_u32 v10, v5, 16, 1
	v_lshrrev_b32_e32 v6, 16, v6
	v_and_or_b32 v7, v7, s96, v6
	v_add3_u32 v5, v5, v10, s95
	v_bfe_u32 v6, v4, 16, 1
	ds_read2_b32 v[10:11], v86 offset0:56 offset1:121
	v_add3_u32 v4, v4, v6, s95
	v_lshrrev_b32_e32 v4, 16, v4
	v_and_or_b32 v6, v5, s96, v4
	s_waitcnt lgkmcnt(1)
	v_bfe_u32 v5, v8, 16, 1
	v_bfe_u32 v4, v9, 16, 1
	v_add3_u32 v5, v8, v5, s95
	v_add3_u32 v4, v9, v4, s95
	v_lshrrev_b32_e32 v5, 16, v5
	s_waitcnt lgkmcnt(0)
	v_bfe_u32 v8, v10, 16, 1
	v_and_or_b32 v5, v4, s96, v5
	v_bfe_u32 v4, v11, 16, 1
	v_add3_u32 v8, v10, v8, s95
	v_add3_u32 v4, v11, v4, s95
	v_lshrrev_b32_e32 v8, 16, v8
	v_and_or_b32 v4, v4, s96, v8
	v_or_b32_e32 v8, v115, v93
	v_ashrrev_i32_e32 v9, 31, v8
	v_lshlrev_b64 v[8:9], 12, v[8:9]
	v_lshl_add_u64 v[2:3], v[2:3], 0, v[8:9]
	global_store_dwordx4 v[2:3], v[4:7], off nt
	s_branch .LBB0_14

.LBB0_1504:
	v_lshl_add_u64 v[54:55], s[2:3], 0, v[32:33]
	v_lshl_add_u64 v[74:75], s[2:3], 0, v[34:35]
	v_lshl_add_u64 v[76:77], v[54:55], 0, s[12:13]
	v_add_co_u32_e32 v78, vcc, 0x38e00000, v54
	v_lshl_add_u64 v[80:81], v[54:55], 0, s[14:15]
	v_add_co_u32_e64 v82, s[0:1], s19, v74
	global_load_dwordx4 v[38:41], v[76:77], off offset:16
	global_load_dwordx4 v[42:45], v[76:77], off offset:32
	global_load_dwordx4 v[46:49], v[80:81], off offset:48
	global_load_dwordx4 v[50:53], v[80:81], off offset:32
	v_addc_co_u32_e32 v79, vcc, 0, v55, vcc
	v_addc_co_u32_e64 v83, s[0:1], 0, v75, s[0:1]
	global_load_dwordx4 v[54:57], v[78:79], off
	global_load_dwordx4 v[58:61], v[76:77], off offset:48
	global_load_dwordx4 v[62:65], v[78:79], off offset:64
	global_load_dwordx4 v[66:69], v[80:81], off offset:16
	global_load_dwordx4 v[70:73], v[82:83], off offset:-4096 nt
	v_add_co_u32_e32 v74, vcc, s18, v74
	v_lshl_add_u64 v[76:77], s[6:7], 0, v[34:35]
	s_nop 0
	v_addc_co_u32_e32 v75, vcc, 0, v75, vcc
	global_load_dwordx4 v[86:89], v[74:75], off offset:1024 nt
	global_load_dwordx4 v[90:93], v[74:75], off offset:2048 nt
	global_load_dwordx4 v[94:97], v[74:75], off offset:3072 nt
	global_load_dwordx4 v[98:101], v[82:83], off nt
	global_load_dwordx4 v[102:105], v[82:83], off offset:1024 nt
	global_load_dwordx4 v[106:109], v[82:83], off offset:2048 nt
	global_load_dwordx4 v[110:113], v[82:83], off offset:3072 nt
	v_add_u32_e32 v36, s22, v36
	v_lshl_add_u64 v[32:33], v[32:33], 0, s[4:5]
	v_lshl_add_u64 v[34:35], v[34:35], 0, s[8:9]
	s_waitcnt vmcnt(15)
	v_mov_b32_e32 v79, v38
	v_mov_b32_e32 v81, v40
	s_waitcnt vmcnt(14)
	v_mov_b32_e32 v84, v43
	v_mov_b32_e32 v85, v44
	s_waitcnt vmcnt(11)
	v_mov_b32_e32 v78, v54
	v_mov_b32_e32 v38, v55
	v_mov_b32_e32 v80, v56
	v_mov_b32_e32 v40, v57
	v_mov_b32_e32 v43, v45
	v_pk_add_f32 v[38:39], v[78:79], v[38:39]
	v_pk_add_f32 v[40:41], v[80:81], v[40:41]
	v_pk_add_f32 v[42:43], v[84:85], v[42:43]
	v_pk_add_f32 v[38:39], v[38:39], v[40:41]
	v_pk_add_f32 v[42:43], v[42:43], v[42:43] op_sel:[0,1] op_sel_hi:[1,0]
	v_add_f32_e32 v38, 0, v38
	v_add_f32_e32 v44, v50, v51
	v_add_f32_e32 v50, v52, v53
	v_mov_b32_e32 v45, v48
	v_mov_b32_e32 v51, v49
	s_waitcnt vmcnt(10)
	v_add_f32_e32 v48, v58, v59
	v_add_f32_e32 v52, v60, v61
	s_waitcnt vmcnt(9)
	v_mov_b32_e32 v55, v62
	v_mov_b32_e32 v49, v64
	v_mov_b32_e32 v53, v65
	v_mov_b32_e32 v43, v63
	v_add_f32_e32 v54, v38, v39
	s_waitcnt vmcnt(8)
	v_mov_b32_e32 v56, v67
	v_mov_b32_e32 v57, v68
	v_mov_b32_e32 v67, v69
	v_pk_add_f32 v[48:49], v[48:49], v[52:53]
	v_pk_add_f32 v[38:39], v[54:55], v[42:43]
	v_pk_add_f32 v[44:45], v[44:45], v[50:51]
	v_pk_add_f32 v[50:51], v[56:57], v[66:67]
	v_pk_add_f32 v[38:39], v[38:39], v[48:49]
	v_pk_add_f32 v[40:41], v[50:51], v[50:51] op_sel:[0,1] op_sel_hi:[1,0]
	v_pk_add_f32 v[38:39], v[38:39], v[38:39] op_sel:[0,1] op_sel_hi:[1,0]
	v_mov_b32_e32 v41, v47
	v_mov_b32_e32 v39, v46
	v_pk_add_f32 v[38:39], v[38:39], v[40:41]
	s_nop 0
	v_pk_add_f32 v[38:39], v[38:39], v[44:45]
	s_nop 0
	v_add_f32_e32 v38, v38, v39
	v_fmamk_f32 v38, v38, 0x3a000000, v37
	v_mul_f32_e32 v39, 0x4b800000, v38
	v_cmp_gt_f32_e32 vcc, s17, v38
	s_nop 1
	v_cndmask_b32_e32 v38, v38, v39, vcc
	v_rsq_f32_e32 v38, v38
	s_nop 0
	v_mul_f32_e32 v39, 0x45800000, v38
	v_cndmask_b32_e32 v42, v38, v39, vcc
	s_waitcnt vmcnt(7)
	v_pk_mul_f32 v[38:39], v[70:71], v[42:43] op_sel_hi:[1,0]
	v_pk_mul_f32 v[40:41], v[72:73], v[42:43] op_sel_hi:[1,0]
	v_pk_mul_f32 v[38:39], v[0:1], v[38:39]
	v_pk_mul_f32 v[40:41], v[2:3], v[40:41]
	global_store_dwordx4 v[76:77], v[38:41], off nt
	v_add_co_u32_e32 v44, vcc, s16, v76
	s_waitcnt vmcnt(7)
	s_nop 1
	v_pk_mul_f32 v[40:41], v[88:89], v[42:43] op_sel_hi:[1,0]
	v_pk_mul_f32 v[38:39], v[86:87], v[42:43] op_sel_hi:[1,0]
	v_pk_mul_f32 v[40:41], v[6:7], v[40:41]
	v_pk_mul_f32 v[38:39], v[4:5], v[38:39]
	global_store_dwordx4 v[76:77], v[38:41], off offset:1024 nt
	v_addc_co_u32_e32 v45, vcc, 0, v77, vcc
	v_cmp_lt_i32_e32 vcc, s20, v36
	s_or_b64 s[10:11], vcc, s[10:11]
	s_waitcnt vmcnt(7)
	s_nop 1
	v_pk_mul_f32 v[40:41], v[92:93], v[42:43] op_sel_hi:[1,0]
	v_pk_mul_f32 v[38:39], v[90:91], v[42:43] op_sel_hi:[1,0]
	v_pk_mul_f32 v[40:41], v[10:11], v[40:41]
	v_pk_mul_f32 v[38:39], v[8:9], v[38:39]
	global_store_dwordx4 v[76:77], v[38:41], off offset:2048 nt
	s_waitcnt vmcnt(7)
	s_nop 1
	v_pk_mul_f32 v[40:41], v[96:97], v[42:43] op_sel_hi:[1,0]
	v_pk_mul_f32 v[38:39], v[94:95], v[42:43] op_sel_hi:[1,0]
	v_pk_mul_f32 v[40:41], v[14:15], v[40:41]
	v_pk_mul_f32 v[38:39], v[12:13], v[38:39]
	global_store_dwordx4 v[76:77], v[38:41], off offset:3072 nt
	s_waitcnt vmcnt(7)
	s_nop 1
	v_pk_mul_f32 v[40:41], v[100:101], v[42:43] op_sel_hi:[1,0]
	v_pk_mul_f32 v[38:39], v[98:99], v[42:43] op_sel_hi:[1,0]
	v_pk_mul_f32 v[40:41], v[18:19], v[40:41]
	v_pk_mul_f32 v[38:39], v[16:17], v[38:39]
	global_store_dwordx4 v[44:45], v[38:41], off nt
	s_waitcnt vmcnt(7)
	s_nop 1
	v_pk_mul_f32 v[40:41], v[104:105], v[42:43] op_sel_hi:[1,0]
	v_pk_mul_f32 v[38:39], v[102:103], v[42:43] op_sel_hi:[1,0]
	v_pk_mul_f32 v[40:41], v[22:23], v[40:41]
	v_pk_mul_f32 v[38:39], v[20:21], v[38:39]
	global_store_dwordx4 v[44:45], v[38:41], off offset:1024 nt
	s_waitcnt vmcnt(7)
	s_nop 1
	v_pk_mul_f32 v[40:41], v[42:43], v[108:109] op_sel_hi:[0,1]
	v_pk_mul_f32 v[38:39], v[42:43], v[106:107] op_sel_hi:[0,1]
	v_pk_mul_f32 v[38:39], v[24:25], v[38:39]
	v_pk_mul_f32 v[40:41], v[26:27], v[40:41]
	global_store_dwordx4 v[44:45], v[38:41], off offset:2048 nt
	s_waitcnt vmcnt(7)
	s_nop 1
	v_pk_mul_f32 v[40:41], v[42:43], v[112:113] op_sel_hi:[0,1]
	v_pk_mul_f32 v[38:39], v[42:43], v[110:111] op_sel_hi:[0,1]
	v_pk_mul_f32 v[38:39], v[28:29], v[38:39]
	v_pk_mul_f32 v[40:41], v[30:31], v[40:41]
	global_store_dwordx4 v[44:45], v[38:41], off offset:3072 nt
	s_andn2_b64 exec, exec, s[10:11]
	s_cbranch_execnz .LBB0_1504
